# GEMM K loops: per-segment s_setprio flips removed, one static priority raise for waves 4-7 during each K loop
# speedup vs baseline: 1.0100x; 1.0043x over previous
; #define PG8_STAGE(bufoff, gbase, voff) do { _Pragma("unroll") for (int _i = 0; _i < 2; ++_i) \
;         __builtin_amdgcn_global_load_lds((const unsigned*)((const char*)(gbase) + (voff)[_i]), (PG8_LAS unsigned*)(lds + (bufoff) + ldsw + _i * 8192), 16, 0, 0); } while (0)
; #define PG8_LDA(dst, b, h) do { _Pragma("unroll") for (int m = 0; m < 4; ++m) _Pragma("unroll") for (int k = 0; k < 2; ++k) dst[m][k] = *(const PG8_LAS bf16x8*)(lds + PG8_SA(b, h) + aoff + m * 2048 + k * 1024); } while (0)
; #define PG8_LDB(dst, b, h) do { _Pragma("unroll") for (int n = 0; n < 2; ++n) _Pragma("unroll") for (int k = 0; k < 2; ++k) dst[n][k] = *(const PG8_LAS bf16x8*)(lds + PG8_SB(b, h) + boff + n * 2048 + k * 1024); } while (0)
; #define PG8_MMA(ai, bj, At, Bt) do { __builtin_amdgcn_s_setprio(1); _Pragma("unroll") for (int m = 0; m < 4; ++m) _Pragma("unroll") for (int n = 0; n < 2; ++n) _Pragma("unroll") for (int k = 0; k < 2; ++k) \
;         acc[ai][bj][m][n] = __builtin_amdgcn_mfma_f32_16x16x32_bf16(Bt[n][k], At[m][k], acc[ai][bj][m][n], 0, 0, 0); __builtin_amdgcn_s_setprio(0); } while (0)
; #define PG8_WAIT_V(n) asm volatile("s_waitcnt vmcnt(" #n ")" ::: "memory")
; #define PG8_BAR __builtin_amdgcn_s_barrier()
; template <class Epi, class Sched, bool ALIGN_EPI = false, bool SP2 = false>
; __device__ __forceinline__ void gemm_phase(PG8_LAS unsigned char* lds, const Gemm g, const Sched& S, const Epi& E) {
;     ...
;         for (int t = 0; t < nt; t += 2) {
;             const bool last = (t == nt - 2);
;             const char* a1 = cA + (size_t)(t + 1) * kstep;
;             const char* a2 = last ? nA : cA + (size_t)(t + 2) * kstep; const char* b2 = last ? nB : cB + (size_t)(t + 2) * kstep;
;             const char* a3 = a2 + kstep; const char* b3 = b2 + kstep;
;             if (last && has_next) S.a_ready(nxt);
;             if constexpr (SP2) {
;             PG8_LDB(B0, 0, 0); PG8_LDB(B1, 0, 1); PG8_SCHED; PG8_LDA(At, 0, 0); PG8_STAGE(PG8_SA(1, 1), a1 + hstepA, voffA);
;             PG8_WAIT_V(8); PG8_WAIT_L(0); PG8_BAR; PG8_MMA(0, 0, At, B0); PG8_MMA(0, 1, At, B1); PG8_BAR; PG8_SCHED;
;     ...
; #pragma unroll
;         for (int a = 0; a < 2; ++a)
; #pragma unroll
;             for (int b = 0; b < 2; ++b)
; #pragma unroll
;                 for (int m = 0; m < 4; ++m)
; #pragma unroll
;                     for (int n = 0; n < 2; ++n) acc[a][b][m][n] = (f32x4){0.f, 0.f, 0.f, 0.f};
.LBB0_281:
	s_ashr_i32 s25, s24, 31
	s_lshl_b64 s[26:27], s[24:25], 19
	s_add_u32 s26, s48, s26
	s_addc_u32 s27, s49, s27
	s_and_b64 s[28:29], s[4:5], exec
	s_cselect_b32 s25, s27, s37
	s_cselect_b32 s31, s26, s36
	s_ashr_i32 s23, s22, 31
	s_lshl_b64 s[28:29], s[22:23], 19
	s_add_u32 s28, s0, s28
	s_addc_u32 s29, s1, s29
	s_and_b64 s[38:39], s[4:5], exec
	s_cselect_b32 s23, s29, s35
	s_cselect_b32 s40, s28, s34
	s_add_u32 s41, s34, 0x100
	s_addc_u32 s42, s35, 0
	s_add_u32 s34, s36, 0x40080
	v_mov_b32_e32 v2, 0
	s_addc_u32 s35, s37, 0
	s_mov_b32 s43, -2
	v_mov_b32_e32 v3, v2
	v_mov_b32_e32 v4, v2
	v_mov_b32_e32 v5, v2
	v_mov_b32_e32 v6, v2
	v_mov_b32_e32 v7, v2
	v_mov_b32_e32 v8, v2
	v_mov_b32_e32 v9, v2
	v_mov_b32_e32 v18, v2
	v_mov_b32_e32 v19, v2
	v_mov_b32_e32 v20, v2
	v_mov_b32_e32 v21, v2
	v_mov_b32_e32 v22, v2
	v_mov_b32_e32 v23, v2
	v_mov_b32_e32 v24, v2
	v_mov_b32_e32 v25, v2
	v_mov_b32_e32 v34, v2
	v_mov_b32_e32 v35, v2
	v_mov_b32_e32 v36, v2
	v_mov_b32_e32 v37, v2
	v_mov_b32_e32 v38, v2
	v_mov_b32_e32 v39, v2
	v_mov_b32_e32 v40, v2
	v_mov_b32_e32 v41, v2
	v_mov_b32_e32 v50, v2
	v_mov_b32_e32 v51, v2
	v_mov_b32_e32 v52, v2
	v_mov_b32_e32 v53, v2
	v_mov_b32_e32 v54, v2
	v_mov_b32_e32 v55, v2
	v_mov_b32_e32 v56, v2
	v_mov_b32_e32 v57, v2
	v_mov_b32_e32 v10, v2
	v_mov_b32_e32 v11, v2
	v_mov_b32_e32 v12, v2
	v_mov_b32_e32 v13, v2
	v_mov_b32_e32 v14, v2
	v_mov_b32_e32 v15, v2
	v_mov_b32_e32 v16, v2
	v_mov_b32_e32 v17, v2
	v_mov_b32_e32 v26, v2
	v_mov_b32_e32 v27, v2
	v_mov_b32_e32 v28, v2
	v_mov_b32_e32 v29, v2
	v_mov_b32_e32 v30, v2
	v_mov_b32_e32 v31, v2
	v_mov_b32_e32 v32, v2
	v_mov_b32_e32 v33, v2
	v_mov_b32_e32 v42, v2
	v_mov_b32_e32 v43, v2
	v_mov_b32_e32 v44, v2
	v_mov_b32_e32 v45, v2
	v_mov_b32_e32 v46, v2
	v_mov_b32_e32 v47, v2
	v_mov_b32_e32 v48, v2
	v_mov_b32_e32 v49, v2
	v_mov_b32_e32 v58, v2
	v_mov_b32_e32 v59, v2
	v_mov_b32_e32 v60, v2
	v_mov_b32_e32 v61, v2
	v_mov_b32_e32 v62, v2
	v_mov_b32_e32 v63, v2
	v_mov_b32_e32 v64, v2
	v_mov_b32_e32 v65, v2
	v_mov_b32_e32 v66, v2
	v_mov_b32_e32 v67, v2
	v_mov_b32_e32 v68, v2
	v_mov_b32_e32 v69, v2
	v_mov_b32_e32 v70, v2
	v_mov_b32_e32 v71, v2
	v_mov_b32_e32 v72, v2
	v_mov_b32_e32 v73, v2
	v_mov_b32_e32 v82, v2
	v_mov_b32_e32 v83, v2
	v_mov_b32_e32 v84, v2
	v_mov_b32_e32 v85, v2
	v_mov_b32_e32 v86, v2
	v_mov_b32_e32 v87, v2
	v_mov_b32_e32 v88, v2
	v_mov_b32_e32 v89, v2
	v_mov_b32_e32 v98, v2
	v_mov_b32_e32 v99, v2
	v_mov_b32_e32 v100, v2
	v_mov_b32_e32 v101, v2
	v_mov_b32_e32 v102, v2
	v_mov_b32_e32 v103, v2
	v_mov_b32_e32 v104, v2
	v_mov_b32_e32 v105, v2
	v_mov_b32_e32 v114, v2
	v_mov_b32_e32 v115, v2
	v_mov_b32_e32 v116, v2
	v_mov_b32_e32 v117, v2
	v_mov_b32_e32 v118, v2
	v_mov_b32_e32 v119, v2
	v_mov_b32_e32 v120, v2
	v_mov_b32_e32 v121, v2
	v_mov_b32_e32 v74, v2
	v_mov_b32_e32 v75, v2
	v_mov_b32_e32 v76, v2
	v_mov_b32_e32 v77, v2
	v_mov_b32_e32 v78, v2
	v_mov_b32_e32 v79, v2
	v_mov_b32_e32 v80, v2
	v_mov_b32_e32 v81, v2
	v_mov_b32_e32 v90, v2
	v_mov_b32_e32 v91, v2
	v_mov_b32_e32 v92, v2
	v_mov_b32_e32 v93, v2
	v_mov_b32_e32 v94, v2
	v_mov_b32_e32 v95, v2
	v_mov_b32_e32 v96, v2
	v_mov_b32_e32 v97, v2
	v_mov_b32_e32 v106, v2
	v_mov_b32_e32 v107, v2
	v_mov_b32_e32 v108, v2
	v_mov_b32_e32 v109, v2
	v_mov_b32_e32 v110, v2
	v_mov_b32_e32 v111, v2
	v_mov_b32_e32 v112, v2
	v_mov_b32_e32 v113, v2
	v_mov_b32_e32 v122, v2
	v_mov_b32_e32 v123, v2
	v_mov_b32_e32 v124, v2
	v_mov_b32_e32 v125, v2
	v_mov_b32_e32 v126, v2
	v_mov_b32_e32 v127, v2
	v_mov_b32_e32 v128, v2
	v_mov_b32_e32 v129, v2
	v_readlane_b32 s98, v250, 4
	s_cmp_lt_u32 s98, 4
	s_cbranch_scc1 .Lgp_1
	s_setprio 1
.Lgp_1:
.LBB0_282:
	ds_read_b128 v[158:161], v163
	ds_read_b128 v[166:169], v163 offset:1024
	ds_read_b128 v[170:173], v163 offset:2048
	ds_read_b128 v[174:177], v163 offset:3072
	ds_read_b128 v[178:181], v164
	ds_read_b128 v[188:191], v164 offset:1024
	ds_read_b128 v[192:195], v164 offset:2048
	ds_read_b128 v[196:199], v164 offset:3072
	s_add_u32 s36, s34, 0xfffc0080
	s_addc_u32 s37, s35, -1
	s_cmp_eq_u32 s43, 12
	s_cselect_b32 s39, s25, s37
	s_cselect_b32 s38, s31, s36
	s_cselect_b32 s37, s23, s42
	s_cselect_b32 s36, s40, s41
	v_lshl_add_u64 v[182:183], s[34:35], 0, v[148:149]
	s_add_i32 m0, s44, 0xc000
	ds_read_b128 v[200:203], v165
	ds_read_b128 v[204:207], v165 offset:1024
	ds_read_b128 v[208:211], v165 offset:2048
	ds_read_b128 v[212:215], v165 offset:3072
	ds_read_b128 v[216:219], v165 offset:4096
	ds_read_b128 v[220:223], v165 offset:5120
	ds_read_b128 v[224:227], v165 offset:6144
	ds_read_b128 v[228:231], v165 offset:7168
	global_load_lds_dwordx4 v[182:183], off
	v_lshl_add_u64 v[182:183], s[34:35], 0, v[146:147]
	s_add_i32 m0, s44, 0xe000
	s_nop 0
	global_load_lds_dwordx4 v[182:183], off
	s_waitcnt vmcnt(8)
	s_waitcnt lgkmcnt(0)
	s_barrier
; #define PG8_STAGE(bufoff, gbase, voff) do { _Pragma("unroll") for (int _i = 0; _i < 2; ++_i) \
;         __builtin_amdgcn_global_load_lds((const unsigned*)((const char*)(gbase) + (voff)[_i]), (PG8_LAS unsigned*)(lds + (bufoff) + ldsw + _i * 8192), 16, 0, 0); } while (0)
; #define PG8_LDA(dst, b, h) do { _Pragma("unroll") for (int m = 0; m < 4; ++m) _Pragma("unroll") for (int k = 0; k < 2; ++k) dst[m][k] = *(const PG8_LAS bf16x8*)(lds + PG8_SA(b, h) + aoff + m * 2048 + k * 1024); } while (0)
; #define PG8_MMA(ai, bj, At, Bt) do { __builtin_amdgcn_s_setprio(1); _Pragma("unroll") for (int m = 0; m < 4; ++m) _Pragma("unroll") for (int n = 0; n < 2; ++n) _Pragma("unroll") for (int k = 0; k < 2; ++k) \
;         acc[ai][bj][m][n] = __builtin_amdgcn_mfma_f32_16x16x32_bf16(Bt[n][k], At[m][k], acc[ai][bj][m][n], 0, 0, 0); __builtin_amdgcn_s_setprio(0); } while (0)
; #define PG8_WAIT_V(n) asm volatile("s_waitcnt vmcnt(" #n ")" ::: "memory")
; #define PG8_WAIT_L(n) asm volatile("s_waitcnt lgkmcnt(" #n ")" ::: "memory")
; #define PG8_BAR __builtin_amdgcn_s_barrier()
; #define PG8_SCHED __builtin_amdgcn_sched_barrier(0)
; template <class Epi, class Sched, bool ALIGN_EPI = false, bool SP2 = false>
; __device__ __forceinline__ void gemm_phase(PG8_LAS unsigned char* lds, const Gemm g, const Sched& S, const Epi& E) {
;     ...
;             PG8_WAIT_V(8); PG8_WAIT_L(0); PG8_BAR; PG8_MMA(0, 0, At, B0); PG8_MMA(0, 1, At, B1); PG8_BAR; PG8_SCHED;
;             PG8_LDA(At, 0, 1); PG8_STAGE(PG8_SB(0, 0), b2, voffB); PG8_STAGE(PG8_SB(0, 1), b2 + hstepB, voffB); PG8_STAGE(PG8_SA(0, 0), a2, voffA);
;             PG8_WAIT_V(8); PG8_WAIT_L(0); PG8_BAR; PG8_MMA(1, 0, At, B0); PG8_MMA(1, 1, At, B1); PG8_BAR; PG8_SCHED;
	s_waitcnt lgkmcnt(0)
	v_mfma_f32_16x16x32_bf16 v[126:129], v[158:161], v[200:203], v[126:129]
	v_mfma_f32_16x16x32_bf16 v[122:125], v[170:173], v[200:203], v[122:125]
	v_mfma_f32_16x16x32_bf16 v[110:113], v[158:161], v[208:211], v[110:113]
	v_mfma_f32_16x16x32_bf16 v[106:109], v[170:173], v[208:211], v[106:109]
	v_mfma_f32_16x16x32_bf16 v[94:97], v[158:161], v[216:219], v[94:97]
	v_mfma_f32_16x16x32_bf16 v[90:93], v[170:173], v[216:219], v[90:93]
	v_mfma_f32_16x16x32_bf16 v[78:81], v[158:161], v[224:227], v[78:81]
	v_mfma_f32_16x16x32_bf16 v[74:77], v[170:173], v[224:227], v[74:77]
	v_mfma_f32_16x16x32_bf16 v[126:129], v[166:169], v[204:207], v[126:129]
	v_mfma_f32_16x16x32_bf16 v[122:125], v[174:177], v[204:207], v[122:125]
	v_mfma_f32_16x16x32_bf16 v[110:113], v[166:169], v[212:215], v[110:113]
	v_mfma_f32_16x16x32_bf16 v[106:109], v[174:177], v[212:215], v[106:109]
	v_mfma_f32_16x16x32_bf16 v[94:97], v[166:169], v[220:223], v[94:97]
	v_mfma_f32_16x16x32_bf16 v[90:93], v[174:177], v[220:223], v[90:93]
	v_mfma_f32_16x16x32_bf16 v[78:81], v[166:169], v[228:231], v[78:81]
	v_mfma_f32_16x16x32_bf16 v[74:77], v[174:177], v[228:231], v[74:77]
	v_mfma_f32_16x16x32_bf16 v[118:121], v[178:181], v[200:203], v[118:121]
	v_mfma_f32_16x16x32_bf16 v[114:117], v[192:195], v[200:203], v[114:117]
	v_mfma_f32_16x16x32_bf16 v[102:105], v[178:181], v[208:211], v[102:105]
	v_mfma_f32_16x16x32_bf16 v[98:101], v[192:195], v[208:211], v[98:101]
	v_mfma_f32_16x16x32_bf16 v[86:89], v[178:181], v[216:219], v[86:89]
	v_mfma_f32_16x16x32_bf16 v[82:85], v[192:195], v[216:219], v[82:85]
	v_mfma_f32_16x16x32_bf16 v[70:73], v[178:181], v[224:227], v[70:73]
	v_mfma_f32_16x16x32_bf16 v[66:69], v[192:195], v[224:227], v[66:69]
	v_mfma_f32_16x16x32_bf16 v[118:121], v[188:191], v[204:207], v[118:121]
	v_mfma_f32_16x16x32_bf16 v[114:117], v[196:199], v[204:207], v[114:117]
	v_mfma_f32_16x16x32_bf16 v[102:105], v[188:191], v[212:215], v[102:105]
	v_mfma_f32_16x16x32_bf16 v[98:101], v[196:199], v[212:215], v[98:101]
	v_mfma_f32_16x16x32_bf16 v[86:89], v[188:191], v[220:223], v[86:89]
	v_mfma_f32_16x16x32_bf16 v[82:85], v[196:199], v[220:223], v[82:85]
	v_mfma_f32_16x16x32_bf16 v[70:73], v[188:191], v[228:231], v[70:73]
	v_mfma_f32_16x16x32_bf16 v[66:69], v[196:199], v[228:231], v[66:69]
	s_barrier
	s_add_i32 s65, s62, s33
	v_lshl_add_u64 v[182:183], s[36:37], 0, v[132:133]
	s_mov_b32 m0, s65
	ds_read_b128 v[200:203], v165 offset:16384
	ds_read_b128 v[204:207], v165 offset:17408
	ds_read_b128 v[208:211], v165 offset:18432
	ds_read_b128 v[212:215], v165 offset:19456
	ds_read_b128 v[216:219], v165 offset:20480
	ds_read_b128 v[220:223], v165 offset:21504
	ds_read_b128 v[224:227], v165 offset:22528
	ds_read_b128 v[228:231], v165 offset:23552
	global_load_lds_dwordx4 v[182:183], off
	s_add_i32 m0, s65, 0x2000
	s_add_u32 s66, s36, 0x40000
	v_lshl_add_u64 v[232:233], s[36:37], 0, v[136:137]
	s_addc_u32 s67, s37, 0
	s_add_i32 s65, s63, s33
	global_load_lds_dwordx4 v[232:233], off
	v_lshl_add_u64 v[234:235], s[66:67], 0, v[132:133]
	s_mov_b32 m0, s65
	v_lshl_add_u64 v[236:237], s[38:39], 0, v[134:135]
	global_load_lds_dwordx4 v[234:235], off
	v_lshl_add_u64 v[234:235], s[66:67], 0, v[136:137]
	s_add_i32 m0, s65, 0x2000
	s_nop 0
	global_load_lds_dwordx4 v[234:235], off
	v_lshl_add_u64 v[234:235], s[38:39], 0, v[130:131]
	s_mov_b32 m0, s44
	s_nop 0
	global_load_lds_dwordx4 v[234:235], off
	s_mov_b32 m0, s45
	s_nop 0
	global_load_lds_dwordx4 v[236:237], off
	s_waitcnt vmcnt(8)
	s_waitcnt lgkmcnt(0)
	s_barrier
	s_waitcnt lgkmcnt(0)
	v_mfma_f32_16x16x32_bf16 v[62:65], v[158:161], v[200:203], v[62:65]
	v_mfma_f32_16x16x32_bf16 v[58:61], v[170:173], v[200:203], v[58:61]
	v_mfma_f32_16x16x32_bf16 v[46:49], v[158:161], v[208:211], v[46:49]
	v_mfma_f32_16x16x32_bf16 v[42:45], v[170:173], v[208:211], v[42:45]
	v_mfma_f32_16x16x32_bf16 v[30:33], v[158:161], v[216:219], v[30:33]
	v_mfma_f32_16x16x32_bf16 v[26:29], v[170:173], v[216:219], v[26:29]
	v_mfma_f32_16x16x32_bf16 v[14:17], v[158:161], v[224:227], v[14:17]
	v_mfma_f32_16x16x32_bf16 v[10:13], v[170:173], v[224:227], v[10:13]
	v_mfma_f32_16x16x32_bf16 v[62:65], v[166:169], v[204:207], v[62:65]
	v_mfma_f32_16x16x32_bf16 v[58:61], v[174:177], v[204:207], v[58:61]
	v_mfma_f32_16x16x32_bf16 v[46:49], v[166:169], v[212:215], v[46:49]
	v_mfma_f32_16x16x32_bf16 v[42:45], v[174:177], v[212:215], v[42:45]
	v_mfma_f32_16x16x32_bf16 v[30:33], v[166:169], v[220:223], v[30:33]
	v_mfma_f32_16x16x32_bf16 v[26:29], v[174:177], v[220:223], v[26:29]
	v_mfma_f32_16x16x32_bf16 v[14:17], v[166:169], v[228:231], v[14:17]
	v_mfma_f32_16x16x32_bf16 v[10:13], v[174:177], v[228:231], v[10:13]
	v_mfma_f32_16x16x32_bf16 v[54:57], v[178:181], v[200:203], v[54:57]
	v_mfma_f32_16x16x32_bf16 v[50:53], v[192:195], v[200:203], v[50:53]
	v_mfma_f32_16x16x32_bf16 v[38:41], v[178:181], v[208:211], v[38:41]
	v_mfma_f32_16x16x32_bf16 v[34:37], v[192:195], v[208:211], v[34:37]
	v_mfma_f32_16x16x32_bf16 v[22:25], v[178:181], v[216:219], v[22:25]
	v_mfma_f32_16x16x32_bf16 v[18:21], v[192:195], v[216:219], v[18:21]
	v_mfma_f32_16x16x32_bf16 v[6:9], v[178:181], v[224:227], v[6:9]
	v_mfma_f32_16x16x32_bf16 v[2:5], v[192:195], v[224:227], v[2:5]
	v_mfma_f32_16x16x32_bf16 v[54:57], v[188:191], v[204:207], v[54:57]
	v_mfma_f32_16x16x32_bf16 v[50:53], v[196:199], v[204:207], v[50:53]
	v_mfma_f32_16x16x32_bf16 v[38:41], v[188:191], v[212:215], v[38:41]
	v_mfma_f32_16x16x32_bf16 v[34:37], v[196:199], v[212:215], v[34:37]
	v_mfma_f32_16x16x32_bf16 v[22:25], v[188:191], v[220:223], v[22:25]
	v_mfma_f32_16x16x32_bf16 v[18:21], v[196:199], v[220:223], v[18:21]
	v_mfma_f32_16x16x32_bf16 v[6:9], v[188:191], v[228:231], v[6:9]
	v_mfma_f32_16x16x32_bf16 v[2:5], v[196:199], v[228:231], v[2:5]
	s_barrier
; #define PG8_STAGE(bufoff, gbase, voff) do { _Pragma("unroll") for (int _i = 0; _i < 2; ++_i) \
;         __builtin_amdgcn_global_load_lds((const unsigned*)((const char*)(gbase) + (voff)[_i]), (PG8_LAS unsigned*)(lds + (bufoff) + ldsw + _i * 8192), 16, 0, 0); } while (0)
; #define PG8_LDA(dst, b, h) do { _Pragma("unroll") for (int m = 0; m < 4; ++m) _Pragma("unroll") for (int k = 0; k < 2; ++k) dst[m][k] = *(const PG8_LAS bf16x8*)(lds + PG8_SA(b, h) + aoff + m * 2048 + k * 1024); } while (0)
; #define PG8_LDB(dst, b, h) do { _Pragma("unroll") for (int n = 0; n < 2; ++n) _Pragma("unroll") for (int k = 0; k < 2; ++k) dst[n][k] = *(const PG8_LAS bf16x8*)(lds + PG8_SB(b, h) + boff + n * 2048 + k * 1024); } while (0)
; #define PG8_MMA(ai, bj, At, Bt) do { __builtin_amdgcn_s_setprio(1); _Pragma("unroll") for (int m = 0; m < 4; ++m) _Pragma("unroll") for (int n = 0; n < 2; ++n) _Pragma("unroll") for (int k = 0; k < 2; ++k) \
;         acc[ai][bj][m][n] = __builtin_amdgcn_mfma_f32_16x16x32_bf16(Bt[n][k], At[m][k], acc[ai][bj][m][n], 0, 0, 0); __builtin_amdgcn_s_setprio(0); } while (0)
; #define PG8_WAIT_V(n) asm volatile("s_waitcnt vmcnt(" #n ")" ::: "memory")
; #define PG8_WAIT_L(n) asm volatile("s_waitcnt lgkmcnt(" #n ")" ::: "memory")
; #define PG8_BAR __builtin_amdgcn_s_barrier()
; #define PG8_SCHED __builtin_amdgcn_sched_barrier(0)
; template <class Epi, class Sched, bool ALIGN_EPI = false, bool SP2 = false>
; __device__ __forceinline__ void gemm_phase(PG8_LAS unsigned char* lds, const Gemm g, const Sched& S, const Epi& E) {
;     ...
;             PG8_LDB(B0, 1, 0); PG8_LDB(B1, 1, 1); PG8_SCHED; PG8_LDA(At, 1, 0); PG8_STAGE(PG8_SA(0, 1), a2 + hstepA, voffA);
;             PG8_WAIT_V(8); PG8_WAIT_L(0); PG8_BAR; PG8_MMA(0, 0, At, B0); PG8_MMA(0, 1, At, B1); PG8_BAR; PG8_SCHED;
	s_add_i32 s65, 0, 0x18000
	s_add_i32 s66, 0, 0x1c000
	v_add_u32_e32 v174, s65, v162
	v_add_u32_e32 v187, s66, v162
	ds_read_b128 v[158:161], v174
	ds_read_b128 v[166:169], v174 offset:1024
	ds_read_b128 v[170:173], v174 offset:2048
	ds_read_b128 v[174:177], v174 offset:3072
	ds_read_b128 v[178:181], v187
	ds_read_b128 v[188:191], v187 offset:1024
	ds_read_b128 v[192:195], v187 offset:2048
	ds_read_b128 v[196:199], v187 offset:3072
	s_add_u32 s38, s38, 0x40000
	s_addc_u32 s39, s39, 0
	s_mov_b32 m0, s46
	v_lshl_add_u64 v[238:239], s[38:39], 0, v[130:131]
	ds_read_b128 v[200:203], v165 offset:32768
	ds_read_b128 v[204:207], v165 offset:33792
	ds_read_b128 v[208:211], v165 offset:34816
	ds_read_b128 v[212:215], v165 offset:35840
	ds_read_b128 v[216:219], v165 offset:36864
	ds_read_b128 v[220:223], v165 offset:37888
	ds_read_b128 v[224:227], v165 offset:38912
	ds_read_b128 v[228:231], v165 offset:39936
	global_load_lds_dwordx4 v[238:239], off
	v_lshl_add_u64 v[238:239], s[38:39], 0, v[134:135]
	s_mov_b32 m0, s47
	s_nop 0
	global_load_lds_dwordx4 v[238:239], off
	s_waitcnt vmcnt(8)
	s_waitcnt lgkmcnt(0)
	s_barrier
	s_waitcnt lgkmcnt(0)
	v_mfma_f32_16x16x32_bf16 v[126:129], v[158:161], v[200:203], v[126:129]
	v_mfma_f32_16x16x32_bf16 v[122:125], v[170:173], v[200:203], v[122:125]
	v_mfma_f32_16x16x32_bf16 v[110:113], v[158:161], v[208:211], v[110:113]
	v_mfma_f32_16x16x32_bf16 v[106:109], v[170:173], v[208:211], v[106:109]
	v_mfma_f32_16x16x32_bf16 v[94:97], v[158:161], v[216:219], v[94:97]
	v_mfma_f32_16x16x32_bf16 v[90:93], v[170:173], v[216:219], v[90:93]
	v_mfma_f32_16x16x32_bf16 v[78:81], v[158:161], v[224:227], v[78:81]
	v_mfma_f32_16x16x32_bf16 v[74:77], v[170:173], v[224:227], v[74:77]
	v_mfma_f32_16x16x32_bf16 v[126:129], v[166:169], v[204:207], v[126:129]
	v_mfma_f32_16x16x32_bf16 v[122:125], v[174:177], v[204:207], v[122:125]
	v_mfma_f32_16x16x32_bf16 v[110:113], v[166:169], v[212:215], v[110:113]
	v_mfma_f32_16x16x32_bf16 v[106:109], v[174:177], v[212:215], v[106:109]
	v_mfma_f32_16x16x32_bf16 v[94:97], v[166:169], v[220:223], v[94:97]
	v_mfma_f32_16x16x32_bf16 v[90:93], v[174:177], v[220:223], v[90:93]
	v_mfma_f32_16x16x32_bf16 v[78:81], v[166:169], v[228:231], v[78:81]
	v_mfma_f32_16x16x32_bf16 v[74:77], v[174:177], v[228:231], v[74:77]
	v_mfma_f32_16x16x32_bf16 v[118:121], v[178:181], v[200:203], v[118:121]
	v_mfma_f32_16x16x32_bf16 v[114:117], v[192:195], v[200:203], v[114:117]
	v_mfma_f32_16x16x32_bf16 v[102:105], v[178:181], v[208:211], v[102:105]
	v_mfma_f32_16x16x32_bf16 v[98:101], v[192:195], v[208:211], v[98:101]
	v_mfma_f32_16x16x32_bf16 v[86:89], v[178:181], v[216:219], v[86:89]
	v_mfma_f32_16x16x32_bf16 v[82:85], v[192:195], v[216:219], v[82:85]
	v_mfma_f32_16x16x32_bf16 v[70:73], v[178:181], v[224:227], v[70:73]
	v_mfma_f32_16x16x32_bf16 v[66:69], v[192:195], v[224:227], v[66:69]
	v_mfma_f32_16x16x32_bf16 v[118:121], v[188:191], v[204:207], v[118:121]
	v_mfma_f32_16x16x32_bf16 v[114:117], v[196:199], v[204:207], v[114:117]
	v_mfma_f32_16x16x32_bf16 v[102:105], v[188:191], v[212:215], v[102:105]
	v_mfma_f32_16x16x32_bf16 v[98:101], v[196:199], v[212:215], v[98:101]
	v_mfma_f32_16x16x32_bf16 v[86:89], v[188:191], v[220:223], v[86:89]
	v_mfma_f32_16x16x32_bf16 v[82:85], v[196:199], v[220:223], v[82:85]
	v_mfma_f32_16x16x32_bf16 v[70:73], v[188:191], v[228:231], v[70:73]
	v_mfma_f32_16x16x32_bf16 v[66:69], v[196:199], v[228:231], v[66:69]
	s_barrier
; #define PG8_STAGE(bufoff, gbase, voff) do { _Pragma("unroll") for (int _i = 0; _i < 2; ++_i) \
;         __builtin_amdgcn_global_load_lds((const unsigned*)((const char*)(gbase) + (voff)[_i]), (PG8_LAS unsigned*)(lds + (bufoff) + ldsw + _i * 8192), 16, 0, 0); } while (0)
; #define PG8_LDA(dst, b, h) do { _Pragma("unroll") for (int m = 0; m < 4; ++m) _Pragma("unroll") for (int k = 0; k < 2; ++k) dst[m][k] = *(const PG8_LAS bf16x8*)(lds + PG8_SA(b, h) + aoff + m * 2048 + k * 1024); } while (0)
; #define PG8_MMA(ai, bj, At, Bt) do { __builtin_amdgcn_s_setprio(1); _Pragma("unroll") for (int m = 0; m < 4; ++m) _Pragma("unroll") for (int n = 0; n < 2; ++n) _Pragma("unroll") for (int k = 0; k < 2; ++k) \
;         acc[ai][bj][m][n] = __builtin_amdgcn_mfma_f32_16x16x32_bf16(Bt[n][k], At[m][k], acc[ai][bj][m][n], 0, 0, 0); __builtin_amdgcn_s_setprio(0); } while (0)
; #define PG8_WAIT_V(n) asm volatile("s_waitcnt vmcnt(" #n ")" ::: "memory")
; #define PG8_WAIT_L(n) asm volatile("s_waitcnt lgkmcnt(" #n ")" ::: "memory")
; #define PG8_BAR __builtin_amdgcn_s_barrier()
; #define PG8_SCHED __builtin_amdgcn_sched_barrier(0)
; template <class Epi, class Sched, bool ALIGN_EPI = false, bool SP2 = false>
; __device__ __forceinline__ void gemm_phase(PG8_LAS unsigned char* lds, const Gemm g, const Sched& S, const Epi& E) {
;     ...
;             PG8_LDA(At, 1, 1); PG8_STAGE(PG8_SB(1, 0), b3, voffB); PG8_STAGE(PG8_SB(1, 1), b3 + hstepB, voffB); PG8_STAGE(PG8_SA(1, 0), a3, voffA);
;             PG8_WAIT_V(8); PG8_WAIT_L(0); PG8_BAR; PG8_MMA(1, 0, At, B0); PG8_MMA(1, 1, At, B1); PG8_BAR; PG8_SCHED;
;     ...
;         if constexpr (ALIGN_EPI) { if (wr == 0) PG8_BAR; }
	s_add_i32 s38, s65, s33
	v_lshl_add_u64 v[182:183], v[182:183], 0, s[8:9]
	s_mov_b32 m0, s38
	ds_read_b128 v[200:203], v165 offset:49152
	ds_read_b128 v[204:207], v165 offset:50176
	ds_read_b128 v[208:211], v165 offset:51200
	ds_read_b128 v[212:215], v165 offset:52224
	ds_read_b128 v[216:219], v165 offset:53248
	ds_read_b128 v[220:223], v165 offset:54272
	ds_read_b128 v[224:227], v165 offset:55296
	ds_read_b128 v[228:231], v165 offset:56320
	global_load_lds_dwordx4 v[182:183], off
	s_add_i32 m0, s38, 0x2000
	s_add_u32 s36, s36, 0x40080
	v_lshl_add_u64 v[182:183], v[232:233], 0, s[8:9]
	s_addc_u32 s37, s37, 0
	s_add_i32 s38, s66, s33
	global_load_lds_dwordx4 v[182:183], off
	v_lshl_add_u64 v[182:183], s[36:37], 0, v[132:133]
	s_mov_b32 m0, s38
	s_nop 0
	global_load_lds_dwordx4 v[182:183], off
	v_lshl_add_u64 v[182:183], s[36:37], 0, v[136:137]
	s_add_i32 m0, s38, 0x2000
	s_nop 0
	global_load_lds_dwordx4 v[182:183], off
	v_lshl_add_u64 v[182:183], v[234:235], 0, s[8:9]
	s_mov_b32 m0, s50
	s_nop 0
	global_load_lds_dwordx4 v[182:183], off
	v_lshl_add_u64 v[182:183], v[236:237], 0, s[8:9]
	s_mov_b32 m0, s51
	s_nop 0
	global_load_lds_dwordx4 v[182:183], off
	s_waitcnt vmcnt(8)
	s_waitcnt lgkmcnt(0)
	s_barrier
	s_waitcnt lgkmcnt(0)
	v_mfma_f32_16x16x32_bf16 v[62:65], v[158:161], v[200:203], v[62:65]
	v_mfma_f32_16x16x32_bf16 v[58:61], v[170:173], v[200:203], v[58:61]
	v_mfma_f32_16x16x32_bf16 v[46:49], v[158:161], v[208:211], v[46:49]
	v_mfma_f32_16x16x32_bf16 v[42:45], v[170:173], v[208:211], v[42:45]
	v_mfma_f32_16x16x32_bf16 v[30:33], v[158:161], v[216:219], v[30:33]
	v_mfma_f32_16x16x32_bf16 v[26:29], v[170:173], v[216:219], v[26:29]
	v_mfma_f32_16x16x32_bf16 v[14:17], v[158:161], v[224:227], v[14:17]
	v_mfma_f32_16x16x32_bf16 v[10:13], v[170:173], v[224:227], v[10:13]
	v_mfma_f32_16x16x32_bf16 v[62:65], v[166:169], v[204:207], v[62:65]
	v_mfma_f32_16x16x32_bf16 v[58:61], v[174:177], v[204:207], v[58:61]
	v_mfma_f32_16x16x32_bf16 v[46:49], v[166:169], v[212:215], v[46:49]
	v_mfma_f32_16x16x32_bf16 v[42:45], v[174:177], v[212:215], v[42:45]
	v_mfma_f32_16x16x32_bf16 v[30:33], v[166:169], v[220:223], v[30:33]
	v_mfma_f32_16x16x32_bf16 v[26:29], v[174:177], v[220:223], v[26:29]
	v_mfma_f32_16x16x32_bf16 v[14:17], v[166:169], v[228:231], v[14:17]
	v_mfma_f32_16x16x32_bf16 v[10:13], v[174:177], v[228:231], v[10:13]
	v_mfma_f32_16x16x32_bf16 v[54:57], v[178:181], v[200:203], v[54:57]
	v_mfma_f32_16x16x32_bf16 v[50:53], v[192:195], v[200:203], v[50:53]
	v_mfma_f32_16x16x32_bf16 v[38:41], v[178:181], v[208:211], v[38:41]
	v_mfma_f32_16x16x32_bf16 v[34:37], v[192:195], v[208:211], v[34:37]
	v_mfma_f32_16x16x32_bf16 v[22:25], v[178:181], v[216:219], v[22:25]
	v_mfma_f32_16x16x32_bf16 v[18:21], v[192:195], v[216:219], v[18:21]
	v_mfma_f32_16x16x32_bf16 v[6:9], v[178:181], v[224:227], v[6:9]
	v_mfma_f32_16x16x32_bf16 v[2:5], v[192:195], v[224:227], v[2:5]
	v_mfma_f32_16x16x32_bf16 v[54:57], v[188:191], v[204:207], v[54:57]
	v_mfma_f32_16x16x32_bf16 v[50:53], v[196:199], v[204:207], v[50:53]
	v_mfma_f32_16x16x32_bf16 v[38:41], v[188:191], v[212:215], v[38:41]
	v_mfma_f32_16x16x32_bf16 v[34:37], v[196:199], v[212:215], v[34:37]
	v_mfma_f32_16x16x32_bf16 v[22:25], v[188:191], v[220:223], v[22:25]
	v_mfma_f32_16x16x32_bf16 v[18:21], v[196:199], v[220:223], v[18:21]
	v_mfma_f32_16x16x32_bf16 v[6:9], v[188:191], v[228:231], v[6:9]
	v_mfma_f32_16x16x32_bf16 v[2:5], v[196:199], v[228:231], v[2:5]
	s_barrier
	s_add_i32 s43, s43, 2
	s_add_u32 s41, s41, 0x100
	s_addc_u32 s42, s42, 0
	s_add_u32 s34, s34, 0x100
	s_addc_u32 s35, s35, 0
	s_cmp_gt_u32 s43, 13
	s_cbranch_scc0 .LBB0_282
	s_setprio 0
	s_and_b64 vcc, exec, s[10:11]
	s_cbranch_vccz .LBB0_287
	s_barrier
	v_lshl_add_u32 v158, s2, 8, v1
	s_cmp_lg_u32 s30, 2
	s_mov_b64 s[34:35], -1
	s_cbranch_scc1 .LBB0_288

; #define PG8_STAGE(bufoff, gbase, voff) do { _Pragma("unroll") for (int _i = 0; _i < 2; ++_i) \
;         __builtin_amdgcn_global_load_lds((const unsigned*)((const char*)(gbase) + (voff)[_i]), (PG8_LAS unsigned*)(lds + (bufoff) + ldsw + _i * 8192), 16, 0, 0); } while (0)
; #define PG8_LDA(dst, b, h) do { _Pragma("unroll") for (int m = 0; m < 4; ++m) _Pragma("unroll") for (int k = 0; k < 2; ++k) dst[m][k] = *(const PG8_LAS bf16x8*)(lds + PG8_SA(b, h) + aoff + m * 2048 + k * 1024); } while (0)
; #define PG8_LDB(dst, b, h) do { _Pragma("unroll") for (int n = 0; n < 2; ++n) _Pragma("unroll") for (int k = 0; k < 2; ++k) dst[n][k] = *(const PG8_LAS bf16x8*)(lds + PG8_SB(b, h) + boff + n * 2048 + k * 1024); } while (0)
; #define PG8_MMA(ai, bj, At, Bt) do { __builtin_amdgcn_s_setprio(1); _Pragma("unroll") for (int m = 0; m < 4; ++m) _Pragma("unroll") for (int n = 0; n < 2; ++n) _Pragma("unroll") for (int k = 0; k < 2; ++k) \
;         acc[ai][bj][m][n] = __builtin_amdgcn_mfma_f32_16x16x32_bf16(Bt[n][k], At[m][k], acc[ai][bj][m][n], 0, 0, 0); __builtin_amdgcn_s_setprio(0); } while (0)
; #define PG8_WAIT_V(n) asm volatile("s_waitcnt vmcnt(" #n ")" ::: "memory")
; #define PG8_BAR __builtin_amdgcn_s_barrier()
; template <class Epi, class Sched, bool ALIGN_EPI = false, bool SP2 = false>
; __device__ __forceinline__ void gemm_phase(PG8_LAS unsigned char* lds, const Gemm g, const Sched& S, const Epi& E) {
;     ...
;         for (int t = 0; t < nt; t += 2) {
;             const bool last = (t == nt - 2);
;             const char* a1 = cA + (size_t)(t + 1) * kstep;
;             const char* a2 = last ? nA : cA + (size_t)(t + 2) * kstep; const char* b2 = last ? nB : cB + (size_t)(t + 2) * kstep;
;             const char* a3 = a2 + kstep; const char* b3 = b2 + kstep;
;             if (last && has_next) S.a_ready(nxt);
;             if constexpr (SP2) {
;             PG8_LDB(B0, 0, 0); PG8_LDB(B1, 0, 1); PG8_SCHED; PG8_LDA(At, 0, 0); PG8_STAGE(PG8_SA(1, 1), a1 + hstepA, voffA);
;             PG8_WAIT_V(8); PG8_WAIT_L(0); PG8_BAR; PG8_MMA(0, 0, At, B0); PG8_MMA(0, 1, At, B1); PG8_BAR; PG8_SCHED;
;     ...
; #pragma unroll
;         for (int a = 0; a < 2; ++a)
; #pragma unroll
;             for (int b = 0; b < 2; ++b)
; #pragma unroll
;                 for (int m = 0; m < 4; ++m)
; #pragma unroll
;                     for (int n = 0; n < 2; ++n) acc[a][b][m][n] = (f32x4){0.f, 0.f, 0.f, 0.f};
.LBB0_673:
	s_ashr_i32 s25, s24, 31
	s_lshl_b64 s[14:15], s[24:25], 18
	s_add_u32 s26, s37, s14
	s_addc_u32 s27, s38, s15
	s_and_b64 s[14:15], s[4:5], exec
	s_cselect_b32 s25, s27, s13
	s_cselect_b32 s48, s26, s12
	s_ashr_i32 s23, s22, 31
	s_lshl_b64 s[14:15], s[22:23], 18
	s_add_u32 s28, s39, s14
	s_addc_u32 s29, s40, s15
	s_and_b64 s[14:15], s[4:5], exec
	s_cselect_b32 s23, s29, s11
	s_cselect_b32 s49, s28, s10
	s_add_u32 s50, s10, 0x100
	s_addc_u32 s51, s11, 0
	s_add_u32 s10, s12, 0x20080
	v_mov_b32_e32 v2, 0
	s_addc_u32 s11, s13, 0
	s_mov_b32 s52, -2
	v_mov_b32_e32 v3, v2
	v_mov_b32_e32 v4, v2
	v_mov_b32_e32 v5, v2
	v_mov_b32_e32 v6, v2
	v_mov_b32_e32 v7, v2
	v_mov_b32_e32 v8, v2
	v_mov_b32_e32 v9, v2
	v_mov_b32_e32 v18, v2
	v_mov_b32_e32 v19, v2
	v_mov_b32_e32 v20, v2
	v_mov_b32_e32 v21, v2
	v_mov_b32_e32 v30, v2
	v_mov_b32_e32 v31, v2
	v_mov_b32_e32 v32, v2
	v_mov_b32_e32 v33, v2
	v_mov_b32_e32 v42, v2
	v_mov_b32_e32 v43, v2
	v_mov_b32_e32 v44, v2
	v_mov_b32_e32 v45, v2
	v_mov_b32_e32 v46, v2
	v_mov_b32_e32 v47, v2
	v_mov_b32_e32 v48, v2
	v_mov_b32_e32 v49, v2
	v_mov_b32_e32 v50, v2
	v_mov_b32_e32 v51, v2
	v_mov_b32_e32 v52, v2
	v_mov_b32_e32 v53, v2
	v_mov_b32_e32 v54, v2
	v_mov_b32_e32 v55, v2
	v_mov_b32_e32 v56, v2
	v_mov_b32_e32 v57, v2
	v_mov_b32_e32 v10, v2
	v_mov_b32_e32 v11, v2
	v_mov_b32_e32 v12, v2
	v_mov_b32_e32 v13, v2
	v_mov_b32_e32 v14, v2
	v_mov_b32_e32 v15, v2
	v_mov_b32_e32 v16, v2
	v_mov_b32_e32 v17, v2
	v_mov_b32_e32 v82, v2
	v_mov_b32_e32 v83, v2
	v_mov_b32_e32 v84, v2
	v_mov_b32_e32 v85, v2
	v_mov_b32_e32 v86, v2
	v_mov_b32_e32 v87, v2
	v_mov_b32_e32 v88, v2
	v_mov_b32_e32 v89, v2
	v_mov_b32_e32 v90, v2
	v_mov_b32_e32 v91, v2
	v_mov_b32_e32 v92, v2
	v_mov_b32_e32 v93, v2
	v_mov_b32_e32 v94, v2
	v_mov_b32_e32 v95, v2
	v_mov_b32_e32 v96, v2
	v_mov_b32_e32 v97, v2
	v_mov_b32_e32 v98, v2
	v_mov_b32_e32 v99, v2
	v_mov_b32_e32 v100, v2
	v_mov_b32_e32 v101, v2
	v_mov_b32_e32 v102, v2
	v_mov_b32_e32 v103, v2
	v_mov_b32_e32 v104, v2
	v_mov_b32_e32 v105, v2
	v_mov_b32_e32 v58, v2
	v_mov_b32_e32 v59, v2
	v_mov_b32_e32 v60, v2
	v_mov_b32_e32 v61, v2
	v_mov_b32_e32 v62, v2
	v_mov_b32_e32 v63, v2
	v_mov_b32_e32 v64, v2
	v_mov_b32_e32 v65, v2
	v_mov_b32_e32 v66, v2
	v_mov_b32_e32 v67, v2
	v_mov_b32_e32 v68, v2
	v_mov_b32_e32 v69, v2
	v_mov_b32_e32 v70, v2
	v_mov_b32_e32 v71, v2
	v_mov_b32_e32 v72, v2
	v_mov_b32_e32 v73, v2
	v_mov_b32_e32 v74, v2
	v_mov_b32_e32 v75, v2
	v_mov_b32_e32 v76, v2
	v_mov_b32_e32 v77, v2
	v_mov_b32_e32 v78, v2
	v_mov_b32_e32 v79, v2
	v_mov_b32_e32 v80, v2
	v_mov_b32_e32 v81, v2
	v_mov_b32_e32 v22, v2
	v_mov_b32_e32 v23, v2
	v_mov_b32_e32 v24, v2
	v_mov_b32_e32 v25, v2
	v_mov_b32_e32 v26, v2
	v_mov_b32_e32 v27, v2
	v_mov_b32_e32 v28, v2
	v_mov_b32_e32 v29, v2
	v_mov_b32_e32 v106, v2
	v_mov_b32_e32 v107, v2
	v_mov_b32_e32 v108, v2
	v_mov_b32_e32 v109, v2
	v_mov_b32_e32 v110, v2
	v_mov_b32_e32 v111, v2
	v_mov_b32_e32 v112, v2
	v_mov_b32_e32 v113, v2
	v_mov_b32_e32 v114, v2
	v_mov_b32_e32 v115, v2
	v_mov_b32_e32 v116, v2
	v_mov_b32_e32 v117, v2
	v_mov_b32_e32 v118, v2
	v_mov_b32_e32 v119, v2
	v_mov_b32_e32 v120, v2
	v_mov_b32_e32 v121, v2
	v_mov_b32_e32 v122, v2
	v_mov_b32_e32 v123, v2
	v_mov_b32_e32 v124, v2
	v_mov_b32_e32 v125, v2
	v_mov_b32_e32 v126, v2
	v_mov_b32_e32 v127, v2
	v_mov_b32_e32 v128, v2
	v_mov_b32_e32 v129, v2
	v_mov_b32_e32 v34, v2
	v_mov_b32_e32 v35, v2
	v_mov_b32_e32 v36, v2
	v_mov_b32_e32 v37, v2
	v_mov_b32_e32 v38, v2
	v_mov_b32_e32 v39, v2
	v_mov_b32_e32 v40, v2
	v_mov_b32_e32 v41, v2
	v_readlane_b32 s98, v250, 4
	s_cmp_lt_u32 s98, 4
	s_cbranch_scc1 .Lgp_2
	s_setprio 1
.Lgp_2:
.LBB0_674:
	ds_read_b128 v[130:133], v180
	ds_read_b128 v[134:137], v180 offset:1024
	ds_read_b128 v[138:141], v180 offset:2048
	ds_read_b128 v[162:165], v180 offset:3072
	ds_read_b128 v[166:169], v181
	ds_read_b128 v[170:173], v181 offset:1024
	ds_read_b128 v[174:177], v181 offset:2048
	ds_read_b128 v[196:199], v181 offset:3072
	s_add_u32 s12, s10, 0xfffe0080
	s_addc_u32 s13, s11, -1
	s_cmp_eq_u32 s52, 4
	s_cselect_b32 s15, s25, s13
	s_cselect_b32 s14, s48, s12
	s_cselect_b32 s13, s23, s51
	s_cselect_b32 s12, s49, s50
	v_lshl_add_u64 v[232:233], s[10:11], 0, v[156:157]
	s_add_i32 m0, s33, 0xc000
	ds_read_b128 v[200:203], v182
	ds_read_b128 v[204:207], v182 offset:1024
	ds_read_b128 v[208:211], v182 offset:2048
	ds_read_b128 v[212:215], v182 offset:3072
	ds_read_b128 v[216:219], v182 offset:4096
	ds_read_b128 v[220:223], v182 offset:5120
	ds_read_b128 v[224:227], v182 offset:6144
	ds_read_b128 v[228:231], v182 offset:7168
	global_load_lds_dwordx4 v[232:233], off
	v_lshl_add_u64 v[232:233], s[10:11], 0, v[154:155]
	s_add_i32 m0, s33, 0xe000
	s_nop 0
	global_load_lds_dwordx4 v[232:233], off
	s_waitcnt vmcnt(8)
	s_waitcnt lgkmcnt(0)
	s_barrier
; #define PG8_STAGE(bufoff, gbase, voff) do { _Pragma("unroll") for (int _i = 0; _i < 2; ++_i) \
;         __builtin_amdgcn_global_load_lds((const unsigned*)((const char*)(gbase) + (voff)[_i]), (PG8_LAS unsigned*)(lds + (bufoff) + ldsw + _i * 8192), 16, 0, 0); } while (0)
; #define PG8_LDA(dst, b, h) do { _Pragma("unroll") for (int m = 0; m < 4; ++m) _Pragma("unroll") for (int k = 0; k < 2; ++k) dst[m][k] = *(const PG8_LAS bf16x8*)(lds + PG8_SA(b, h) + aoff + m * 2048 + k * 1024); } while (0)
; #define PG8_MMA(ai, bj, At, Bt) do { __builtin_amdgcn_s_setprio(1); _Pragma("unroll") for (int m = 0; m < 4; ++m) _Pragma("unroll") for (int n = 0; n < 2; ++n) _Pragma("unroll") for (int k = 0; k < 2; ++k) \
;         acc[ai][bj][m][n] = __builtin_amdgcn_mfma_f32_16x16x32_bf16(Bt[n][k], At[m][k], acc[ai][bj][m][n], 0, 0, 0); __builtin_amdgcn_s_setprio(0); } while (0)
; #define PG8_WAIT_V(n) asm volatile("s_waitcnt vmcnt(" #n ")" ::: "memory")
; #define PG8_WAIT_L(n) asm volatile("s_waitcnt lgkmcnt(" #n ")" ::: "memory")
; #define PG8_BAR __builtin_amdgcn_s_barrier()
; #define PG8_SCHED __builtin_amdgcn_sched_barrier(0)
; template <class Epi, class Sched, bool ALIGN_EPI = false, bool SP2 = false>
; __device__ __forceinline__ void gemm_phase(PG8_LAS unsigned char* lds, const Gemm g, const Sched& S, const Epi& E) {
;     ...
;             PG8_WAIT_V(8); PG8_WAIT_L(0); PG8_BAR; PG8_MMA(0, 0, At, B0); PG8_MMA(0, 1, At, B1); PG8_BAR; PG8_SCHED;
;             PG8_LDA(At, 0, 1); PG8_STAGE(PG8_SB(0, 0), b2, voffB); PG8_STAGE(PG8_SB(0, 1), b2 + hstepB, voffB); PG8_STAGE(PG8_SA(0, 0), a2, voffA);
;             PG8_WAIT_V(8); PG8_WAIT_L(0); PG8_BAR; PG8_MMA(1, 0, At, B0); PG8_MMA(1, 1, At, B1); PG8_BAR; PG8_SCHED;
	s_waitcnt lgkmcnt(0)
	v_mfma_f32_16x16x32_bf16 v[38:41], v[130:133], v[200:203], v[38:41]
	v_mfma_f32_16x16x32_bf16 v[34:37], v[138:141], v[200:203], v[34:37]
	v_mfma_f32_16x16x32_bf16 v[126:129], v[130:133], v[208:211], v[126:129]
	v_mfma_f32_16x16x32_bf16 v[122:125], v[138:141], v[208:211], v[122:125]
	v_mfma_f32_16x16x32_bf16 v[118:121], v[130:133], v[216:219], v[118:121]
	v_mfma_f32_16x16x32_bf16 v[114:117], v[138:141], v[216:219], v[114:117]
	v_mfma_f32_16x16x32_bf16 v[110:113], v[130:133], v[224:227], v[110:113]
	v_mfma_f32_16x16x32_bf16 v[106:109], v[138:141], v[224:227], v[106:109]
	v_mfma_f32_16x16x32_bf16 v[38:41], v[134:137], v[204:207], v[38:41]
	v_mfma_f32_16x16x32_bf16 v[34:37], v[162:165], v[204:207], v[34:37]
	v_mfma_f32_16x16x32_bf16 v[126:129], v[134:137], v[212:215], v[126:129]
	v_mfma_f32_16x16x32_bf16 v[122:125], v[162:165], v[212:215], v[122:125]
	v_mfma_f32_16x16x32_bf16 v[118:121], v[134:137], v[220:223], v[118:121]
	v_mfma_f32_16x16x32_bf16 v[114:117], v[162:165], v[220:223], v[114:117]
	v_mfma_f32_16x16x32_bf16 v[110:113], v[134:137], v[228:231], v[110:113]
	v_mfma_f32_16x16x32_bf16 v[106:109], v[162:165], v[228:231], v[106:109]
	v_mfma_f32_16x16x32_bf16 v[26:29], v[166:169], v[200:203], v[26:29]
	v_mfma_f32_16x16x32_bf16 v[22:25], v[174:177], v[200:203], v[22:25]
	v_mfma_f32_16x16x32_bf16 v[78:81], v[166:169], v[208:211], v[78:81]
	v_mfma_f32_16x16x32_bf16 v[74:77], v[174:177], v[208:211], v[74:77]
	v_mfma_f32_16x16x32_bf16 v[70:73], v[166:169], v[216:219], v[70:73]
	v_mfma_f32_16x16x32_bf16 v[66:69], v[174:177], v[216:219], v[66:69]
	v_mfma_f32_16x16x32_bf16 v[62:65], v[166:169], v[224:227], v[62:65]
	v_mfma_f32_16x16x32_bf16 v[58:61], v[174:177], v[224:227], v[58:61]
	v_mfma_f32_16x16x32_bf16 v[26:29], v[170:173], v[204:207], v[26:29]
	v_mfma_f32_16x16x32_bf16 v[22:25], v[196:199], v[204:207], v[22:25]
	v_mfma_f32_16x16x32_bf16 v[78:81], v[170:173], v[212:215], v[78:81]
	v_mfma_f32_16x16x32_bf16 v[74:77], v[196:199], v[212:215], v[74:77]
	v_mfma_f32_16x16x32_bf16 v[70:73], v[170:173], v[220:223], v[70:73]
	v_mfma_f32_16x16x32_bf16 v[66:69], v[196:199], v[220:223], v[66:69]
	v_mfma_f32_16x16x32_bf16 v[62:65], v[170:173], v[228:231], v[62:65]
	v_mfma_f32_16x16x32_bf16 v[58:61], v[196:199], v[228:231], v[58:61]
	s_barrier
	s_add_i32 s53, s46, s31
	v_lshl_add_u64 v[232:233], s[12:13], 0, v[144:145]
	s_mov_b32 m0, s53
	ds_read_b128 v[200:203], v182 offset:16384
	ds_read_b128 v[204:207], v182 offset:17408
	ds_read_b128 v[208:211], v182 offset:18432
	ds_read_b128 v[212:215], v182 offset:19456
	ds_read_b128 v[216:219], v182 offset:20480
	ds_read_b128 v[220:223], v182 offset:21504
	ds_read_b128 v[224:227], v182 offset:22528
	ds_read_b128 v[228:231], v182 offset:23552
	global_load_lds_dwordx4 v[232:233], off
	s_add_i32 m0, s53, 0x2000
	s_add_u32 s54, s12, 0x20000
	v_lshl_add_u64 v[234:235], s[12:13], 0, v[148:149]
	s_addc_u32 s55, s13, 0
	s_add_i32 s53, s47, s31
	global_load_lds_dwordx4 v[234:235], off
	v_lshl_add_u64 v[236:237], s[54:55], 0, v[144:145]
	s_mov_b32 m0, s53
	v_lshl_add_u64 v[238:239], s[14:15], 0, v[146:147]
	global_load_lds_dwordx4 v[236:237], off
	v_lshl_add_u64 v[236:237], s[54:55], 0, v[148:149]
	s_add_i32 m0, s53, 0x2000
	s_nop 0
	global_load_lds_dwordx4 v[236:237], off
	v_lshl_add_u64 v[236:237], s[14:15], 0, v[142:143]
	s_mov_b32 m0, s33
	s_nop 0
	global_load_lds_dwordx4 v[236:237], off
	s_mov_b32 m0, s34
	s_nop 0
	global_load_lds_dwordx4 v[238:239], off
	s_waitcnt vmcnt(8)
	s_waitcnt lgkmcnt(0)
	s_barrier
	s_waitcnt lgkmcnt(0)
	v_mfma_f32_16x16x32_bf16 v[102:105], v[130:133], v[200:203], v[102:105]
	v_mfma_f32_16x16x32_bf16 v[98:101], v[138:141], v[200:203], v[98:101]
	v_mfma_f32_16x16x32_bf16 v[94:97], v[130:133], v[208:211], v[94:97]
	v_mfma_f32_16x16x32_bf16 v[90:93], v[138:141], v[208:211], v[90:93]
	v_mfma_f32_16x16x32_bf16 v[86:89], v[130:133], v[216:219], v[86:89]
	v_mfma_f32_16x16x32_bf16 v[82:85], v[138:141], v[216:219], v[82:85]
	v_mfma_f32_16x16x32_bf16 v[14:17], v[130:133], v[224:227], v[14:17]
	v_mfma_f32_16x16x32_bf16 v[10:13], v[138:141], v[224:227], v[10:13]
	v_mfma_f32_16x16x32_bf16 v[102:105], v[134:137], v[204:207], v[102:105]
	v_mfma_f32_16x16x32_bf16 v[98:101], v[162:165], v[204:207], v[98:101]
	v_mfma_f32_16x16x32_bf16 v[94:97], v[134:137], v[212:215], v[94:97]
	v_mfma_f32_16x16x32_bf16 v[90:93], v[162:165], v[212:215], v[90:93]
	v_mfma_f32_16x16x32_bf16 v[86:89], v[134:137], v[220:223], v[86:89]
	v_mfma_f32_16x16x32_bf16 v[82:85], v[162:165], v[220:223], v[82:85]
	v_mfma_f32_16x16x32_bf16 v[14:17], v[134:137], v[228:231], v[14:17]
	v_mfma_f32_16x16x32_bf16 v[10:13], v[162:165], v[228:231], v[10:13]
	v_mfma_f32_16x16x32_bf16 v[54:57], v[166:169], v[200:203], v[54:57]
	v_mfma_f32_16x16x32_bf16 v[50:53], v[174:177], v[200:203], v[50:53]
	v_mfma_f32_16x16x32_bf16 v[46:49], v[166:169], v[208:211], v[46:49]
	v_mfma_f32_16x16x32_bf16 v[42:45], v[174:177], v[208:211], v[42:45]
	v_mfma_f32_16x16x32_bf16 v[30:33], v[166:169], v[216:219], v[30:33]
	v_mfma_f32_16x16x32_bf16 v[18:21], v[174:177], v[216:219], v[18:21]
	v_mfma_f32_16x16x32_bf16 v[6:9], v[166:169], v[224:227], v[6:9]
	v_mfma_f32_16x16x32_bf16 v[2:5], v[174:177], v[224:227], v[2:5]
	v_mfma_f32_16x16x32_bf16 v[54:57], v[170:173], v[204:207], v[54:57]
	v_mfma_f32_16x16x32_bf16 v[50:53], v[196:199], v[204:207], v[50:53]
	v_mfma_f32_16x16x32_bf16 v[46:49], v[170:173], v[212:215], v[46:49]
	v_mfma_f32_16x16x32_bf16 v[42:45], v[196:199], v[212:215], v[42:45]
	v_mfma_f32_16x16x32_bf16 v[30:33], v[170:173], v[220:223], v[30:33]
	v_mfma_f32_16x16x32_bf16 v[18:21], v[196:199], v[220:223], v[18:21]
	v_mfma_f32_16x16x32_bf16 v[6:9], v[170:173], v[228:231], v[6:9]
	v_mfma_f32_16x16x32_bf16 v[2:5], v[196:199], v[228:231], v[2:5]
	s_barrier
; #define PG8_STAGE(bufoff, gbase, voff) do { _Pragma("unroll") for (int _i = 0; _i < 2; ++_i) \
;         __builtin_amdgcn_global_load_lds((const unsigned*)((const char*)(gbase) + (voff)[_i]), (PG8_LAS unsigned*)(lds + (bufoff) + ldsw + _i * 8192), 16, 0, 0); } while (0)
; #define PG8_LDA(dst, b, h) do { _Pragma("unroll") for (int m = 0; m < 4; ++m) _Pragma("unroll") for (int k = 0; k < 2; ++k) dst[m][k] = *(const PG8_LAS bf16x8*)(lds + PG8_SA(b, h) + aoff + m * 2048 + k * 1024); } while (0)
; #define PG8_LDB(dst, b, h) do { _Pragma("unroll") for (int n = 0; n < 2; ++n) _Pragma("unroll") for (int k = 0; k < 2; ++k) dst[n][k] = *(const PG8_LAS bf16x8*)(lds + PG8_SB(b, h) + boff + n * 2048 + k * 1024); } while (0)
; #define PG8_MMA(ai, bj, At, Bt) do { __builtin_amdgcn_s_setprio(1); _Pragma("unroll") for (int m = 0; m < 4; ++m) _Pragma("unroll") for (int n = 0; n < 2; ++n) _Pragma("unroll") for (int k = 0; k < 2; ++k) \
;         acc[ai][bj][m][n] = __builtin_amdgcn_mfma_f32_16x16x32_bf16(Bt[n][k], At[m][k], acc[ai][bj][m][n], 0, 0, 0); __builtin_amdgcn_s_setprio(0); } while (0)
; #define PG8_WAIT_V(n) asm volatile("s_waitcnt vmcnt(" #n ")" ::: "memory")
; #define PG8_WAIT_L(n) asm volatile("s_waitcnt lgkmcnt(" #n ")" ::: "memory")
; #define PG8_BAR __builtin_amdgcn_s_barrier()
; #define PG8_SCHED __builtin_amdgcn_sched_barrier(0)
; template <class Epi, class Sched, bool ALIGN_EPI = false, bool SP2 = false>
; __device__ __forceinline__ void gemm_phase(PG8_LAS unsigned char* lds, const Gemm g, const Sched& S, const Epi& E) {
;     ...
;             PG8_LDB(B0, 1, 0); PG8_LDB(B1, 1, 1); PG8_SCHED; PG8_LDA(At, 1, 0); PG8_STAGE(PG8_SA(0, 1), a2 + hstepA, voffA);
;             PG8_WAIT_V(8); PG8_WAIT_L(0); PG8_BAR; PG8_MMA(0, 0, At, B0); PG8_MMA(0, 1, At, B1); PG8_BAR; PG8_SCHED;
	s_add_i32 s53, 0, 0x18000
	s_add_i32 s54, 0, 0x1c000
	v_add_u32_e32 v162, s53, v178
	v_add_u32_e32 v183, s54, v178
	ds_read_b128 v[130:133], v162
	ds_read_b128 v[134:137], v162 offset:1024
	ds_read_b128 v[138:141], v162 offset:2048
	ds_read_b128 v[162:165], v162 offset:3072
	ds_read_b128 v[166:169], v183
	ds_read_b128 v[170:173], v183 offset:1024
	ds_read_b128 v[174:177], v183 offset:2048
	ds_read_b128 v[196:199], v183 offset:3072
	s_add_u32 s14, s14, 0x20000
	s_addc_u32 s15, s15, 0
	s_mov_b32 m0, s35
	v_lshl_add_u64 v[240:241], s[14:15], 0, v[142:143]
	ds_read_b128 v[200:203], v182 offset:32768
	ds_read_b128 v[204:207], v182 offset:33792
	ds_read_b128 v[208:211], v182 offset:34816
	ds_read_b128 v[212:215], v182 offset:35840
	ds_read_b128 v[216:219], v182 offset:36864
	ds_read_b128 v[220:223], v182 offset:37888
	ds_read_b128 v[224:227], v182 offset:38912
	ds_read_b128 v[228:231], v182 offset:39936
	global_load_lds_dwordx4 v[240:241], off
	v_lshl_add_u64 v[240:241], s[14:15], 0, v[146:147]
	s_mov_b32 m0, s36
	s_nop 0
	global_load_lds_dwordx4 v[240:241], off
	s_waitcnt vmcnt(8)
	s_waitcnt lgkmcnt(0)
	s_barrier
	s_waitcnt lgkmcnt(0)
	v_mfma_f32_16x16x32_bf16 v[38:41], v[130:133], v[200:203], v[38:41]
	v_mfma_f32_16x16x32_bf16 v[34:37], v[138:141], v[200:203], v[34:37]
	v_mfma_f32_16x16x32_bf16 v[126:129], v[130:133], v[208:211], v[126:129]
	v_mfma_f32_16x16x32_bf16 v[122:125], v[138:141], v[208:211], v[122:125]
	v_mfma_f32_16x16x32_bf16 v[118:121], v[130:133], v[216:219], v[118:121]
	v_mfma_f32_16x16x32_bf16 v[114:117], v[138:141], v[216:219], v[114:117]
	v_mfma_f32_16x16x32_bf16 v[110:113], v[130:133], v[224:227], v[110:113]
	v_mfma_f32_16x16x32_bf16 v[106:109], v[138:141], v[224:227], v[106:109]
	v_mfma_f32_16x16x32_bf16 v[38:41], v[134:137], v[204:207], v[38:41]
	v_mfma_f32_16x16x32_bf16 v[34:37], v[162:165], v[204:207], v[34:37]
	v_mfma_f32_16x16x32_bf16 v[126:129], v[134:137], v[212:215], v[126:129]
	v_mfma_f32_16x16x32_bf16 v[122:125], v[162:165], v[212:215], v[122:125]
	v_mfma_f32_16x16x32_bf16 v[118:121], v[134:137], v[220:223], v[118:121]
	v_mfma_f32_16x16x32_bf16 v[114:117], v[162:165], v[220:223], v[114:117]
	v_mfma_f32_16x16x32_bf16 v[110:113], v[134:137], v[228:231], v[110:113]
	v_mfma_f32_16x16x32_bf16 v[106:109], v[162:165], v[228:231], v[106:109]
	v_mfma_f32_16x16x32_bf16 v[26:29], v[166:169], v[200:203], v[26:29]
	v_mfma_f32_16x16x32_bf16 v[22:25], v[174:177], v[200:203], v[22:25]
	v_mfma_f32_16x16x32_bf16 v[78:81], v[166:169], v[208:211], v[78:81]
	v_mfma_f32_16x16x32_bf16 v[74:77], v[174:177], v[208:211], v[74:77]
	v_mfma_f32_16x16x32_bf16 v[70:73], v[166:169], v[216:219], v[70:73]
	v_mfma_f32_16x16x32_bf16 v[66:69], v[174:177], v[216:219], v[66:69]
	v_mfma_f32_16x16x32_bf16 v[62:65], v[166:169], v[224:227], v[62:65]
	v_mfma_f32_16x16x32_bf16 v[58:61], v[174:177], v[224:227], v[58:61]
	v_mfma_f32_16x16x32_bf16 v[26:29], v[170:173], v[204:207], v[26:29]
	v_mfma_f32_16x16x32_bf16 v[22:25], v[196:199], v[204:207], v[22:25]
	v_mfma_f32_16x16x32_bf16 v[78:81], v[170:173], v[212:215], v[78:81]
	v_mfma_f32_16x16x32_bf16 v[74:77], v[196:199], v[212:215], v[74:77]
	v_mfma_f32_16x16x32_bf16 v[70:73], v[170:173], v[220:223], v[70:73]
	v_mfma_f32_16x16x32_bf16 v[66:69], v[196:199], v[220:223], v[66:69]
	v_mfma_f32_16x16x32_bf16 v[62:65], v[170:173], v[228:231], v[62:65]
	v_mfma_f32_16x16x32_bf16 v[58:61], v[196:199], v[228:231], v[58:61]
	s_barrier
; #define PG8_STAGE(bufoff, gbase, voff) do { _Pragma("unroll") for (int _i = 0; _i < 2; ++_i) \
;         __builtin_amdgcn_global_load_lds((const unsigned*)((const char*)(gbase) + (voff)[_i]), (PG8_LAS unsigned*)(lds + (bufoff) + ldsw + _i * 8192), 16, 0, 0); } while (0)
; #define PG8_LDA(dst, b, h) do { _Pragma("unroll") for (int m = 0; m < 4; ++m) _Pragma("unroll") for (int k = 0; k < 2; ++k) dst[m][k] = *(const PG8_LAS bf16x8*)(lds + PG8_SA(b, h) + aoff + m * 2048 + k * 1024); } while (0)
; #define PG8_MMA(ai, bj, At, Bt) do { __builtin_amdgcn_s_setprio(1); _Pragma("unroll") for (int m = 0; m < 4; ++m) _Pragma("unroll") for (int n = 0; n < 2; ++n) _Pragma("unroll") for (int k = 0; k < 2; ++k) \
;         acc[ai][bj][m][n] = __builtin_amdgcn_mfma_f32_16x16x32_bf16(Bt[n][k], At[m][k], acc[ai][bj][m][n], 0, 0, 0); __builtin_amdgcn_s_setprio(0); } while (0)
; #define PG8_WAIT_V(n) asm volatile("s_waitcnt vmcnt(" #n ")" ::: "memory")
; #define PG8_WAIT_L(n) asm volatile("s_waitcnt lgkmcnt(" #n ")" ::: "memory")
; #define PG8_BAR __builtin_amdgcn_s_barrier()
; #define PG8_SCHED __builtin_amdgcn_sched_barrier(0)
; template <class Epi, class Sched, bool ALIGN_EPI = false, bool SP2 = false>
; __device__ __forceinline__ void gemm_phase(PG8_LAS unsigned char* lds, const Gemm g, const Sched& S, const Epi& E) {
;     ...
;             PG8_LDA(At, 1, 1); PG8_STAGE(PG8_SB(1, 0), b3, voffB); PG8_STAGE(PG8_SB(1, 1), b3 + hstepB, voffB); PG8_STAGE(PG8_SA(1, 0), a3, voffA);
;             PG8_WAIT_V(8); PG8_WAIT_L(0); PG8_BAR; PG8_MMA(1, 0, At, B0); PG8_MMA(1, 1, At, B1); PG8_BAR; PG8_SCHED;
;     ...
;         if constexpr (ALIGN_EPI) { if (wr == 0) PG8_BAR; }
	s_add_i32 s14, s53, s31
	v_lshl_add_u64 v[232:233], v[232:233], 0, s[18:19]
	s_mov_b32 m0, s14
	ds_read_b128 v[200:203], v182 offset:49152
	ds_read_b128 v[204:207], v182 offset:50176
	ds_read_b128 v[208:211], v182 offset:51200
	ds_read_b128 v[212:215], v182 offset:52224
	ds_read_b128 v[216:219], v182 offset:53248
	ds_read_b128 v[220:223], v182 offset:54272
	ds_read_b128 v[224:227], v182 offset:55296
	ds_read_b128 v[228:231], v182 offset:56320
	global_load_lds_dwordx4 v[232:233], off
	s_add_i32 m0, s14, 0x2000
	s_add_u32 s12, s12, 0x20080
	v_lshl_add_u64 v[232:233], v[234:235], 0, s[18:19]
	s_addc_u32 s13, s13, 0
	s_add_i32 s14, s54, s31
	global_load_lds_dwordx4 v[232:233], off
	v_lshl_add_u64 v[232:233], s[12:13], 0, v[144:145]
	s_mov_b32 m0, s14
	s_nop 0
	global_load_lds_dwordx4 v[232:233], off
	v_lshl_add_u64 v[232:233], s[12:13], 0, v[148:149]
	s_add_i32 m0, s14, 0x2000
	s_nop 0
	global_load_lds_dwordx4 v[232:233], off
	v_lshl_add_u64 v[232:233], v[236:237], 0, s[18:19]
	s_mov_b32 m0, s42
	s_nop 0
	global_load_lds_dwordx4 v[232:233], off
	v_lshl_add_u64 v[232:233], v[238:239], 0, s[18:19]
	s_mov_b32 m0, s43
	s_nop 0
	global_load_lds_dwordx4 v[232:233], off
	s_waitcnt vmcnt(8)
	s_waitcnt lgkmcnt(0)
	s_barrier
	s_waitcnt lgkmcnt(0)
	v_mfma_f32_16x16x32_bf16 v[102:105], v[130:133], v[200:203], v[102:105]
	v_mfma_f32_16x16x32_bf16 v[98:101], v[138:141], v[200:203], v[98:101]
	v_mfma_f32_16x16x32_bf16 v[94:97], v[130:133], v[208:211], v[94:97]
	v_mfma_f32_16x16x32_bf16 v[90:93], v[138:141], v[208:211], v[90:93]
	v_mfma_f32_16x16x32_bf16 v[86:89], v[130:133], v[216:219], v[86:89]
	v_mfma_f32_16x16x32_bf16 v[82:85], v[138:141], v[216:219], v[82:85]
	v_mfma_f32_16x16x32_bf16 v[14:17], v[130:133], v[224:227], v[14:17]
	v_mfma_f32_16x16x32_bf16 v[10:13], v[138:141], v[224:227], v[10:13]
	v_mfma_f32_16x16x32_bf16 v[102:105], v[134:137], v[204:207], v[102:105]
	v_mfma_f32_16x16x32_bf16 v[98:101], v[162:165], v[204:207], v[98:101]
	v_mfma_f32_16x16x32_bf16 v[94:97], v[134:137], v[212:215], v[94:97]
	v_mfma_f32_16x16x32_bf16 v[90:93], v[162:165], v[212:215], v[90:93]
	v_mfma_f32_16x16x32_bf16 v[86:89], v[134:137], v[220:223], v[86:89]
	v_mfma_f32_16x16x32_bf16 v[82:85], v[162:165], v[220:223], v[82:85]
	v_mfma_f32_16x16x32_bf16 v[14:17], v[134:137], v[228:231], v[14:17]
	v_mfma_f32_16x16x32_bf16 v[10:13], v[162:165], v[228:231], v[10:13]
	v_mfma_f32_16x16x32_bf16 v[54:57], v[166:169], v[200:203], v[54:57]
	v_mfma_f32_16x16x32_bf16 v[50:53], v[174:177], v[200:203], v[50:53]
	v_mfma_f32_16x16x32_bf16 v[46:49], v[166:169], v[208:211], v[46:49]
	v_mfma_f32_16x16x32_bf16 v[42:45], v[174:177], v[208:211], v[42:45]
	v_mfma_f32_16x16x32_bf16 v[30:33], v[166:169], v[216:219], v[30:33]
	v_mfma_f32_16x16x32_bf16 v[18:21], v[174:177], v[216:219], v[18:21]
	v_mfma_f32_16x16x32_bf16 v[6:9], v[166:169], v[224:227], v[6:9]
	v_mfma_f32_16x16x32_bf16 v[2:5], v[174:177], v[224:227], v[2:5]
	v_mfma_f32_16x16x32_bf16 v[54:57], v[170:173], v[204:207], v[54:57]
	v_mfma_f32_16x16x32_bf16 v[50:53], v[196:199], v[204:207], v[50:53]
	v_mfma_f32_16x16x32_bf16 v[46:49], v[170:173], v[212:215], v[46:49]
	v_mfma_f32_16x16x32_bf16 v[42:45], v[196:199], v[212:215], v[42:45]
	v_mfma_f32_16x16x32_bf16 v[30:33], v[170:173], v[220:223], v[30:33]
	v_mfma_f32_16x16x32_bf16 v[18:21], v[196:199], v[220:223], v[18:21]
	v_mfma_f32_16x16x32_bf16 v[6:9], v[170:173], v[228:231], v[6:9]
	v_mfma_f32_16x16x32_bf16 v[2:5], v[196:199], v[228:231], v[2:5]
	s_barrier
	s_add_i32 s52, s52, 2
	s_add_u32 s50, s50, 0x100
	s_addc_u32 s51, s51, 0
	s_add_u32 s10, s10, 0x100
	s_addc_u32 s11, s11, 0
	s_cmp_gt_u32 s52, 5
	s_cbranch_scc0 .LBB0_674
	s_setprio 0
	s_and_b64 vcc, exec, s[20:21]
	s_cbranch_vccz .LBB0_677
	s_barrier

; #define PG8_STAGE(bufoff, gbase, voff) do { _Pragma("unroll") for (int _i = 0; _i < 2; ++_i) \
;         __builtin_amdgcn_global_load_lds((const unsigned*)((const char*)(gbase) + (voff)[_i]), (PG8_LAS unsigned*)(lds + (bufoff) + ldsw + _i * 8192), 16, 0, 0); } while (0)
; #define PG8_LDA(dst, b, h) do { _Pragma("unroll") for (int m = 0; m < 4; ++m) _Pragma("unroll") for (int k = 0; k < 2; ++k) dst[m][k] = *(const PG8_LAS bf16x8*)(lds + PG8_SA(b, h) + aoff + m * 2048 + k * 1024); } while (0)
; #define PG8_LDB(dst, b, h) do { _Pragma("unroll") for (int n = 0; n < 2; ++n) _Pragma("unroll") for (int k = 0; k < 2; ++k) dst[n][k] = *(const PG8_LAS bf16x8*)(lds + PG8_SB(b, h) + boff + n * 2048 + k * 1024); } while (0)
; #define PG8_MMA(ai, bj, At, Bt) do { __builtin_amdgcn_s_setprio(1); _Pragma("unroll") for (int m = 0; m < 4; ++m) _Pragma("unroll") for (int n = 0; n < 2; ++n) _Pragma("unroll") for (int k = 0; k < 2; ++k) \
;         acc[ai][bj][m][n] = __builtin_amdgcn_mfma_f32_16x16x32_bf16(Bt[n][k], At[m][k], acc[ai][bj][m][n], 0, 0, 0); __builtin_amdgcn_s_setprio(0); } while (0)
; #define PG8_WAIT_V(n) asm volatile("s_waitcnt vmcnt(" #n ")" ::: "memory")
; #define PG8_BAR __builtin_amdgcn_s_barrier()
; template <class Epi, class Sched, bool ALIGN_EPI = false, bool SP2 = false>
; __device__ __forceinline__ void gemm_phase(PG8_LAS unsigned char* lds, const Gemm g, const Sched& S, const Epi& E) {
;     ...
;         for (int t = 0; t < nt; t += 2) {
;             const bool last = (t == nt - 2);
;             const char* a1 = cA + (size_t)(t + 1) * kstep;
;             const char* a2 = last ? nA : cA + (size_t)(t + 2) * kstep; const char* b2 = last ? nB : cB + (size_t)(t + 2) * kstep;
;             const char* a3 = a2 + kstep; const char* b3 = b2 + kstep;
;             if (last && has_next) S.a_ready(nxt);
;             if constexpr (SP2) {
;             PG8_LDB(B0, 0, 0); PG8_LDB(B1, 0, 1); PG8_SCHED; PG8_LDA(At, 0, 0); PG8_STAGE(PG8_SA(1, 1), a1 + hstepA, voffA);
;             PG8_WAIT_V(8); PG8_WAIT_L(0); PG8_BAR; PG8_MMA(0, 0, At, B0); PG8_MMA(0, 1, At, B1); PG8_BAR; PG8_SCHED;
;     ...
; #pragma unroll
;         for (int a = 0; a < 2; ++a)
; #pragma unroll
;             for (int b = 0; b < 2; ++b)
; #pragma unroll
;                 for (int m = 0; m < 4; ++m)
; #pragma unroll
;                     for (int n = 0; n < 2; ++n) acc[a][b][m][n] = (f32x4){0.f, 0.f, 0.f, 0.f};
.LBB0_697:
	s_ashr_i32 s23, s22, 31
	s_lshl_b64 s[16:17], s[22:23], 18
	s_add_u32 s24, s35, s16
	s_addc_u32 s25, s36, s17
	s_and_b64 s[16:17], s[6:7], exec
	s_cselect_b32 s23, s25, s15
	s_cselect_b32 s46, s24, s14
	s_ashr_i32 s21, s20, 31
	s_lshl_b64 s[16:17], s[20:21], 18
	s_add_u32 s26, s37, s16
	s_addc_u32 s27, s38, s17
	s_and_b64 s[16:17], s[6:7], exec
	s_cselect_b32 s21, s27, s13
	s_cselect_b32 s47, s26, s12
	s_add_u32 s48, s12, 0x100
	s_addc_u32 s49, s13, 0
	s_add_u32 s12, s14, 0x20080
	v_mov_b32_e32 v2, 0
	s_addc_u32 s13, s15, 0
	s_mov_b32 s50, -2
	v_mov_b32_e32 v3, v2
	v_mov_b32_e32 v4, v2
	v_mov_b32_e32 v5, v2
	v_mov_b32_e32 v6, v2
	v_mov_b32_e32 v7, v2
	v_mov_b32_e32 v8, v2
	v_mov_b32_e32 v9, v2
	v_mov_b32_e32 v26, v2
	v_mov_b32_e32 v27, v2
	v_mov_b32_e32 v28, v2
	v_mov_b32_e32 v29, v2
	v_mov_b32_e32 v34, v2
	v_mov_b32_e32 v35, v2
	v_mov_b32_e32 v36, v2
	v_mov_b32_e32 v37, v2
	v_mov_b32_e32 v42, v2
	v_mov_b32_e32 v43, v2
	v_mov_b32_e32 v44, v2
	v_mov_b32_e32 v45, v2
	v_mov_b32_e32 v46, v2
	v_mov_b32_e32 v47, v2
	v_mov_b32_e32 v48, v2
	v_mov_b32_e32 v49, v2
	v_mov_b32_e32 v50, v2
	v_mov_b32_e32 v51, v2
	v_mov_b32_e32 v52, v2
	v_mov_b32_e32 v53, v2
	v_mov_b32_e32 v54, v2
	v_mov_b32_e32 v55, v2
	v_mov_b32_e32 v56, v2
	v_mov_b32_e32 v57, v2
	v_mov_b32_e32 v10, v2
	v_mov_b32_e32 v11, v2
	v_mov_b32_e32 v12, v2
	v_mov_b32_e32 v13, v2
	v_mov_b32_e32 v18, v2
	v_mov_b32_e32 v19, v2
	v_mov_b32_e32 v20, v2
	v_mov_b32_e32 v21, v2
	v_mov_b32_e32 v82, v2
	v_mov_b32_e32 v83, v2
	v_mov_b32_e32 v84, v2
	v_mov_b32_e32 v85, v2
	v_mov_b32_e32 v86, v2
	v_mov_b32_e32 v87, v2
	v_mov_b32_e32 v88, v2
	v_mov_b32_e32 v89, v2
	v_mov_b32_e32 v90, v2
	v_mov_b32_e32 v91, v2
	v_mov_b32_e32 v92, v2
	v_mov_b32_e32 v93, v2
	v_mov_b32_e32 v94, v2
	v_mov_b32_e32 v95, v2
	v_mov_b32_e32 v96, v2
	v_mov_b32_e32 v97, v2
	v_mov_b32_e32 v98, v2
	v_mov_b32_e32 v99, v2
	v_mov_b32_e32 v100, v2
	v_mov_b32_e32 v101, v2
	v_mov_b32_e32 v102, v2
	v_mov_b32_e32 v103, v2
	v_mov_b32_e32 v104, v2
	v_mov_b32_e32 v105, v2
	v_mov_b32_e32 v58, v2
	v_mov_b32_e32 v59, v2
	v_mov_b32_e32 v60, v2
	v_mov_b32_e32 v61, v2
	v_mov_b32_e32 v62, v2
	v_mov_b32_e32 v63, v2
	v_mov_b32_e32 v64, v2
	v_mov_b32_e32 v65, v2
	v_mov_b32_e32 v66, v2
	v_mov_b32_e32 v67, v2
	v_mov_b32_e32 v68, v2
	v_mov_b32_e32 v69, v2
	v_mov_b32_e32 v70, v2
	v_mov_b32_e32 v71, v2
	v_mov_b32_e32 v72, v2
	v_mov_b32_e32 v73, v2
	v_mov_b32_e32 v74, v2
	v_mov_b32_e32 v75, v2
	v_mov_b32_e32 v76, v2
	v_mov_b32_e32 v77, v2
	v_mov_b32_e32 v78, v2
	v_mov_b32_e32 v79, v2
	v_mov_b32_e32 v80, v2
	v_mov_b32_e32 v81, v2
	v_mov_b32_e32 v14, v2
	v_mov_b32_e32 v15, v2
	v_mov_b32_e32 v16, v2
	v_mov_b32_e32 v17, v2
	v_mov_b32_e32 v22, v2
	v_mov_b32_e32 v23, v2
	v_mov_b32_e32 v24, v2
	v_mov_b32_e32 v25, v2
	v_mov_b32_e32 v106, v2
	v_mov_b32_e32 v107, v2
	v_mov_b32_e32 v108, v2
	v_mov_b32_e32 v109, v2
	v_mov_b32_e32 v110, v2
	v_mov_b32_e32 v111, v2
	v_mov_b32_e32 v112, v2
	v_mov_b32_e32 v113, v2
	v_mov_b32_e32 v114, v2
	v_mov_b32_e32 v115, v2
	v_mov_b32_e32 v116, v2
	v_mov_b32_e32 v117, v2
	v_mov_b32_e32 v118, v2
	v_mov_b32_e32 v119, v2
	v_mov_b32_e32 v120, v2
	v_mov_b32_e32 v121, v2
	v_mov_b32_e32 v122, v2
	v_mov_b32_e32 v123, v2
	v_mov_b32_e32 v124, v2
	v_mov_b32_e32 v125, v2
	v_mov_b32_e32 v126, v2
	v_mov_b32_e32 v127, v2
	v_mov_b32_e32 v128, v2
	v_mov_b32_e32 v129, v2
	v_mov_b32_e32 v30, v2
	v_mov_b32_e32 v31, v2
	v_mov_b32_e32 v32, v2
	v_mov_b32_e32 v33, v2
	v_mov_b32_e32 v38, v2
	v_mov_b32_e32 v39, v2
	v_mov_b32_e32 v40, v2
	v_mov_b32_e32 v41, v2
	v_readlane_b32 s98, v250, 4
	s_cmp_lt_u32 s98, 4
	s_cbranch_scc1 .Lgp_3
	s_setprio 1
.Lgp_3:
.LBB0_698:
	ds_read_b128 v[130:133], v197
	ds_read_b128 v[134:137], v197 offset:1024
	ds_read_b128 v[138:141], v197 offset:2048
	ds_read_b128 v[142:145], v197 offset:3072
	ds_read_b128 v[146:149], v198
	ds_read_b128 v[170:173], v198 offset:1024
	ds_read_b128 v[174:177], v198 offset:2048
	ds_read_b128 v[178:181], v198 offset:3072
	s_add_u32 s14, s12, 0xfffe0080
	s_addc_u32 s15, s13, -1
	s_cmp_eq_u32 s50, 4
	s_cselect_b32 s17, s23, s15
	s_cselect_b32 s16, s46, s14
	s_cselect_b32 s15, s21, s49
	s_cselect_b32 s14, s47, s48
	v_lshl_add_u64 v[182:183], s[12:13], 0, v[164:165]
	s_add_i32 m0, s30, 0xc000
	ds_read_b128 v[200:203], v199
	ds_read_b128 v[204:207], v199 offset:1024
	ds_read_b128 v[208:211], v199 offset:2048
	ds_read_b128 v[212:215], v199 offset:3072
	ds_read_b128 v[216:219], v199 offset:4096
	ds_read_b128 v[220:223], v199 offset:5120
	ds_read_b128 v[224:227], v199 offset:6144
	ds_read_b128 v[228:231], v199 offset:7168
	global_load_lds_dwordx4 v[182:183], off
	v_lshl_add_u64 v[182:183], s[12:13], 0, v[162:163]
	s_add_i32 m0, s30, 0xe000
	s_nop 0
	global_load_lds_dwordx4 v[182:183], off
	s_waitcnt vmcnt(8)
	s_waitcnt lgkmcnt(0)
	s_barrier
; #define PG8_STAGE(bufoff, gbase, voff) do { _Pragma("unroll") for (int _i = 0; _i < 2; ++_i) \
;         __builtin_amdgcn_global_load_lds((const unsigned*)((const char*)(gbase) + (voff)[_i]), (PG8_LAS unsigned*)(lds + (bufoff) + ldsw + _i * 8192), 16, 0, 0); } while (0)
; #define PG8_LDA(dst, b, h) do { _Pragma("unroll") for (int m = 0; m < 4; ++m) _Pragma("unroll") for (int k = 0; k < 2; ++k) dst[m][k] = *(const PG8_LAS bf16x8*)(lds + PG8_SA(b, h) + aoff + m * 2048 + k * 1024); } while (0)
; #define PG8_MMA(ai, bj, At, Bt) do { __builtin_amdgcn_s_setprio(1); _Pragma("unroll") for (int m = 0; m < 4; ++m) _Pragma("unroll") for (int n = 0; n < 2; ++n) _Pragma("unroll") for (int k = 0; k < 2; ++k) \
;         acc[ai][bj][m][n] = __builtin_amdgcn_mfma_f32_16x16x32_bf16(Bt[n][k], At[m][k], acc[ai][bj][m][n], 0, 0, 0); __builtin_amdgcn_s_setprio(0); } while (0)
; #define PG8_WAIT_V(n) asm volatile("s_waitcnt vmcnt(" #n ")" ::: "memory")
; #define PG8_WAIT_L(n) asm volatile("s_waitcnt lgkmcnt(" #n ")" ::: "memory")
; #define PG8_BAR __builtin_amdgcn_s_barrier()
; #define PG8_SCHED __builtin_amdgcn_sched_barrier(0)
; template <class Epi, class Sched, bool ALIGN_EPI = false, bool SP2 = false>
; __device__ __forceinline__ void gemm_phase(PG8_LAS unsigned char* lds, const Gemm g, const Sched& S, const Epi& E) {
;     ...
;             PG8_WAIT_V(8); PG8_WAIT_L(0); PG8_BAR; PG8_MMA(0, 0, At, B0); PG8_MMA(0, 1, At, B1); PG8_BAR; PG8_SCHED;
;             PG8_LDA(At, 0, 1); PG8_STAGE(PG8_SB(0, 0), b2, voffB); PG8_STAGE(PG8_SB(0, 1), b2 + hstepB, voffB); PG8_STAGE(PG8_SA(0, 0), a2, voffA);
;             PG8_WAIT_V(8); PG8_WAIT_L(0); PG8_BAR; PG8_MMA(1, 0, At, B0); PG8_MMA(1, 1, At, B1); PG8_BAR; PG8_SCHED;
	s_waitcnt lgkmcnt(0)
	v_mfma_f32_16x16x32_bf16 v[38:41], v[130:133], v[200:203], v[38:41]
	v_mfma_f32_16x16x32_bf16 v[30:33], v[138:141], v[200:203], v[30:33]
	v_mfma_f32_16x16x32_bf16 v[126:129], v[130:133], v[208:211], v[126:129]
	v_mfma_f32_16x16x32_bf16 v[122:125], v[138:141], v[208:211], v[122:125]
	v_mfma_f32_16x16x32_bf16 v[118:121], v[130:133], v[216:219], v[118:121]
	v_mfma_f32_16x16x32_bf16 v[114:117], v[138:141], v[216:219], v[114:117]
	v_mfma_f32_16x16x32_bf16 v[110:113], v[130:133], v[224:227], v[110:113]
	v_mfma_f32_16x16x32_bf16 v[106:109], v[138:141], v[224:227], v[106:109]
	v_mfma_f32_16x16x32_bf16 v[38:41], v[134:137], v[204:207], v[38:41]
	v_mfma_f32_16x16x32_bf16 v[30:33], v[142:145], v[204:207], v[30:33]
	v_mfma_f32_16x16x32_bf16 v[126:129], v[134:137], v[212:215], v[126:129]
	v_mfma_f32_16x16x32_bf16 v[122:125], v[142:145], v[212:215], v[122:125]
	v_mfma_f32_16x16x32_bf16 v[118:121], v[134:137], v[220:223], v[118:121]
	v_mfma_f32_16x16x32_bf16 v[114:117], v[142:145], v[220:223], v[114:117]
	v_mfma_f32_16x16x32_bf16 v[110:113], v[134:137], v[228:231], v[110:113]
	v_mfma_f32_16x16x32_bf16 v[106:109], v[142:145], v[228:231], v[106:109]
	v_mfma_f32_16x16x32_bf16 v[22:25], v[146:149], v[200:203], v[22:25]
	v_mfma_f32_16x16x32_bf16 v[14:17], v[174:177], v[200:203], v[14:17]
	v_mfma_f32_16x16x32_bf16 v[78:81], v[146:149], v[208:211], v[78:81]
	v_mfma_f32_16x16x32_bf16 v[74:77], v[174:177], v[208:211], v[74:77]
	v_mfma_f32_16x16x32_bf16 v[70:73], v[146:149], v[216:219], v[70:73]
	v_mfma_f32_16x16x32_bf16 v[66:69], v[174:177], v[216:219], v[66:69]
	v_mfma_f32_16x16x32_bf16 v[62:65], v[146:149], v[224:227], v[62:65]
	v_mfma_f32_16x16x32_bf16 v[58:61], v[174:177], v[224:227], v[58:61]
	v_mfma_f32_16x16x32_bf16 v[22:25], v[170:173], v[204:207], v[22:25]
	v_mfma_f32_16x16x32_bf16 v[14:17], v[178:181], v[204:207], v[14:17]
	v_mfma_f32_16x16x32_bf16 v[78:81], v[170:173], v[212:215], v[78:81]
	v_mfma_f32_16x16x32_bf16 v[74:77], v[178:181], v[212:215], v[74:77]
	v_mfma_f32_16x16x32_bf16 v[70:73], v[170:173], v[220:223], v[70:73]
	v_mfma_f32_16x16x32_bf16 v[66:69], v[178:181], v[220:223], v[66:69]
	v_mfma_f32_16x16x32_bf16 v[62:65], v[170:173], v[228:231], v[62:65]
	v_mfma_f32_16x16x32_bf16 v[58:61], v[178:181], v[228:231], v[58:61]
	s_barrier
	s_add_i32 s51, s44, s29
	v_lshl_add_u64 v[182:183], s[14:15], 0, v[156:157]
	s_mov_b32 m0, s51
	ds_read_b128 v[200:203], v199 offset:16384
	ds_read_b128 v[204:207], v199 offset:17408
	ds_read_b128 v[208:211], v199 offset:18432
	ds_read_b128 v[212:215], v199 offset:19456
	ds_read_b128 v[216:219], v199 offset:20480
	ds_read_b128 v[220:223], v199 offset:21504
	ds_read_b128 v[224:227], v199 offset:22528
	ds_read_b128 v[228:231], v199 offset:23552
	global_load_lds_dwordx4 v[182:183], off
	s_add_i32 m0, s51, 0x2000
	s_add_u32 s52, s14, 0x20000
	v_lshl_add_u64 v[232:233], s[14:15], 0, v[160:161]
	s_addc_u32 s53, s15, 0
	s_add_i32 s51, s45, s29
	global_load_lds_dwordx4 v[232:233], off
	v_lshl_add_u64 v[234:235], s[52:53], 0, v[156:157]
	s_mov_b32 m0, s51
	v_lshl_add_u64 v[236:237], s[16:17], 0, v[158:159]
	global_load_lds_dwordx4 v[234:235], off
	v_lshl_add_u64 v[234:235], s[52:53], 0, v[160:161]
	s_add_i32 m0, s51, 0x2000
	s_nop 0
	global_load_lds_dwordx4 v[234:235], off
	v_lshl_add_u64 v[234:235], s[16:17], 0, v[154:155]
	s_mov_b32 m0, s30
	s_nop 0
	global_load_lds_dwordx4 v[234:235], off
	s_mov_b32 m0, s31
	s_nop 0
	global_load_lds_dwordx4 v[236:237], off
	s_waitcnt vmcnt(8)
	s_waitcnt lgkmcnt(0)
	s_barrier
	s_waitcnt lgkmcnt(0)
	v_mfma_f32_16x16x32_bf16 v[102:105], v[130:133], v[200:203], v[102:105]
	v_mfma_f32_16x16x32_bf16 v[98:101], v[138:141], v[200:203], v[98:101]
	v_mfma_f32_16x16x32_bf16 v[94:97], v[130:133], v[208:211], v[94:97]
	v_mfma_f32_16x16x32_bf16 v[90:93], v[138:141], v[208:211], v[90:93]
	v_mfma_f32_16x16x32_bf16 v[86:89], v[130:133], v[216:219], v[86:89]
	v_mfma_f32_16x16x32_bf16 v[82:85], v[138:141], v[216:219], v[82:85]
	v_mfma_f32_16x16x32_bf16 v[18:21], v[130:133], v[224:227], v[18:21]
	v_mfma_f32_16x16x32_bf16 v[10:13], v[138:141], v[224:227], v[10:13]
	v_mfma_f32_16x16x32_bf16 v[102:105], v[134:137], v[204:207], v[102:105]
	v_mfma_f32_16x16x32_bf16 v[98:101], v[142:145], v[204:207], v[98:101]
	v_mfma_f32_16x16x32_bf16 v[94:97], v[134:137], v[212:215], v[94:97]
	v_mfma_f32_16x16x32_bf16 v[90:93], v[142:145], v[212:215], v[90:93]
	v_mfma_f32_16x16x32_bf16 v[86:89], v[134:137], v[220:223], v[86:89]
	v_mfma_f32_16x16x32_bf16 v[82:85], v[142:145], v[220:223], v[82:85]
	v_mfma_f32_16x16x32_bf16 v[18:21], v[134:137], v[228:231], v[18:21]
	v_mfma_f32_16x16x32_bf16 v[10:13], v[142:145], v[228:231], v[10:13]
	v_mfma_f32_16x16x32_bf16 v[54:57], v[146:149], v[200:203], v[54:57]
	v_mfma_f32_16x16x32_bf16 v[50:53], v[174:177], v[200:203], v[50:53]
	v_mfma_f32_16x16x32_bf16 v[46:49], v[146:149], v[208:211], v[46:49]
	v_mfma_f32_16x16x32_bf16 v[42:45], v[174:177], v[208:211], v[42:45]
	v_mfma_f32_16x16x32_bf16 v[34:37], v[146:149], v[216:219], v[34:37]
	v_mfma_f32_16x16x32_bf16 v[26:29], v[174:177], v[216:219], v[26:29]
	v_mfma_f32_16x16x32_bf16 v[6:9], v[146:149], v[224:227], v[6:9]
	v_mfma_f32_16x16x32_bf16 v[2:5], v[174:177], v[224:227], v[2:5]
	v_mfma_f32_16x16x32_bf16 v[54:57], v[170:173], v[204:207], v[54:57]
	v_mfma_f32_16x16x32_bf16 v[50:53], v[178:181], v[204:207], v[50:53]
	v_mfma_f32_16x16x32_bf16 v[46:49], v[170:173], v[212:215], v[46:49]
	v_mfma_f32_16x16x32_bf16 v[42:45], v[178:181], v[212:215], v[42:45]
	v_mfma_f32_16x16x32_bf16 v[34:37], v[170:173], v[220:223], v[34:37]
	v_mfma_f32_16x16x32_bf16 v[26:29], v[178:181], v[220:223], v[26:29]
	v_mfma_f32_16x16x32_bf16 v[6:9], v[170:173], v[228:231], v[6:9]
	v_mfma_f32_16x16x32_bf16 v[2:5], v[178:181], v[228:231], v[2:5]
	s_barrier
; #define PG8_STAGE(bufoff, gbase, voff) do { _Pragma("unroll") for (int _i = 0; _i < 2; ++_i) \
;         __builtin_amdgcn_global_load_lds((const unsigned*)((const char*)(gbase) + (voff)[_i]), (PG8_LAS unsigned*)(lds + (bufoff) + ldsw + _i * 8192), 16, 0, 0); } while (0)
; #define PG8_LDA(dst, b, h) do { _Pragma("unroll") for (int m = 0; m < 4; ++m) _Pragma("unroll") for (int k = 0; k < 2; ++k) dst[m][k] = *(const PG8_LAS bf16x8*)(lds + PG8_SA(b, h) + aoff + m * 2048 + k * 1024); } while (0)
; #define PG8_LDB(dst, b, h) do { _Pragma("unroll") for (int n = 0; n < 2; ++n) _Pragma("unroll") for (int k = 0; k < 2; ++k) dst[n][k] = *(const PG8_LAS bf16x8*)(lds + PG8_SB(b, h) + boff + n * 2048 + k * 1024); } while (0)
; #define PG8_MMA(ai, bj, At, Bt) do { __builtin_amdgcn_s_setprio(1); _Pragma("unroll") for (int m = 0; m < 4; ++m) _Pragma("unroll") for (int n = 0; n < 2; ++n) _Pragma("unroll") for (int k = 0; k < 2; ++k) \
;         acc[ai][bj][m][n] = __builtin_amdgcn_mfma_f32_16x16x32_bf16(Bt[n][k], At[m][k], acc[ai][bj][m][n], 0, 0, 0); __builtin_amdgcn_s_setprio(0); } while (0)
; #define PG8_WAIT_V(n) asm volatile("s_waitcnt vmcnt(" #n ")" ::: "memory")
; #define PG8_WAIT_L(n) asm volatile("s_waitcnt lgkmcnt(" #n ")" ::: "memory")
; #define PG8_BAR __builtin_amdgcn_s_barrier()
; #define PG8_SCHED __builtin_amdgcn_sched_barrier(0)
; template <class Epi, class Sched, bool ALIGN_EPI = false, bool SP2 = false>
; __device__ __forceinline__ void gemm_phase(PG8_LAS unsigned char* lds, const Gemm g, const Sched& S, const Epi& E) {
;     ...
;             PG8_LDB(B0, 1, 0); PG8_LDB(B1, 1, 1); PG8_SCHED; PG8_LDA(At, 1, 0); PG8_STAGE(PG8_SA(0, 1), a2 + hstepA, voffA);
;             PG8_WAIT_V(8); PG8_WAIT_L(0); PG8_BAR; PG8_MMA(0, 0, At, B0); PG8_MMA(0, 1, At, B1); PG8_BAR; PG8_SCHED;
	s_add_i32 s51, 0, 0x18000
	s_add_i32 s52, 0, 0x1c000
	v_add_u32_e32 v142, s51, v195
	v_add_u32_e32 v178, s52, v195
	ds_read_b128 v[130:133], v142
	ds_read_b128 v[134:137], v142 offset:1024
	ds_read_b128 v[138:141], v142 offset:2048
	ds_read_b128 v[142:145], v142 offset:3072
	ds_read_b128 v[146:149], v178
	ds_read_b128 v[170:173], v178 offset:1024
	ds_read_b128 v[174:177], v178 offset:2048
	ds_read_b128 v[178:181], v178 offset:3072
	s_add_u32 s16, s16, 0x20000
	s_addc_u32 s17, s17, 0
	s_mov_b32 m0, s33
	v_lshl_add_u64 v[238:239], s[16:17], 0, v[154:155]
	ds_read_b128 v[200:203], v199 offset:32768
	ds_read_b128 v[204:207], v199 offset:33792
	ds_read_b128 v[208:211], v199 offset:34816
	ds_read_b128 v[212:215], v199 offset:35840
	ds_read_b128 v[216:219], v199 offset:36864
	ds_read_b128 v[220:223], v199 offset:37888
	ds_read_b128 v[224:227], v199 offset:38912
	ds_read_b128 v[228:231], v199 offset:39936
	global_load_lds_dwordx4 v[238:239], off
	v_lshl_add_u64 v[238:239], s[16:17], 0, v[158:159]
	s_mov_b32 m0, s34
	s_nop 0
	global_load_lds_dwordx4 v[238:239], off
	s_waitcnt vmcnt(8)
	s_waitcnt lgkmcnt(0)
	s_barrier
	s_waitcnt lgkmcnt(0)
	v_mfma_f32_16x16x32_bf16 v[38:41], v[130:133], v[200:203], v[38:41]
	v_mfma_f32_16x16x32_bf16 v[30:33], v[138:141], v[200:203], v[30:33]
	v_mfma_f32_16x16x32_bf16 v[126:129], v[130:133], v[208:211], v[126:129]
	v_mfma_f32_16x16x32_bf16 v[122:125], v[138:141], v[208:211], v[122:125]
	v_mfma_f32_16x16x32_bf16 v[118:121], v[130:133], v[216:219], v[118:121]
	v_mfma_f32_16x16x32_bf16 v[114:117], v[138:141], v[216:219], v[114:117]
	v_mfma_f32_16x16x32_bf16 v[110:113], v[130:133], v[224:227], v[110:113]
	v_mfma_f32_16x16x32_bf16 v[106:109], v[138:141], v[224:227], v[106:109]
	v_mfma_f32_16x16x32_bf16 v[38:41], v[134:137], v[204:207], v[38:41]
	v_mfma_f32_16x16x32_bf16 v[30:33], v[142:145], v[204:207], v[30:33]
	v_mfma_f32_16x16x32_bf16 v[126:129], v[134:137], v[212:215], v[126:129]
	v_mfma_f32_16x16x32_bf16 v[122:125], v[142:145], v[212:215], v[122:125]
	v_mfma_f32_16x16x32_bf16 v[118:121], v[134:137], v[220:223], v[118:121]
	v_mfma_f32_16x16x32_bf16 v[114:117], v[142:145], v[220:223], v[114:117]
	v_mfma_f32_16x16x32_bf16 v[110:113], v[134:137], v[228:231], v[110:113]
	v_mfma_f32_16x16x32_bf16 v[106:109], v[142:145], v[228:231], v[106:109]
	v_mfma_f32_16x16x32_bf16 v[22:25], v[146:149], v[200:203], v[22:25]
	v_mfma_f32_16x16x32_bf16 v[14:17], v[174:177], v[200:203], v[14:17]
	v_mfma_f32_16x16x32_bf16 v[78:81], v[146:149], v[208:211], v[78:81]
	v_mfma_f32_16x16x32_bf16 v[74:77], v[174:177], v[208:211], v[74:77]
	v_mfma_f32_16x16x32_bf16 v[70:73], v[146:149], v[216:219], v[70:73]
	v_mfma_f32_16x16x32_bf16 v[66:69], v[174:177], v[216:219], v[66:69]
	v_mfma_f32_16x16x32_bf16 v[62:65], v[146:149], v[224:227], v[62:65]
	v_mfma_f32_16x16x32_bf16 v[58:61], v[174:177], v[224:227], v[58:61]
	v_mfma_f32_16x16x32_bf16 v[22:25], v[170:173], v[204:207], v[22:25]
	v_mfma_f32_16x16x32_bf16 v[14:17], v[178:181], v[204:207], v[14:17]
	v_mfma_f32_16x16x32_bf16 v[78:81], v[170:173], v[212:215], v[78:81]
	v_mfma_f32_16x16x32_bf16 v[74:77], v[178:181], v[212:215], v[74:77]
	v_mfma_f32_16x16x32_bf16 v[70:73], v[170:173], v[220:223], v[70:73]
	v_mfma_f32_16x16x32_bf16 v[66:69], v[178:181], v[220:223], v[66:69]
	v_mfma_f32_16x16x32_bf16 v[62:65], v[170:173], v[228:231], v[62:65]
	v_mfma_f32_16x16x32_bf16 v[58:61], v[178:181], v[228:231], v[58:61]
	s_barrier
; #define PG8_STAGE(bufoff, gbase, voff) do { _Pragma("unroll") for (int _i = 0; _i < 2; ++_i) \
;         __builtin_amdgcn_global_load_lds((const unsigned*)((const char*)(gbase) + (voff)[_i]), (PG8_LAS unsigned*)(lds + (bufoff) + ldsw + _i * 8192), 16, 0, 0); } while (0)
; #define PG8_LDA(dst, b, h) do { _Pragma("unroll") for (int m = 0; m < 4; ++m) _Pragma("unroll") for (int k = 0; k < 2; ++k) dst[m][k] = *(const PG8_LAS bf16x8*)(lds + PG8_SA(b, h) + aoff + m * 2048 + k * 1024); } while (0)
; #define PG8_MMA(ai, bj, At, Bt) do { __builtin_amdgcn_s_setprio(1); _Pragma("unroll") for (int m = 0; m < 4; ++m) _Pragma("unroll") for (int n = 0; n < 2; ++n) _Pragma("unroll") for (int k = 0; k < 2; ++k) \
;         acc[ai][bj][m][n] = __builtin_amdgcn_mfma_f32_16x16x32_bf16(Bt[n][k], At[m][k], acc[ai][bj][m][n], 0, 0, 0); __builtin_amdgcn_s_setprio(0); } while (0)
; #define PG8_WAIT_V(n) asm volatile("s_waitcnt vmcnt(" #n ")" ::: "memory")
; #define PG8_WAIT_L(n) asm volatile("s_waitcnt lgkmcnt(" #n ")" ::: "memory")
; #define PG8_BAR __builtin_amdgcn_s_barrier()
; #define PG8_SCHED __builtin_amdgcn_sched_barrier(0)
; template <class Epi, class Sched, bool ALIGN_EPI = false, bool SP2 = false>
; __device__ __forceinline__ void gemm_phase(PG8_LAS unsigned char* lds, const Gemm g, const Sched& S, const Epi& E) {
;     ...
;             PG8_LDA(At, 1, 1); PG8_STAGE(PG8_SB(1, 0), b3, voffB); PG8_STAGE(PG8_SB(1, 1), b3 + hstepB, voffB); PG8_STAGE(PG8_SA(1, 0), a3, voffA);
;             PG8_WAIT_V(8); PG8_WAIT_L(0); PG8_BAR; PG8_MMA(1, 0, At, B0); PG8_MMA(1, 1, At, B1); PG8_BAR; PG8_SCHED;
;     ...
;         if constexpr (ALIGN_EPI) { if (wr == 0) PG8_BAR; }
	s_add_i32 s16, s51, s29
	v_lshl_add_u64 v[182:183], v[182:183], 0, s[8:9]
	s_mov_b32 m0, s16
	ds_read_b128 v[200:203], v199 offset:49152
	ds_read_b128 v[204:207], v199 offset:50176
	ds_read_b128 v[208:211], v199 offset:51200
	ds_read_b128 v[212:215], v199 offset:52224
	ds_read_b128 v[216:219], v199 offset:53248
	ds_read_b128 v[220:223], v199 offset:54272
	ds_read_b128 v[224:227], v199 offset:55296
	ds_read_b128 v[228:231], v199 offset:56320
	global_load_lds_dwordx4 v[182:183], off
	s_add_i32 m0, s16, 0x2000
	s_add_u32 s14, s14, 0x20080
	v_lshl_add_u64 v[182:183], v[232:233], 0, s[8:9]
	s_addc_u32 s15, s15, 0
	s_add_i32 s16, s52, s29
	global_load_lds_dwordx4 v[182:183], off
	v_lshl_add_u64 v[182:183], s[14:15], 0, v[156:157]
	s_mov_b32 m0, s16
	s_nop 0
	global_load_lds_dwordx4 v[182:183], off
	v_lshl_add_u64 v[182:183], s[14:15], 0, v[160:161]
	s_add_i32 m0, s16, 0x2000
	s_nop 0
	global_load_lds_dwordx4 v[182:183], off
	v_lshl_add_u64 v[182:183], v[234:235], 0, s[8:9]
	s_mov_b32 m0, s40
	s_nop 0
	global_load_lds_dwordx4 v[182:183], off
	v_lshl_add_u64 v[182:183], v[236:237], 0, s[8:9]
	s_mov_b32 m0, s41
	s_nop 0
	global_load_lds_dwordx4 v[182:183], off
	s_waitcnt vmcnt(8)
	s_waitcnt lgkmcnt(0)
	s_barrier
	s_waitcnt lgkmcnt(0)
	v_mfma_f32_16x16x32_bf16 v[102:105], v[130:133], v[200:203], v[102:105]
	v_mfma_f32_16x16x32_bf16 v[98:101], v[138:141], v[200:203], v[98:101]
	v_mfma_f32_16x16x32_bf16 v[94:97], v[130:133], v[208:211], v[94:97]
	v_mfma_f32_16x16x32_bf16 v[90:93], v[138:141], v[208:211], v[90:93]
	v_mfma_f32_16x16x32_bf16 v[86:89], v[130:133], v[216:219], v[86:89]
	v_mfma_f32_16x16x32_bf16 v[82:85], v[138:141], v[216:219], v[82:85]
	v_mfma_f32_16x16x32_bf16 v[18:21], v[130:133], v[224:227], v[18:21]
	v_mfma_f32_16x16x32_bf16 v[10:13], v[138:141], v[224:227], v[10:13]
	v_mfma_f32_16x16x32_bf16 v[102:105], v[134:137], v[204:207], v[102:105]
	v_mfma_f32_16x16x32_bf16 v[98:101], v[142:145], v[204:207], v[98:101]
	v_mfma_f32_16x16x32_bf16 v[94:97], v[134:137], v[212:215], v[94:97]
	v_mfma_f32_16x16x32_bf16 v[90:93], v[142:145], v[212:215], v[90:93]
	v_mfma_f32_16x16x32_bf16 v[86:89], v[134:137], v[220:223], v[86:89]
	v_mfma_f32_16x16x32_bf16 v[82:85], v[142:145], v[220:223], v[82:85]
	v_mfma_f32_16x16x32_bf16 v[18:21], v[134:137], v[228:231], v[18:21]
	v_mfma_f32_16x16x32_bf16 v[10:13], v[142:145], v[228:231], v[10:13]
	v_mfma_f32_16x16x32_bf16 v[54:57], v[146:149], v[200:203], v[54:57]
	v_mfma_f32_16x16x32_bf16 v[50:53], v[174:177], v[200:203], v[50:53]
	v_mfma_f32_16x16x32_bf16 v[46:49], v[146:149], v[208:211], v[46:49]
	v_mfma_f32_16x16x32_bf16 v[42:45], v[174:177], v[208:211], v[42:45]
	v_mfma_f32_16x16x32_bf16 v[34:37], v[146:149], v[216:219], v[34:37]
	v_mfma_f32_16x16x32_bf16 v[26:29], v[174:177], v[216:219], v[26:29]
	v_mfma_f32_16x16x32_bf16 v[6:9], v[146:149], v[224:227], v[6:9]
	v_mfma_f32_16x16x32_bf16 v[2:5], v[174:177], v[224:227], v[2:5]
	v_mfma_f32_16x16x32_bf16 v[54:57], v[170:173], v[204:207], v[54:57]
	v_mfma_f32_16x16x32_bf16 v[50:53], v[178:181], v[204:207], v[50:53]
	v_mfma_f32_16x16x32_bf16 v[46:49], v[170:173], v[212:215], v[46:49]
	v_mfma_f32_16x16x32_bf16 v[42:45], v[178:181], v[212:215], v[42:45]
	v_mfma_f32_16x16x32_bf16 v[34:37], v[170:173], v[220:223], v[34:37]
	v_mfma_f32_16x16x32_bf16 v[26:29], v[178:181], v[220:223], v[26:29]
	v_mfma_f32_16x16x32_bf16 v[6:9], v[170:173], v[228:231], v[6:9]
	v_mfma_f32_16x16x32_bf16 v[2:5], v[178:181], v[228:231], v[2:5]
	s_barrier
	s_add_i32 s50, s50, 2
	s_add_u32 s48, s48, 0x100
	s_addc_u32 s49, s49, 0
	s_add_u32 s12, s12, 0x100
	s_addc_u32 s13, s13, 0
	s_cmp_gt_u32 s50, 5
	s_cbranch_scc0 .LBB0_698
	s_setprio 0
	s_and_b64 vcc, exec, s[18:19]
	s_cbranch_vccz .LBB0_701
	s_barrier

; #define PG8_STAGE(bufoff, gbase, voff) do { _Pragma("unroll") for (int _i = 0; _i < 2; ++_i) \
;         __builtin_amdgcn_global_load_lds((const unsigned*)((const char*)(gbase) + (voff)[_i]), (PG8_LAS unsigned*)(lds + (bufoff) + ldsw + _i * 8192), 16, 0, 0); } while (0)
; #define PG8_LDA(dst, b, h) do { _Pragma("unroll") for (int m = 0; m < 4; ++m) _Pragma("unroll") for (int k = 0; k < 2; ++k) dst[m][k] = *(const PG8_LAS bf16x8*)(lds + PG8_SA(b, h) + aoff + m * 2048 + k * 1024); } while (0)
; #define PG8_LDB(dst, b, h) do { _Pragma("unroll") for (int n = 0; n < 2; ++n) _Pragma("unroll") for (int k = 0; k < 2; ++k) dst[n][k] = *(const PG8_LAS bf16x8*)(lds + PG8_SB(b, h) + boff + n * 2048 + k * 1024); } while (0)
; #define PG8_MMA(ai, bj, At, Bt) do { __builtin_amdgcn_s_setprio(1); _Pragma("unroll") for (int m = 0; m < 4; ++m) _Pragma("unroll") for (int n = 0; n < 2; ++n) _Pragma("unroll") for (int k = 0; k < 2; ++k) \
;         acc[ai][bj][m][n] = __builtin_amdgcn_mfma_f32_16x16x32_bf16(Bt[n][k], At[m][k], acc[ai][bj][m][n], 0, 0, 0); __builtin_amdgcn_s_setprio(0); } while (0)
; #define PG8_WAIT_V(n) asm volatile("s_waitcnt vmcnt(" #n ")" ::: "memory")
; #define PG8_BAR __builtin_amdgcn_s_barrier()
; template <class Epi, class Sched, bool ALIGN_EPI = false, bool SP2 = false>
; __device__ __forceinline__ void gemm_phase(PG8_LAS unsigned char* lds, const Gemm g, const Sched& S, const Epi& E) {
;     ...
;         for (int t = 0; t < nt; t += 2) {
;             const bool last = (t == nt - 2);
;             const char* a1 = cA + (size_t)(t + 1) * kstep;
;             const char* a2 = last ? nA : cA + (size_t)(t + 2) * kstep; const char* b2 = last ? nB : cB + (size_t)(t + 2) * kstep;
;             const char* a3 = a2 + kstep; const char* b3 = b2 + kstep;
;             if (last && has_next) S.a_ready(nxt);
;             if constexpr (SP2) {
;             PG8_LDB(B0, 0, 0); PG8_LDB(B1, 0, 1); PG8_SCHED; PG8_LDA(At, 0, 0); PG8_STAGE(PG8_SA(1, 1), a1 + hstepA, voffA);
;             PG8_WAIT_V(8); PG8_WAIT_L(0); PG8_BAR; PG8_MMA(0, 0, At, B0); PG8_MMA(0, 1, At, B1); PG8_BAR; PG8_SCHED;
;     ...
; #pragma unroll
;         for (int a = 0; a < 2; ++a)
; #pragma unroll
;             for (int b = 0; b < 2; ++b)
; #pragma unroll
;                 for (int m = 0; m < 4; ++m)
; #pragma unroll
;                     for (int n = 0; n < 2; ++n) acc[a][b][m][n] = (f32x4){0.f, 0.f, 0.f, 0.f};
.LBB0_773:
	s_ashr_i32 s21, s20, 31
	s_lshl_b64 s[22:23], s[20:21], 19
	s_add_u32 s22, s38, s22
	s_addc_u32 s23, s39, s23
	s_and_b64 s[24:25], s[6:7], exec
	s_cselect_b32 s21, s23, s29
	s_cselect_b32 s53, s22, s28
	s_ashr_i32 s19, s18, 31
	s_lshl_b64 s[24:25], s[18:19], 19
	s_add_u32 s24, s40, s24
	s_addc_u32 s25, s41, s25
	s_and_b64 s[30:31], s[6:7], exec
	s_cselect_b32 s19, s25, s27
	s_cselect_b32 s54, s24, s26
	s_add_u32 s55, s26, 0x100
	s_addc_u32 s56, s27, 0
	s_add_u32 s26, s28, 0x40080
	v_mov_b32_e32 v2, 0
	s_addc_u32 s27, s29, 0
	s_mov_b32 s57, -2
	v_mov_b32_e32 v3, v2
	v_mov_b32_e32 v4, v2
	v_mov_b32_e32 v5, v2
	v_mov_b32_e32 v6, v2
	v_mov_b32_e32 v7, v2
	v_mov_b32_e32 v8, v2
	v_mov_b32_e32 v9, v2
	v_mov_b32_e32 v10, v2
	v_mov_b32_e32 v11, v2
	v_mov_b32_e32 v12, v2
	v_mov_b32_e32 v13, v2
	v_mov_b32_e32 v14, v2
	v_mov_b32_e32 v15, v2
	v_mov_b32_e32 v16, v2
	v_mov_b32_e32 v17, v2
	v_mov_b32_e32 v18, v2
	v_mov_b32_e32 v19, v2
	v_mov_b32_e32 v20, v2
	v_mov_b32_e32 v21, v2
	v_mov_b32_e32 v22, v2
	v_mov_b32_e32 v23, v2
	v_mov_b32_e32 v24, v2
	v_mov_b32_e32 v25, v2
	v_mov_b32_e32 v26, v2
	v_mov_b32_e32 v27, v2
	v_mov_b32_e32 v28, v2
	v_mov_b32_e32 v29, v2
	v_mov_b32_e32 v30, v2
	v_mov_b32_e32 v31, v2
	v_mov_b32_e32 v32, v2
	v_mov_b32_e32 v33, v2
	v_mov_b32_e32 v42, v2
	v_mov_b32_e32 v43, v2
	v_mov_b32_e32 v44, v2
	v_mov_b32_e32 v45, v2
	v_mov_b32_e32 v46, v2
	v_mov_b32_e32 v47, v2
	v_mov_b32_e32 v48, v2
	v_mov_b32_e32 v49, v2
	v_mov_b32_e32 v58, v2
	v_mov_b32_e32 v59, v2
	v_mov_b32_e32 v60, v2
	v_mov_b32_e32 v61, v2
	v_mov_b32_e32 v66, v2
	v_mov_b32_e32 v67, v2
	v_mov_b32_e32 v68, v2
	v_mov_b32_e32 v69, v2
	v_mov_b32_e32 v78, v2
	v_mov_b32_e32 v79, v2
	v_mov_b32_e32 v80, v2
	v_mov_b32_e32 v81, v2
	v_mov_b32_e32 v86, v2
	v_mov_b32_e32 v87, v2
	v_mov_b32_e32 v88, v2
	v_mov_b32_e32 v89, v2
	v_mov_b32_e32 v90, v2
	v_mov_b32_e32 v91, v2
	v_mov_b32_e32 v92, v2
	v_mov_b32_e32 v93, v2
	v_mov_b32_e32 v94, v2
	v_mov_b32_e32 v95, v2
	v_mov_b32_e32 v96, v2
	v_mov_b32_e32 v97, v2
	v_mov_b32_e32 v34, v2
	v_mov_b32_e32 v35, v2
	v_mov_b32_e32 v36, v2
	v_mov_b32_e32 v37, v2
	v_mov_b32_e32 v38, v2
	v_mov_b32_e32 v39, v2
	v_mov_b32_e32 v40, v2
	v_mov_b32_e32 v41, v2
	v_mov_b32_e32 v50, v2
	v_mov_b32_e32 v51, v2
	v_mov_b32_e32 v52, v2
	v_mov_b32_e32 v53, v2
	v_mov_b32_e32 v54, v2
	v_mov_b32_e32 v55, v2
	v_mov_b32_e32 v56, v2
	v_mov_b32_e32 v57, v2
	v_mov_b32_e32 v62, v2
	v_mov_b32_e32 v63, v2
	v_mov_b32_e32 v64, v2
	v_mov_b32_e32 v65, v2
	v_mov_b32_e32 v70, v2
	v_mov_b32_e32 v71, v2
	v_mov_b32_e32 v72, v2
	v_mov_b32_e32 v73, v2
	v_mov_b32_e32 v74, v2
	v_mov_b32_e32 v75, v2
	v_mov_b32_e32 v76, v2
	v_mov_b32_e32 v77, v2
	v_mov_b32_e32 v82, v2
	v_mov_b32_e32 v83, v2
	v_mov_b32_e32 v84, v2
	v_mov_b32_e32 v85, v2
	v_mov_b32_e32 v98, v2
	v_mov_b32_e32 v99, v2
	v_mov_b32_e32 v100, v2
	v_mov_b32_e32 v101, v2
	v_mov_b32_e32 v102, v2
	v_mov_b32_e32 v103, v2
	v_mov_b32_e32 v104, v2
	v_mov_b32_e32 v105, v2
	v_mov_b32_e32 v106, v2
	v_mov_b32_e32 v107, v2
	v_mov_b32_e32 v108, v2
	v_mov_b32_e32 v109, v2
	v_mov_b32_e32 v110, v2
	v_mov_b32_e32 v111, v2
	v_mov_b32_e32 v112, v2
	v_mov_b32_e32 v113, v2
	v_mov_b32_e32 v114, v2
	v_mov_b32_e32 v115, v2
	v_mov_b32_e32 v116, v2
	v_mov_b32_e32 v117, v2
	v_mov_b32_e32 v118, v2
	v_mov_b32_e32 v119, v2
	v_mov_b32_e32 v120, v2
	v_mov_b32_e32 v121, v2
	v_mov_b32_e32 v122, v2
	v_mov_b32_e32 v123, v2
	v_mov_b32_e32 v124, v2
	v_mov_b32_e32 v125, v2
	v_mov_b32_e32 v126, v2
	v_mov_b32_e32 v127, v2
	v_mov_b32_e32 v128, v2
	v_mov_b32_e32 v129, v2
	v_readlane_b32 s98, v250, 4
	s_cmp_lt_u32 s98, 4
	s_cbranch_scc1 .Lgp_4
	s_setprio 1
.Lgp_4:
.LBB0_774:
	ds_read_b128 v[156:159], v148
	ds_read_b128 v[160:163], v148 offset:1024
	ds_read_b128 v[164:167], v148 offset:2048
	ds_read_b128 v[168:171], v148 offset:3072
	ds_read_b128 v[172:175], v149
	ds_read_b128 v[176:179], v149 offset:1024
	ds_read_b128 v[180:183], v149 offset:2048
	ds_read_b128 v[196:199], v149 offset:3072
	s_add_u32 s28, s26, 0xfffc0080
	s_addc_u32 s29, s27, -1
	s_cmp_eq_u32 s57, 12
	s_cselect_b32 s31, s21, s29
	s_cselect_b32 s30, s53, s28
	s_cselect_b32 s29, s19, s56
	s_cselect_b32 s28, s54, s55
	v_lshl_add_u64 v[232:233], s[26:27], 0, v[140:141]
	s_add_i32 m0, s17, 0xc000
	ds_read_b128 v[200:203], v154
	ds_read_b128 v[204:207], v154 offset:1024
	ds_read_b128 v[208:211], v154 offset:2048
	ds_read_b128 v[212:215], v154 offset:3072
	ds_read_b128 v[216:219], v154 offset:4096
	ds_read_b128 v[220:223], v154 offset:5120
	ds_read_b128 v[224:227], v154 offset:6144
	ds_read_b128 v[228:231], v154 offset:7168
	global_load_lds_dwordx4 v[232:233], off
	v_lshl_add_u64 v[232:233], s[26:27], 0, v[138:139]
	s_add_i32 m0, s17, 0xe000
	s_nop 0
	global_load_lds_dwordx4 v[232:233], off
	s_waitcnt vmcnt(8)
	s_waitcnt lgkmcnt(0)
	s_barrier
; #define PG8_STAGE(bufoff, gbase, voff) do { _Pragma("unroll") for (int _i = 0; _i < 2; ++_i) \
;         __builtin_amdgcn_global_load_lds((const unsigned*)((const char*)(gbase) + (voff)[_i]), (PG8_LAS unsigned*)(lds + (bufoff) + ldsw + _i * 8192), 16, 0, 0); } while (0)
; #define PG8_LDA(dst, b, h) do { _Pragma("unroll") for (int m = 0; m < 4; ++m) _Pragma("unroll") for (int k = 0; k < 2; ++k) dst[m][k] = *(const PG8_LAS bf16x8*)(lds + PG8_SA(b, h) + aoff + m * 2048 + k * 1024); } while (0)
; #define PG8_MMA(ai, bj, At, Bt) do { __builtin_amdgcn_s_setprio(1); _Pragma("unroll") for (int m = 0; m < 4; ++m) _Pragma("unroll") for (int n = 0; n < 2; ++n) _Pragma("unroll") for (int k = 0; k < 2; ++k) \
;         acc[ai][bj][m][n] = __builtin_amdgcn_mfma_f32_16x16x32_bf16(Bt[n][k], At[m][k], acc[ai][bj][m][n], 0, 0, 0); __builtin_amdgcn_s_setprio(0); } while (0)
; #define PG8_WAIT_V(n) asm volatile("s_waitcnt vmcnt(" #n ")" ::: "memory")
; #define PG8_WAIT_L(n) asm volatile("s_waitcnt lgkmcnt(" #n ")" ::: "memory")
; #define PG8_BAR __builtin_amdgcn_s_barrier()
; #define PG8_SCHED __builtin_amdgcn_sched_barrier(0)
; template <class Epi, class Sched, bool ALIGN_EPI = false, bool SP2 = false>
; __device__ __forceinline__ void gemm_phase(PG8_LAS unsigned char* lds, const Gemm g, const Sched& S, const Epi& E) {
;     ...
;             PG8_WAIT_V(8); PG8_WAIT_L(0); PG8_BAR; PG8_MMA(0, 0, At, B0); PG8_MMA(0, 1, At, B1); PG8_BAR; PG8_SCHED;
;             PG8_LDA(At, 0, 1); PG8_STAGE(PG8_SB(0, 0), b2, voffB); PG8_STAGE(PG8_SB(0, 1), b2 + hstepB, voffB); PG8_STAGE(PG8_SA(0, 0), a2, voffA);
;             PG8_WAIT_V(8); PG8_WAIT_L(0); PG8_BAR; PG8_MMA(1, 0, At, B0); PG8_MMA(1, 1, At, B1); PG8_BAR; PG8_SCHED;
	s_waitcnt lgkmcnt(0)
	v_mfma_f32_16x16x32_bf16 v[126:129], v[156:159], v[200:203], v[126:129]
	v_mfma_f32_16x16x32_bf16 v[122:125], v[164:167], v[200:203], v[122:125]
	v_mfma_f32_16x16x32_bf16 v[118:121], v[156:159], v[208:211], v[118:121]
	v_mfma_f32_16x16x32_bf16 v[114:117], v[164:167], v[208:211], v[114:117]
	v_mfma_f32_16x16x32_bf16 v[110:113], v[156:159], v[216:219], v[110:113]
	v_mfma_f32_16x16x32_bf16 v[106:109], v[164:167], v[216:219], v[106:109]
	v_mfma_f32_16x16x32_bf16 v[102:105], v[156:159], v[224:227], v[102:105]
	v_mfma_f32_16x16x32_bf16 v[98:101], v[164:167], v[224:227], v[98:101]
	v_mfma_f32_16x16x32_bf16 v[126:129], v[160:163], v[204:207], v[126:129]
	v_mfma_f32_16x16x32_bf16 v[122:125], v[168:171], v[204:207], v[122:125]
	v_mfma_f32_16x16x32_bf16 v[118:121], v[160:163], v[212:215], v[118:121]
	v_mfma_f32_16x16x32_bf16 v[114:117], v[168:171], v[212:215], v[114:117]
	v_mfma_f32_16x16x32_bf16 v[110:113], v[160:163], v[220:223], v[110:113]
	v_mfma_f32_16x16x32_bf16 v[106:109], v[168:171], v[220:223], v[106:109]
	v_mfma_f32_16x16x32_bf16 v[102:105], v[160:163], v[228:231], v[102:105]
	v_mfma_f32_16x16x32_bf16 v[98:101], v[168:171], v[228:231], v[98:101]
	v_mfma_f32_16x16x32_bf16 v[82:85], v[172:175], v[200:203], v[82:85]
	v_mfma_f32_16x16x32_bf16 v[74:77], v[180:183], v[200:203], v[74:77]
	v_mfma_f32_16x16x32_bf16 v[70:73], v[172:175], v[208:211], v[70:73]
	v_mfma_f32_16x16x32_bf16 v[62:65], v[180:183], v[208:211], v[62:65]
	v_mfma_f32_16x16x32_bf16 v[54:57], v[172:175], v[216:219], v[54:57]
	v_mfma_f32_16x16x32_bf16 v[50:53], v[180:183], v[216:219], v[50:53]
	v_mfma_f32_16x16x32_bf16 v[38:41], v[172:175], v[224:227], v[38:41]
	v_mfma_f32_16x16x32_bf16 v[34:37], v[180:183], v[224:227], v[34:37]
	v_mfma_f32_16x16x32_bf16 v[82:85], v[176:179], v[204:207], v[82:85]
	v_mfma_f32_16x16x32_bf16 v[74:77], v[196:199], v[204:207], v[74:77]
	v_mfma_f32_16x16x32_bf16 v[70:73], v[176:179], v[212:215], v[70:73]
	v_mfma_f32_16x16x32_bf16 v[62:65], v[196:199], v[212:215], v[62:65]
	v_mfma_f32_16x16x32_bf16 v[54:57], v[176:179], v[220:223], v[54:57]
	v_mfma_f32_16x16x32_bf16 v[50:53], v[196:199], v[220:223], v[50:53]
	v_mfma_f32_16x16x32_bf16 v[38:41], v[176:179], v[228:231], v[38:41]
	v_mfma_f32_16x16x32_bf16 v[34:37], v[196:199], v[228:231], v[34:37]
	s_barrier
	s_add_i32 s58, s47, s34
	v_lshl_add_u64 v[232:233], s[28:29], 0, v[132:133]
	s_mov_b32 m0, s58
	ds_read_b128 v[200:203], v154 offset:16384
	ds_read_b128 v[204:207], v154 offset:17408
	ds_read_b128 v[208:211], v154 offset:18432
	ds_read_b128 v[212:215], v154 offset:19456
	ds_read_b128 v[216:219], v154 offset:20480
	ds_read_b128 v[220:223], v154 offset:21504
	ds_read_b128 v[224:227], v154 offset:22528
	ds_read_b128 v[228:231], v154 offset:23552
	global_load_lds_dwordx4 v[232:233], off
	s_add_i32 m0, s58, 0x2000
	s_add_u32 s58, s28, 0x40000
	v_lshl_add_u64 v[234:235], s[28:29], 0, v[136:137]
	s_addc_u32 s59, s29, 0
	s_add_i32 s60, s48, s34
	global_load_lds_dwordx4 v[234:235], off
	v_lshl_add_u64 v[236:237], s[58:59], 0, v[132:133]
	s_mov_b32 m0, s60
	v_lshl_add_u64 v[238:239], s[30:31], 0, v[134:135]
	global_load_lds_dwordx4 v[236:237], off
	v_lshl_add_u64 v[236:237], s[58:59], 0, v[136:137]
	s_add_i32 m0, s60, 0x2000
	s_nop 0
	global_load_lds_dwordx4 v[236:237], off
	v_lshl_add_u64 v[236:237], s[30:31], 0, v[130:131]
	s_mov_b32 m0, s17
	s_nop 0
	global_load_lds_dwordx4 v[236:237], off
	s_mov_b32 m0, s35
	s_nop 0
	global_load_lds_dwordx4 v[238:239], off
	s_waitcnt vmcnt(8)
	s_waitcnt lgkmcnt(0)
	s_barrier
	s_waitcnt lgkmcnt(0)
	v_mfma_f32_16x16x32_bf16 v[94:97], v[156:159], v[200:203], v[94:97]
	v_mfma_f32_16x16x32_bf16 v[90:93], v[164:167], v[200:203], v[90:93]
	v_mfma_f32_16x16x32_bf16 v[86:89], v[156:159], v[208:211], v[86:89]
	v_mfma_f32_16x16x32_bf16 v[78:81], v[164:167], v[208:211], v[78:81]
	v_mfma_f32_16x16x32_bf16 v[66:69], v[156:159], v[216:219], v[66:69]
	v_mfma_f32_16x16x32_bf16 v[58:61], v[164:167], v[216:219], v[58:61]
	v_mfma_f32_16x16x32_bf16 v[46:49], v[156:159], v[224:227], v[46:49]
	v_mfma_f32_16x16x32_bf16 v[42:45], v[164:167], v[224:227], v[42:45]
	v_mfma_f32_16x16x32_bf16 v[94:97], v[160:163], v[204:207], v[94:97]
	v_mfma_f32_16x16x32_bf16 v[90:93], v[168:171], v[204:207], v[90:93]
	v_mfma_f32_16x16x32_bf16 v[86:89], v[160:163], v[212:215], v[86:89]
	v_mfma_f32_16x16x32_bf16 v[78:81], v[168:171], v[212:215], v[78:81]
	v_mfma_f32_16x16x32_bf16 v[66:69], v[160:163], v[220:223], v[66:69]
	v_mfma_f32_16x16x32_bf16 v[58:61], v[168:171], v[220:223], v[58:61]
	v_mfma_f32_16x16x32_bf16 v[46:49], v[160:163], v[228:231], v[46:49]
	v_mfma_f32_16x16x32_bf16 v[42:45], v[168:171], v[228:231], v[42:45]
	v_mfma_f32_16x16x32_bf16 v[30:33], v[172:175], v[200:203], v[30:33]
	v_mfma_f32_16x16x32_bf16 v[26:29], v[180:183], v[200:203], v[26:29]
	v_mfma_f32_16x16x32_bf16 v[22:25], v[172:175], v[208:211], v[22:25]
	v_mfma_f32_16x16x32_bf16 v[18:21], v[180:183], v[208:211], v[18:21]
	v_mfma_f32_16x16x32_bf16 v[14:17], v[172:175], v[216:219], v[14:17]
	v_mfma_f32_16x16x32_bf16 v[10:13], v[180:183], v[216:219], v[10:13]
	v_mfma_f32_16x16x32_bf16 v[6:9], v[172:175], v[224:227], v[6:9]
	v_mfma_f32_16x16x32_bf16 v[2:5], v[180:183], v[224:227], v[2:5]
	v_mfma_f32_16x16x32_bf16 v[30:33], v[176:179], v[204:207], v[30:33]
	v_mfma_f32_16x16x32_bf16 v[26:29], v[196:199], v[204:207], v[26:29]
	v_mfma_f32_16x16x32_bf16 v[22:25], v[176:179], v[212:215], v[22:25]
	v_mfma_f32_16x16x32_bf16 v[18:21], v[196:199], v[212:215], v[18:21]
	v_mfma_f32_16x16x32_bf16 v[14:17], v[176:179], v[220:223], v[14:17]
	v_mfma_f32_16x16x32_bf16 v[10:13], v[196:199], v[220:223], v[10:13]
	v_mfma_f32_16x16x32_bf16 v[6:9], v[176:179], v[228:231], v[6:9]
	v_mfma_f32_16x16x32_bf16 v[2:5], v[196:199], v[228:231], v[2:5]
	s_barrier
; #define PG8_STAGE(bufoff, gbase, voff) do { _Pragma("unroll") for (int _i = 0; _i < 2; ++_i) \
;         __builtin_amdgcn_global_load_lds((const unsigned*)((const char*)(gbase) + (voff)[_i]), (PG8_LAS unsigned*)(lds + (bufoff) + ldsw + _i * 8192), 16, 0, 0); } while (0)
; #define PG8_LDA(dst, b, h) do { _Pragma("unroll") for (int m = 0; m < 4; ++m) _Pragma("unroll") for (int k = 0; k < 2; ++k) dst[m][k] = *(const PG8_LAS bf16x8*)(lds + PG8_SA(b, h) + aoff + m * 2048 + k * 1024); } while (0)
; #define PG8_LDB(dst, b, h) do { _Pragma("unroll") for (int n = 0; n < 2; ++n) _Pragma("unroll") for (int k = 0; k < 2; ++k) dst[n][k] = *(const PG8_LAS bf16x8*)(lds + PG8_SB(b, h) + boff + n * 2048 + k * 1024); } while (0)
; #define PG8_MMA(ai, bj, At, Bt) do { __builtin_amdgcn_s_setprio(1); _Pragma("unroll") for (int m = 0; m < 4; ++m) _Pragma("unroll") for (int n = 0; n < 2; ++n) _Pragma("unroll") for (int k = 0; k < 2; ++k) \
;         acc[ai][bj][m][n] = __builtin_amdgcn_mfma_f32_16x16x32_bf16(Bt[n][k], At[m][k], acc[ai][bj][m][n], 0, 0, 0); __builtin_amdgcn_s_setprio(0); } while (0)
; #define PG8_WAIT_V(n) asm volatile("s_waitcnt vmcnt(" #n ")" ::: "memory")
; #define PG8_WAIT_L(n) asm volatile("s_waitcnt lgkmcnt(" #n ")" ::: "memory")
; #define PG8_BAR __builtin_amdgcn_s_barrier()
; #define PG8_SCHED __builtin_amdgcn_sched_barrier(0)
; template <class Epi, class Sched, bool ALIGN_EPI = false, bool SP2 = false>
; __device__ __forceinline__ void gemm_phase(PG8_LAS unsigned char* lds, const Gemm g, const Sched& S, const Epi& E) {
;     ...
;             PG8_LDB(B0, 1, 0); PG8_LDB(B1, 1, 1); PG8_SCHED; PG8_LDA(At, 1, 0); PG8_STAGE(PG8_SA(0, 1), a2 + hstepA, voffA);
;             PG8_WAIT_V(8); PG8_WAIT_L(0); PG8_BAR; PG8_MMA(0, 0, At, B0); PG8_MMA(0, 1, At, B1); PG8_BAR; PG8_SCHED;
	s_add_i32 s58, 0, 0x18000
	v_add_u32_e32 v155, s58, v146
	s_add_i32 s59, 0, 0x1c000
	ds_read_b128 v[156:159], v155
	ds_read_b128 v[160:163], v155 offset:1024
	ds_read_b128 v[164:167], v155 offset:2048
	ds_read_b128 v[168:171], v155 offset:3072
	v_add_u32_e32 v155, s59, v146
	ds_read_b128 v[172:175], v155
	ds_read_b128 v[176:179], v155 offset:1024
	ds_read_b128 v[180:183], v155 offset:2048
	ds_read_b128 v[196:199], v155 offset:3072
	s_add_u32 s30, s30, 0x40000
	s_addc_u32 s31, s31, 0
	s_mov_b32 m0, s36
	v_lshl_add_u64 v[240:241], s[30:31], 0, v[130:131]
	ds_read_b128 v[200:203], v154 offset:32768
	ds_read_b128 v[204:207], v154 offset:33792
	ds_read_b128 v[208:211], v154 offset:34816
	ds_read_b128 v[212:215], v154 offset:35840
	ds_read_b128 v[216:219], v154 offset:36864
	ds_read_b128 v[220:223], v154 offset:37888
	ds_read_b128 v[224:227], v154 offset:38912
	ds_read_b128 v[228:231], v154 offset:39936
	global_load_lds_dwordx4 v[240:241], off
	v_lshl_add_u64 v[240:241], s[30:31], 0, v[134:135]
	s_mov_b32 m0, s37
	s_nop 0
	global_load_lds_dwordx4 v[240:241], off
	s_waitcnt vmcnt(8)
	s_waitcnt lgkmcnt(0)
	s_barrier
	s_waitcnt lgkmcnt(0)
	v_mfma_f32_16x16x32_bf16 v[126:129], v[156:159], v[200:203], v[126:129]
	v_mfma_f32_16x16x32_bf16 v[122:125], v[164:167], v[200:203], v[122:125]
	v_mfma_f32_16x16x32_bf16 v[118:121], v[156:159], v[208:211], v[118:121]
	v_mfma_f32_16x16x32_bf16 v[114:117], v[164:167], v[208:211], v[114:117]
	v_mfma_f32_16x16x32_bf16 v[110:113], v[156:159], v[216:219], v[110:113]
	v_mfma_f32_16x16x32_bf16 v[106:109], v[164:167], v[216:219], v[106:109]
	v_mfma_f32_16x16x32_bf16 v[102:105], v[156:159], v[224:227], v[102:105]
	v_mfma_f32_16x16x32_bf16 v[98:101], v[164:167], v[224:227], v[98:101]
	v_mfma_f32_16x16x32_bf16 v[126:129], v[160:163], v[204:207], v[126:129]
	v_mfma_f32_16x16x32_bf16 v[122:125], v[168:171], v[204:207], v[122:125]
	v_mfma_f32_16x16x32_bf16 v[118:121], v[160:163], v[212:215], v[118:121]
	v_mfma_f32_16x16x32_bf16 v[114:117], v[168:171], v[212:215], v[114:117]
	v_mfma_f32_16x16x32_bf16 v[110:113], v[160:163], v[220:223], v[110:113]
	v_mfma_f32_16x16x32_bf16 v[106:109], v[168:171], v[220:223], v[106:109]
	v_mfma_f32_16x16x32_bf16 v[102:105], v[160:163], v[228:231], v[102:105]
	v_mfma_f32_16x16x32_bf16 v[98:101], v[168:171], v[228:231], v[98:101]
	v_mfma_f32_16x16x32_bf16 v[82:85], v[172:175], v[200:203], v[82:85]
	v_mfma_f32_16x16x32_bf16 v[74:77], v[180:183], v[200:203], v[74:77]
	v_mfma_f32_16x16x32_bf16 v[70:73], v[172:175], v[208:211], v[70:73]
	v_mfma_f32_16x16x32_bf16 v[62:65], v[180:183], v[208:211], v[62:65]
	v_mfma_f32_16x16x32_bf16 v[54:57], v[172:175], v[216:219], v[54:57]
	v_mfma_f32_16x16x32_bf16 v[50:53], v[180:183], v[216:219], v[50:53]
	v_mfma_f32_16x16x32_bf16 v[38:41], v[172:175], v[224:227], v[38:41]
	v_mfma_f32_16x16x32_bf16 v[34:37], v[180:183], v[224:227], v[34:37]
	v_mfma_f32_16x16x32_bf16 v[82:85], v[176:179], v[204:207], v[82:85]
	v_mfma_f32_16x16x32_bf16 v[74:77], v[196:199], v[204:207], v[74:77]
	v_mfma_f32_16x16x32_bf16 v[70:73], v[176:179], v[212:215], v[70:73]
	v_mfma_f32_16x16x32_bf16 v[62:65], v[196:199], v[212:215], v[62:65]
	v_mfma_f32_16x16x32_bf16 v[54:57], v[176:179], v[220:223], v[54:57]
	v_mfma_f32_16x16x32_bf16 v[50:53], v[196:199], v[220:223], v[50:53]
	v_mfma_f32_16x16x32_bf16 v[38:41], v[176:179], v[228:231], v[38:41]
	v_mfma_f32_16x16x32_bf16 v[34:37], v[196:199], v[228:231], v[34:37]
	s_barrier
; #define PG8_STAGE(bufoff, gbase, voff) do { _Pragma("unroll") for (int _i = 0; _i < 2; ++_i) \
;         __builtin_amdgcn_global_load_lds((const unsigned*)((const char*)(gbase) + (voff)[_i]), (PG8_LAS unsigned*)(lds + (bufoff) + ldsw + _i * 8192), 16, 0, 0); } while (0)
; #define PG8_LDA(dst, b, h) do { _Pragma("unroll") for (int m = 0; m < 4; ++m) _Pragma("unroll") for (int k = 0; k < 2; ++k) dst[m][k] = *(const PG8_LAS bf16x8*)(lds + PG8_SA(b, h) + aoff + m * 2048 + k * 1024); } while (0)
; #define PG8_MMA(ai, bj, At, Bt) do { __builtin_amdgcn_s_setprio(1); _Pragma("unroll") for (int m = 0; m < 4; ++m) _Pragma("unroll") for (int n = 0; n < 2; ++n) _Pragma("unroll") for (int k = 0; k < 2; ++k) \
;         acc[ai][bj][m][n] = __builtin_amdgcn_mfma_f32_16x16x32_bf16(Bt[n][k], At[m][k], acc[ai][bj][m][n], 0, 0, 0); __builtin_amdgcn_s_setprio(0); } while (0)
; #define PG8_WAIT_V(n) asm volatile("s_waitcnt vmcnt(" #n ")" ::: "memory")
; #define PG8_WAIT_L(n) asm volatile("s_waitcnt lgkmcnt(" #n ")" ::: "memory")
; #define PG8_BAR __builtin_amdgcn_s_barrier()
; #define PG8_SCHED __builtin_amdgcn_sched_barrier(0)
; template <class Epi, class Sched, bool ALIGN_EPI = false, bool SP2 = false>
; __device__ __forceinline__ void gemm_phase(PG8_LAS unsigned char* lds, const Gemm g, const Sched& S, const Epi& E) {
;     ...
;             PG8_LDA(At, 1, 1); PG8_STAGE(PG8_SB(1, 0), b3, voffB); PG8_STAGE(PG8_SB(1, 1), b3 + hstepB, voffB); PG8_STAGE(PG8_SA(1, 0), a3, voffA);
;             PG8_WAIT_V(8); PG8_WAIT_L(0); PG8_BAR; PG8_MMA(1, 0, At, B0); PG8_MMA(1, 1, At, B1); PG8_BAR; PG8_SCHED;
;     ...
;         if constexpr (ALIGN_EPI) { if (wr == 0) PG8_BAR; }
	s_add_i32 s30, s58, s34
	v_lshl_add_u64 v[232:233], v[232:233], 0, s[8:9]
	s_mov_b32 m0, s30
	ds_read_b128 v[200:203], v154 offset:49152
	ds_read_b128 v[204:207], v154 offset:50176
	ds_read_b128 v[208:211], v154 offset:51200
	ds_read_b128 v[212:215], v154 offset:52224
	ds_read_b128 v[216:219], v154 offset:53248
	ds_read_b128 v[220:223], v154 offset:54272
	ds_read_b128 v[224:227], v154 offset:55296
	ds_read_b128 v[228:231], v154 offset:56320
	global_load_lds_dwordx4 v[232:233], off
	s_add_i32 m0, s30, 0x2000
	s_add_u32 s28, s28, 0x40080
	v_lshl_add_u64 v[232:233], v[234:235], 0, s[8:9]
	s_addc_u32 s29, s29, 0
	s_add_i32 s30, s59, s34
	global_load_lds_dwordx4 v[232:233], off
	v_lshl_add_u64 v[232:233], s[28:29], 0, v[132:133]
	s_mov_b32 m0, s30
	s_nop 0
	global_load_lds_dwordx4 v[232:233], off
	v_lshl_add_u64 v[232:233], s[28:29], 0, v[136:137]
	s_add_i32 m0, s30, 0x2000
	s_nop 0
	global_load_lds_dwordx4 v[232:233], off
	v_lshl_add_u64 v[232:233], v[236:237], 0, s[8:9]
	s_mov_b32 m0, s43
	s_nop 0
	global_load_lds_dwordx4 v[232:233], off
	v_lshl_add_u64 v[232:233], v[238:239], 0, s[8:9]
	s_mov_b32 m0, s44
	s_nop 0
	global_load_lds_dwordx4 v[232:233], off
	s_waitcnt vmcnt(8)
	s_waitcnt lgkmcnt(0)
	s_barrier
	s_waitcnt lgkmcnt(0)
	v_mfma_f32_16x16x32_bf16 v[94:97], v[156:159], v[200:203], v[94:97]
	v_mfma_f32_16x16x32_bf16 v[90:93], v[164:167], v[200:203], v[90:93]
	v_mfma_f32_16x16x32_bf16 v[86:89], v[156:159], v[208:211], v[86:89]
	v_mfma_f32_16x16x32_bf16 v[78:81], v[164:167], v[208:211], v[78:81]
	v_mfma_f32_16x16x32_bf16 v[66:69], v[156:159], v[216:219], v[66:69]
	v_mfma_f32_16x16x32_bf16 v[58:61], v[164:167], v[216:219], v[58:61]
	v_mfma_f32_16x16x32_bf16 v[46:49], v[156:159], v[224:227], v[46:49]
	v_mfma_f32_16x16x32_bf16 v[42:45], v[164:167], v[224:227], v[42:45]
	v_mfma_f32_16x16x32_bf16 v[94:97], v[160:163], v[204:207], v[94:97]
	v_mfma_f32_16x16x32_bf16 v[90:93], v[168:171], v[204:207], v[90:93]
	v_mfma_f32_16x16x32_bf16 v[86:89], v[160:163], v[212:215], v[86:89]
	v_mfma_f32_16x16x32_bf16 v[78:81], v[168:171], v[212:215], v[78:81]
	v_mfma_f32_16x16x32_bf16 v[66:69], v[160:163], v[220:223], v[66:69]
	v_mfma_f32_16x16x32_bf16 v[58:61], v[168:171], v[220:223], v[58:61]
	v_mfma_f32_16x16x32_bf16 v[46:49], v[160:163], v[228:231], v[46:49]
	v_mfma_f32_16x16x32_bf16 v[42:45], v[168:171], v[228:231], v[42:45]
	v_mfma_f32_16x16x32_bf16 v[30:33], v[172:175], v[200:203], v[30:33]
	v_mfma_f32_16x16x32_bf16 v[26:29], v[180:183], v[200:203], v[26:29]
	v_mfma_f32_16x16x32_bf16 v[22:25], v[172:175], v[208:211], v[22:25]
	v_mfma_f32_16x16x32_bf16 v[18:21], v[180:183], v[208:211], v[18:21]
	v_mfma_f32_16x16x32_bf16 v[14:17], v[172:175], v[216:219], v[14:17]
	v_mfma_f32_16x16x32_bf16 v[10:13], v[180:183], v[216:219], v[10:13]
	v_mfma_f32_16x16x32_bf16 v[6:9], v[172:175], v[224:227], v[6:9]
	v_mfma_f32_16x16x32_bf16 v[2:5], v[180:183], v[224:227], v[2:5]
	v_mfma_f32_16x16x32_bf16 v[30:33], v[176:179], v[204:207], v[30:33]
	v_mfma_f32_16x16x32_bf16 v[26:29], v[196:199], v[204:207], v[26:29]
	v_mfma_f32_16x16x32_bf16 v[22:25], v[176:179], v[212:215], v[22:25]
	v_mfma_f32_16x16x32_bf16 v[18:21], v[196:199], v[212:215], v[18:21]
	v_mfma_f32_16x16x32_bf16 v[14:17], v[176:179], v[220:223], v[14:17]
	v_mfma_f32_16x16x32_bf16 v[10:13], v[196:199], v[220:223], v[10:13]
	v_mfma_f32_16x16x32_bf16 v[6:9], v[176:179], v[228:231], v[6:9]
	v_mfma_f32_16x16x32_bf16 v[2:5], v[196:199], v[228:231], v[2:5]
	s_barrier
	s_add_i32 s57, s57, 2
	s_add_u32 s55, s55, 0x100
	s_addc_u32 s56, s56, 0
	s_add_u32 s26, s26, 0x100
	s_addc_u32 s27, s27, 0
	s_cmp_gt_u32 s57, 13
	s_cbranch_scc0 .LBB0_774
	s_setprio 0
	s_and_b64 vcc, exec, s[10:11]
	s_cbranch_vccz .LBB0_777
	s_barrier

; #define PG8_STAGE(bufoff, gbase, voff) do { _Pragma("unroll") for (int _i = 0; _i < 2; ++_i) \
;         __builtin_amdgcn_global_load_lds((const unsigned*)((const char*)(gbase) + (voff)[_i]), (PG8_LAS unsigned*)(lds + (bufoff) + ldsw + _i * 8192), 16, 0, 0); } while (0)
; #define PG8_LDA(dst, b, h) do { _Pragma("unroll") for (int m = 0; m < 4; ++m) _Pragma("unroll") for (int k = 0; k < 2; ++k) dst[m][k] = *(const PG8_LAS bf16x8*)(lds + PG8_SA(b, h) + aoff + m * 2048 + k * 1024); } while (0)
; #define PG8_LDB(dst, b, h) do { _Pragma("unroll") for (int n = 0; n < 2; ++n) _Pragma("unroll") for (int k = 0; k < 2; ++k) dst[n][k] = *(const PG8_LAS bf16x8*)(lds + PG8_SB(b, h) + boff + n * 2048 + k * 1024); } while (0)
; #define PG8_SCHED __builtin_amdgcn_sched_barrier(0)
;     DI bool next(int i, pg8::Unit& u) const { if (i > 0 || !has) return false; u.pm = pm; u.pn = 0; return true; }
; template <class Epi, class Sched, bool ALIGN_EPI = false, bool SP2 = false>
; __device__ __forceinline__ void gemm_phase(PG8_LAS unsigned char* lds, const Gemm g, const Sched& S, const Epi& E) {
;     ...
;         const bool has_next = S.next(ui + 1, nxt);
;         const char* nA = has_next ? (const char*)g.A + (size_t)nxt.pm * tstepA : cA; const char* nB = has_next ? (const char*)g.Bt + (size_t)nxt.pn * tstepB : cB;
;         for (int t = 0; t < nt; t += 2) {
;             const bool last = (t == nt - 2);
;             const char* a1 = cA + (size_t)(t + 1) * kstep;
;             const char* a2 = last ? nA : cA + (size_t)(t + 2) * kstep; const char* b2 = last ? nB : cB + (size_t)(t + 2) * kstep;
;             const char* a3 = a2 + kstep; const char* b3 = b2 + kstep;
;             if (last && has_next) S.a_ready(nxt);
;             if constexpr (SP2) {
;             PG8_LDB(B0, 0, 0); PG8_LDB(B1, 0, 1); PG8_SCHED; PG8_LDA(At, 0, 0); PG8_STAGE(PG8_SA(1, 1), a1 + hstepA, voffA);
;     ...
; #pragma unroll
;         for (int a = 0; a < 2; ++a)
; #pragma unroll
;             for (int b = 0; b < 2; ++b)
; #pragma unroll
;                 for (int m = 0; m < 4; ++m)
; #pragma unroll
;                     for (int n = 0; n < 2; ++n) acc[a][b][m][n] = (f32x4){0.f, 0.f, 0.f, 0.f};
;         cur = nxt; cA = nA; cB = nB; ++ui;
.LBB0_898:
	s_ashr_i32 s25, s24, 31
	s_lshl_b64 s[26:27], s[24:25], 19
	s_add_u32 s26, s48, s26
	s_addc_u32 s27, s49, s27
	s_and_b64 s[28:29], s[8:9], exec
	s_cselect_b32 s25, s27, s37
	s_cselect_b32 s31, s26, s36
	s_ashr_i32 s23, s22, 31
	s_lshl_b64 s[28:29], s[22:23], 19
	s_add_u32 s28, s50, s28
	s_addc_u32 s29, s51, s29
	s_and_b64 s[38:39], s[8:9], exec
	s_cselect_b32 s23, s29, s35
	s_cselect_b32 s40, s28, s34
	s_add_u32 s41, s34, 0x100
	s_addc_u32 s42, s35, 0
	s_add_u32 s34, s36, 0x40080
	v_mov_b32_e32 v2, 0
	s_addc_u32 s35, s37, 0
	s_mov_b32 s43, -2
	v_mov_b32_e32 v3, v2
	v_mov_b32_e32 v4, v2
	v_mov_b32_e32 v5, v2
	v_mov_b32_e32 v6, v2
	v_mov_b32_e32 v7, v2
	v_mov_b32_e32 v8, v2
	v_mov_b32_e32 v9, v2
	v_mov_b32_e32 v18, v2
	v_mov_b32_e32 v19, v2
	v_mov_b32_e32 v20, v2
	v_mov_b32_e32 v21, v2
	v_mov_b32_e32 v22, v2
	v_mov_b32_e32 v23, v2
	v_mov_b32_e32 v24, v2
	v_mov_b32_e32 v25, v2
	v_mov_b32_e32 v34, v2
	v_mov_b32_e32 v35, v2
	v_mov_b32_e32 v36, v2
	v_mov_b32_e32 v37, v2
	v_mov_b32_e32 v38, v2
	v_mov_b32_e32 v39, v2
	v_mov_b32_e32 v40, v2
	v_mov_b32_e32 v41, v2
	v_mov_b32_e32 v50, v2
	v_mov_b32_e32 v51, v2
	v_mov_b32_e32 v52, v2
	v_mov_b32_e32 v53, v2
	v_mov_b32_e32 v54, v2
	v_mov_b32_e32 v55, v2
	v_mov_b32_e32 v56, v2
	v_mov_b32_e32 v57, v2
	v_mov_b32_e32 v10, v2
	v_mov_b32_e32 v11, v2
	v_mov_b32_e32 v12, v2
	v_mov_b32_e32 v13, v2
	v_mov_b32_e32 v14, v2
	v_mov_b32_e32 v15, v2
	v_mov_b32_e32 v16, v2
	v_mov_b32_e32 v17, v2
	v_mov_b32_e32 v26, v2
	v_mov_b32_e32 v27, v2
	v_mov_b32_e32 v28, v2
	v_mov_b32_e32 v29, v2
	v_mov_b32_e32 v30, v2
	v_mov_b32_e32 v31, v2
	v_mov_b32_e32 v32, v2
	v_mov_b32_e32 v33, v2
	v_mov_b32_e32 v42, v2
	v_mov_b32_e32 v43, v2
	v_mov_b32_e32 v44, v2
	v_mov_b32_e32 v45, v2
	v_mov_b32_e32 v46, v2
	v_mov_b32_e32 v47, v2
	v_mov_b32_e32 v48, v2
	v_mov_b32_e32 v49, v2
	v_mov_b32_e32 v58, v2
	v_mov_b32_e32 v59, v2
	v_mov_b32_e32 v60, v2
	v_mov_b32_e32 v61, v2
	v_mov_b32_e32 v62, v2
	v_mov_b32_e32 v63, v2
	v_mov_b32_e32 v64, v2
	v_mov_b32_e32 v65, v2
	v_mov_b32_e32 v66, v2
	v_mov_b32_e32 v67, v2
	v_mov_b32_e32 v68, v2
	v_mov_b32_e32 v69, v2
	v_mov_b32_e32 v70, v2
	v_mov_b32_e32 v71, v2
	v_mov_b32_e32 v72, v2
	v_mov_b32_e32 v73, v2
	v_mov_b32_e32 v82, v2
	v_mov_b32_e32 v83, v2
	v_mov_b32_e32 v84, v2
	v_mov_b32_e32 v85, v2
	v_mov_b32_e32 v86, v2
	v_mov_b32_e32 v87, v2
	v_mov_b32_e32 v88, v2
	v_mov_b32_e32 v89, v2
	v_mov_b32_e32 v98, v2
	v_mov_b32_e32 v99, v2
	v_mov_b32_e32 v100, v2
	v_mov_b32_e32 v101, v2
	v_mov_b32_e32 v102, v2
	v_mov_b32_e32 v103, v2
	v_mov_b32_e32 v104, v2
	v_mov_b32_e32 v105, v2
	v_mov_b32_e32 v114, v2
	v_mov_b32_e32 v115, v2
	v_mov_b32_e32 v116, v2
	v_mov_b32_e32 v117, v2
	v_mov_b32_e32 v118, v2
	v_mov_b32_e32 v119, v2
	v_mov_b32_e32 v120, v2
	v_mov_b32_e32 v121, v2
	v_mov_b32_e32 v74, v2
	v_mov_b32_e32 v75, v2
	v_mov_b32_e32 v76, v2
	v_mov_b32_e32 v77, v2
	v_mov_b32_e32 v78, v2
	v_mov_b32_e32 v79, v2
	v_mov_b32_e32 v80, v2
	v_mov_b32_e32 v81, v2
	v_mov_b32_e32 v90, v2
	v_mov_b32_e32 v91, v2
	v_mov_b32_e32 v92, v2
	v_mov_b32_e32 v93, v2
	v_mov_b32_e32 v94, v2
	v_mov_b32_e32 v95, v2
	v_mov_b32_e32 v96, v2
	v_mov_b32_e32 v97, v2
	v_mov_b32_e32 v106, v2
	v_mov_b32_e32 v107, v2
	v_mov_b32_e32 v108, v2
	v_mov_b32_e32 v109, v2
	v_mov_b32_e32 v110, v2
	v_mov_b32_e32 v111, v2
	v_mov_b32_e32 v112, v2
	v_mov_b32_e32 v113, v2
	v_mov_b32_e32 v122, v2
	v_mov_b32_e32 v123, v2
	v_mov_b32_e32 v124, v2
	v_mov_b32_e32 v125, v2
	v_mov_b32_e32 v126, v2
	v_mov_b32_e32 v127, v2
	v_mov_b32_e32 v128, v2
	v_mov_b32_e32 v129, v2
	v_readlane_b32 s98, v250, 4
	s_cmp_lt_u32 s98, 4
	s_cbranch_scc1 .Lgp_5
	s_setprio 1
.Lgp_5:
.LBB0_899:
	ds_read_b128 v[160:163], v164
	ds_read_b128 v[168:171], v164 offset:1024
	ds_read_b128 v[172:175], v164 offset:2048
	ds_read_b128 v[176:179], v164 offset:3072
	ds_read_b128 v[180:183], v165
	ds_read_b128 v[196:199], v165 offset:1024
	ds_read_b128 v[200:203], v165 offset:2048
	ds_read_b128 v[204:207], v165 offset:3072
	s_add_u32 s36, s34, 0xfffc0080
	s_addc_u32 s37, s35, -1
	s_cmp_eq_u32 s43, 12
	s_cselect_b32 s39, s25, s37
	s_cselect_b32 s38, s31, s36
	s_cselect_b32 s37, s23, s42
	s_cselect_b32 s36, s40, s41
	v_lshl_add_u64 v[240:241], s[34:35], 0, v[148:149]
	s_add_i32 m0, s44, 0xc000
	ds_read_b128 v[208:211], v166
	ds_read_b128 v[212:215], v166 offset:1024
	ds_read_b128 v[216:219], v166 offset:2048
	ds_read_b128 v[220:223], v166 offset:3072
	ds_read_b128 v[224:227], v166 offset:4096
	ds_read_b128 v[228:231], v166 offset:5120
	ds_read_b128 v[232:235], v166 offset:6144
	ds_read_b128 v[236:239], v166 offset:7168
	global_load_lds_dwordx4 v[240:241], off
	v_lshl_add_u64 v[240:241], s[34:35], 0, v[146:147]
	s_add_i32 m0, s44, 0xe000
	s_nop 0
	global_load_lds_dwordx4 v[240:241], off
	s_waitcnt vmcnt(8)
	s_waitcnt lgkmcnt(0)
	s_barrier
; #define PG8_STAGE(bufoff, gbase, voff) do { _Pragma("unroll") for (int _i = 0; _i < 2; ++_i) \
;         __builtin_amdgcn_global_load_lds((const unsigned*)((const char*)(gbase) + (voff)[_i]), (PG8_LAS unsigned*)(lds + (bufoff) + ldsw + _i * 8192), 16, 0, 0); } while (0)
; #define PG8_LDA(dst, b, h) do { _Pragma("unroll") for (int m = 0; m < 4; ++m) _Pragma("unroll") for (int k = 0; k < 2; ++k) dst[m][k] = *(const PG8_LAS bf16x8*)(lds + PG8_SA(b, h) + aoff + m * 2048 + k * 1024); } while (0)
; #define PG8_MMA(ai, bj, At, Bt) do { __builtin_amdgcn_s_setprio(1); _Pragma("unroll") for (int m = 0; m < 4; ++m) _Pragma("unroll") for (int n = 0; n < 2; ++n) _Pragma("unroll") for (int k = 0; k < 2; ++k) \
;         acc[ai][bj][m][n] = __builtin_amdgcn_mfma_f32_16x16x32_bf16(Bt[n][k], At[m][k], acc[ai][bj][m][n], 0, 0, 0); __builtin_amdgcn_s_setprio(0); } while (0)
; #define PG8_WAIT_V(n) asm volatile("s_waitcnt vmcnt(" #n ")" ::: "memory")
; #define PG8_WAIT_L(n) asm volatile("s_waitcnt lgkmcnt(" #n ")" ::: "memory")
; #define PG8_BAR __builtin_amdgcn_s_barrier()
; #define PG8_SCHED __builtin_amdgcn_sched_barrier(0)
; template <class Epi, class Sched, bool ALIGN_EPI = false, bool SP2 = false>
; __device__ __forceinline__ void gemm_phase(PG8_LAS unsigned char* lds, const Gemm g, const Sched& S, const Epi& E) {
;     ...
;             PG8_WAIT_V(8); PG8_WAIT_L(0); PG8_BAR; PG8_MMA(0, 0, At, B0); PG8_MMA(0, 1, At, B1); PG8_BAR; PG8_SCHED;
;             PG8_LDA(At, 0, 1); PG8_STAGE(PG8_SB(0, 0), b2, voffB); PG8_STAGE(PG8_SB(0, 1), b2 + hstepB, voffB); PG8_STAGE(PG8_SA(0, 0), a2, voffA);
;             PG8_WAIT_V(8); PG8_WAIT_L(0); PG8_BAR; PG8_MMA(1, 0, At, B0); PG8_MMA(1, 1, At, B1); PG8_BAR; PG8_SCHED;
	s_waitcnt lgkmcnt(0)
	v_mfma_f32_16x16x32_bf16 v[126:129], v[160:163], v[208:211], v[126:129]
	v_mfma_f32_16x16x32_bf16 v[122:125], v[172:175], v[208:211], v[122:125]
	v_mfma_f32_16x16x32_bf16 v[110:113], v[160:163], v[216:219], v[110:113]
	v_mfma_f32_16x16x32_bf16 v[106:109], v[172:175], v[216:219], v[106:109]
	v_mfma_f32_16x16x32_bf16 v[94:97], v[160:163], v[224:227], v[94:97]
	v_mfma_f32_16x16x32_bf16 v[90:93], v[172:175], v[224:227], v[90:93]
	v_mfma_f32_16x16x32_bf16 v[78:81], v[160:163], v[232:235], v[78:81]
	v_mfma_f32_16x16x32_bf16 v[74:77], v[172:175], v[232:235], v[74:77]
	v_mfma_f32_16x16x32_bf16 v[126:129], v[168:171], v[212:215], v[126:129]
	v_mfma_f32_16x16x32_bf16 v[122:125], v[176:179], v[212:215], v[122:125]
	v_mfma_f32_16x16x32_bf16 v[110:113], v[168:171], v[220:223], v[110:113]
	v_mfma_f32_16x16x32_bf16 v[106:109], v[176:179], v[220:223], v[106:109]
	v_mfma_f32_16x16x32_bf16 v[94:97], v[168:171], v[228:231], v[94:97]
	v_mfma_f32_16x16x32_bf16 v[90:93], v[176:179], v[228:231], v[90:93]
	v_mfma_f32_16x16x32_bf16 v[78:81], v[168:171], v[236:239], v[78:81]
	v_mfma_f32_16x16x32_bf16 v[74:77], v[176:179], v[236:239], v[74:77]
	v_mfma_f32_16x16x32_bf16 v[118:121], v[180:183], v[208:211], v[118:121]
	v_mfma_f32_16x16x32_bf16 v[114:117], v[200:203], v[208:211], v[114:117]
	v_mfma_f32_16x16x32_bf16 v[102:105], v[180:183], v[216:219], v[102:105]
	v_mfma_f32_16x16x32_bf16 v[98:101], v[200:203], v[216:219], v[98:101]
	v_mfma_f32_16x16x32_bf16 v[86:89], v[180:183], v[224:227], v[86:89]
	v_mfma_f32_16x16x32_bf16 v[82:85], v[200:203], v[224:227], v[82:85]
	v_mfma_f32_16x16x32_bf16 v[70:73], v[180:183], v[232:235], v[70:73]
	v_mfma_f32_16x16x32_bf16 v[66:69], v[200:203], v[232:235], v[66:69]
	v_mfma_f32_16x16x32_bf16 v[118:121], v[196:199], v[212:215], v[118:121]
	v_mfma_f32_16x16x32_bf16 v[114:117], v[204:207], v[212:215], v[114:117]
	v_mfma_f32_16x16x32_bf16 v[102:105], v[196:199], v[220:223], v[102:105]
	v_mfma_f32_16x16x32_bf16 v[98:101], v[204:207], v[220:223], v[98:101]
	v_mfma_f32_16x16x32_bf16 v[86:89], v[196:199], v[228:231], v[86:89]
	v_mfma_f32_16x16x32_bf16 v[82:85], v[204:207], v[228:231], v[82:85]
	v_mfma_f32_16x16x32_bf16 v[70:73], v[196:199], v[236:239], v[70:73]
	v_mfma_f32_16x16x32_bf16 v[66:69], v[204:207], v[236:239], v[66:69]
	s_barrier
	s_add_i32 s66, s63, s33
	v_lshl_add_u64 v[240:241], s[36:37], 0, v[132:133]
	s_mov_b32 m0, s66
	ds_read_b128 v[208:211], v166 offset:16384
	ds_read_b128 v[212:215], v166 offset:17408
	ds_read_b128 v[216:219], v166 offset:18432
	ds_read_b128 v[220:223], v166 offset:19456
	ds_read_b128 v[224:227], v166 offset:20480
	ds_read_b128 v[228:231], v166 offset:21504
	ds_read_b128 v[232:235], v166 offset:22528
	ds_read_b128 v[236:239], v166 offset:23552
	global_load_lds_dwordx4 v[240:241], off
	s_add_i32 m0, s66, 0x2000
	s_add_u32 s66, s36, 0x40000
	v_lshl_add_u64 v[242:243], s[36:37], 0, v[136:137]
	s_addc_u32 s67, s37, 0
	s_add_i32 s68, s64, s33
	global_load_lds_dwordx4 v[242:243], off
	v_lshl_add_u64 v[244:245], s[66:67], 0, v[132:133]
	s_mov_b32 m0, s68
	v_lshl_add_u64 v[246:247], s[38:39], 0, v[134:135]
	global_load_lds_dwordx4 v[244:245], off
	v_lshl_add_u64 v[244:245], s[66:67], 0, v[136:137]
	s_add_i32 m0, s68, 0x2000
	s_nop 0
	global_load_lds_dwordx4 v[244:245], off
	v_lshl_add_u64 v[244:245], s[38:39], 0, v[130:131]
	s_mov_b32 m0, s44
	s_nop 0
	global_load_lds_dwordx4 v[244:245], off
	s_mov_b32 m0, s45
	s_nop 0
	global_load_lds_dwordx4 v[246:247], off
	s_waitcnt vmcnt(8)
	s_waitcnt lgkmcnt(0)
	s_barrier
	s_waitcnt lgkmcnt(0)
	v_mfma_f32_16x16x32_bf16 v[62:65], v[160:163], v[208:211], v[62:65]
	v_mfma_f32_16x16x32_bf16 v[58:61], v[172:175], v[208:211], v[58:61]
	v_mfma_f32_16x16x32_bf16 v[46:49], v[160:163], v[216:219], v[46:49]
	v_mfma_f32_16x16x32_bf16 v[42:45], v[172:175], v[216:219], v[42:45]
	v_mfma_f32_16x16x32_bf16 v[30:33], v[160:163], v[224:227], v[30:33]
	v_mfma_f32_16x16x32_bf16 v[26:29], v[172:175], v[224:227], v[26:29]
	v_mfma_f32_16x16x32_bf16 v[14:17], v[160:163], v[232:235], v[14:17]
	v_mfma_f32_16x16x32_bf16 v[10:13], v[172:175], v[232:235], v[10:13]
	v_mfma_f32_16x16x32_bf16 v[62:65], v[168:171], v[212:215], v[62:65]
	v_mfma_f32_16x16x32_bf16 v[58:61], v[176:179], v[212:215], v[58:61]
	v_mfma_f32_16x16x32_bf16 v[46:49], v[168:171], v[220:223], v[46:49]
	v_mfma_f32_16x16x32_bf16 v[42:45], v[176:179], v[220:223], v[42:45]
	v_mfma_f32_16x16x32_bf16 v[30:33], v[168:171], v[228:231], v[30:33]
	v_mfma_f32_16x16x32_bf16 v[26:29], v[176:179], v[228:231], v[26:29]
	v_mfma_f32_16x16x32_bf16 v[14:17], v[168:171], v[236:239], v[14:17]
	v_mfma_f32_16x16x32_bf16 v[10:13], v[176:179], v[236:239], v[10:13]
	v_mfma_f32_16x16x32_bf16 v[54:57], v[180:183], v[208:211], v[54:57]
	v_mfma_f32_16x16x32_bf16 v[50:53], v[200:203], v[208:211], v[50:53]
	v_mfma_f32_16x16x32_bf16 v[38:41], v[180:183], v[216:219], v[38:41]
	v_mfma_f32_16x16x32_bf16 v[34:37], v[200:203], v[216:219], v[34:37]
	v_mfma_f32_16x16x32_bf16 v[22:25], v[180:183], v[224:227], v[22:25]
	v_mfma_f32_16x16x32_bf16 v[18:21], v[200:203], v[224:227], v[18:21]
	v_mfma_f32_16x16x32_bf16 v[6:9], v[180:183], v[232:235], v[6:9]
	v_mfma_f32_16x16x32_bf16 v[2:5], v[200:203], v[232:235], v[2:5]
	v_mfma_f32_16x16x32_bf16 v[54:57], v[196:199], v[212:215], v[54:57]
	v_mfma_f32_16x16x32_bf16 v[50:53], v[204:207], v[212:215], v[50:53]
	v_mfma_f32_16x16x32_bf16 v[38:41], v[196:199], v[220:223], v[38:41]
	v_mfma_f32_16x16x32_bf16 v[34:37], v[204:207], v[220:223], v[34:37]
	v_mfma_f32_16x16x32_bf16 v[22:25], v[196:199], v[228:231], v[22:25]
	v_mfma_f32_16x16x32_bf16 v[18:21], v[204:207], v[228:231], v[18:21]
	v_mfma_f32_16x16x32_bf16 v[6:9], v[196:199], v[236:239], v[6:9]
	v_mfma_f32_16x16x32_bf16 v[2:5], v[204:207], v[236:239], v[2:5]
	s_barrier
; #define PG8_STAGE(bufoff, gbase, voff) do { _Pragma("unroll") for (int _i = 0; _i < 2; ++_i) \
;         __builtin_amdgcn_global_load_lds((const unsigned*)((const char*)(gbase) + (voff)[_i]), (PG8_LAS unsigned*)(lds + (bufoff) + ldsw + _i * 8192), 16, 0, 0); } while (0)
; #define PG8_LDA(dst, b, h) do { _Pragma("unroll") for (int m = 0; m < 4; ++m) _Pragma("unroll") for (int k = 0; k < 2; ++k) dst[m][k] = *(const PG8_LAS bf16x8*)(lds + PG8_SA(b, h) + aoff + m * 2048 + k * 1024); } while (0)
; #define PG8_LDB(dst, b, h) do { _Pragma("unroll") for (int n = 0; n < 2; ++n) _Pragma("unroll") for (int k = 0; k < 2; ++k) dst[n][k] = *(const PG8_LAS bf16x8*)(lds + PG8_SB(b, h) + boff + n * 2048 + k * 1024); } while (0)
; #define PG8_MMA(ai, bj, At, Bt) do { __builtin_amdgcn_s_setprio(1); _Pragma("unroll") for (int m = 0; m < 4; ++m) _Pragma("unroll") for (int n = 0; n < 2; ++n) _Pragma("unroll") for (int k = 0; k < 2; ++k) \
;         acc[ai][bj][m][n] = __builtin_amdgcn_mfma_f32_16x16x32_bf16(Bt[n][k], At[m][k], acc[ai][bj][m][n], 0, 0, 0); __builtin_amdgcn_s_setprio(0); } while (0)
; #define PG8_WAIT_V(n) asm volatile("s_waitcnt vmcnt(" #n ")" ::: "memory")
; #define PG8_WAIT_L(n) asm volatile("s_waitcnt lgkmcnt(" #n ")" ::: "memory")
; #define PG8_BAR __builtin_amdgcn_s_barrier()
; #define PG8_SCHED __builtin_amdgcn_sched_barrier(0)
; template <class Epi, class Sched, bool ALIGN_EPI = false, bool SP2 = false>
; __device__ __forceinline__ void gemm_phase(PG8_LAS unsigned char* lds, const Gemm g, const Sched& S, const Epi& E) {
;     ...
;             PG8_LDB(B0, 1, 0); PG8_LDB(B1, 1, 1); PG8_SCHED; PG8_LDA(At, 1, 0); PG8_STAGE(PG8_SA(0, 1), a2 + hstepA, voffA);
;             PG8_WAIT_V(8); PG8_WAIT_L(0); PG8_BAR; PG8_MMA(0, 0, At, B0); PG8_MMA(0, 1, At, B1); PG8_BAR; PG8_SCHED;
	s_add_i32 s66, 0, 0x18000
	v_add_u32_e32 v167, s66, v155
	s_add_i32 s67, 0, 0x1c000
	ds_read_b128 v[160:163], v167
	ds_read_b128 v[168:171], v167 offset:1024
	ds_read_b128 v[172:175], v167 offset:2048
	ds_read_b128 v[176:179], v167 offset:3072
	v_add_u32_e32 v167, s67, v155
	ds_read_b128 v[180:183], v167
	ds_read_b128 v[196:199], v167 offset:1024
	ds_read_b128 v[200:203], v167 offset:2048
	ds_read_b128 v[204:207], v167 offset:3072
	s_add_u32 s38, s38, 0x40000
	s_addc_u32 s39, s39, 0
	s_mov_b32 m0, s46
	v_lshl_add_u64 v[248:249], s[38:39], 0, v[130:131]
	ds_read_b128 v[208:211], v166 offset:32768
	ds_read_b128 v[212:215], v166 offset:33792
	ds_read_b128 v[216:219], v166 offset:34816
	ds_read_b128 v[220:223], v166 offset:35840
	ds_read_b128 v[224:227], v166 offset:36864
	ds_read_b128 v[228:231], v166 offset:37888
	ds_read_b128 v[232:235], v166 offset:38912
	ds_read_b128 v[236:239], v166 offset:39936
	global_load_lds_dwordx4 v[248:249], off
	v_lshl_add_u64 v[248:249], s[38:39], 0, v[134:135]
	s_mov_b32 m0, s47
	s_nop 0
	global_load_lds_dwordx4 v[248:249], off
	s_waitcnt vmcnt(8)
	s_waitcnt lgkmcnt(0)
	s_barrier
	s_waitcnt lgkmcnt(0)
	v_mfma_f32_16x16x32_bf16 v[126:129], v[160:163], v[208:211], v[126:129]
	v_mfma_f32_16x16x32_bf16 v[122:125], v[172:175], v[208:211], v[122:125]
	v_mfma_f32_16x16x32_bf16 v[110:113], v[160:163], v[216:219], v[110:113]
	v_mfma_f32_16x16x32_bf16 v[106:109], v[172:175], v[216:219], v[106:109]
	v_mfma_f32_16x16x32_bf16 v[94:97], v[160:163], v[224:227], v[94:97]
	v_mfma_f32_16x16x32_bf16 v[90:93], v[172:175], v[224:227], v[90:93]
	v_mfma_f32_16x16x32_bf16 v[78:81], v[160:163], v[232:235], v[78:81]
	v_mfma_f32_16x16x32_bf16 v[74:77], v[172:175], v[232:235], v[74:77]
	v_mfma_f32_16x16x32_bf16 v[126:129], v[168:171], v[212:215], v[126:129]
	v_mfma_f32_16x16x32_bf16 v[122:125], v[176:179], v[212:215], v[122:125]
	v_mfma_f32_16x16x32_bf16 v[110:113], v[168:171], v[220:223], v[110:113]
	v_mfma_f32_16x16x32_bf16 v[106:109], v[176:179], v[220:223], v[106:109]
	v_mfma_f32_16x16x32_bf16 v[94:97], v[168:171], v[228:231], v[94:97]
	v_mfma_f32_16x16x32_bf16 v[90:93], v[176:179], v[228:231], v[90:93]
	v_mfma_f32_16x16x32_bf16 v[78:81], v[168:171], v[236:239], v[78:81]
	v_mfma_f32_16x16x32_bf16 v[74:77], v[176:179], v[236:239], v[74:77]
	v_mfma_f32_16x16x32_bf16 v[118:121], v[180:183], v[208:211], v[118:121]
	v_mfma_f32_16x16x32_bf16 v[114:117], v[200:203], v[208:211], v[114:117]
	v_mfma_f32_16x16x32_bf16 v[102:105], v[180:183], v[216:219], v[102:105]
	v_mfma_f32_16x16x32_bf16 v[98:101], v[200:203], v[216:219], v[98:101]
	v_mfma_f32_16x16x32_bf16 v[86:89], v[180:183], v[224:227], v[86:89]
	v_mfma_f32_16x16x32_bf16 v[82:85], v[200:203], v[224:227], v[82:85]
	v_mfma_f32_16x16x32_bf16 v[70:73], v[180:183], v[232:235], v[70:73]
	v_mfma_f32_16x16x32_bf16 v[66:69], v[200:203], v[232:235], v[66:69]
	v_mfma_f32_16x16x32_bf16 v[118:121], v[196:199], v[212:215], v[118:121]
	v_mfma_f32_16x16x32_bf16 v[114:117], v[204:207], v[212:215], v[114:117]
	v_mfma_f32_16x16x32_bf16 v[102:105], v[196:199], v[220:223], v[102:105]
	v_mfma_f32_16x16x32_bf16 v[98:101], v[204:207], v[220:223], v[98:101]
	v_mfma_f32_16x16x32_bf16 v[86:89], v[196:199], v[228:231], v[86:89]
	v_mfma_f32_16x16x32_bf16 v[82:85], v[204:207], v[228:231], v[82:85]
	v_mfma_f32_16x16x32_bf16 v[70:73], v[196:199], v[236:239], v[70:73]
	v_mfma_f32_16x16x32_bf16 v[66:69], v[204:207], v[236:239], v[66:69]
	s_barrier
; #define PG8_STAGE(bufoff, gbase, voff) do { _Pragma("unroll") for (int _i = 0; _i < 2; ++_i) \
;         __builtin_amdgcn_global_load_lds((const unsigned*)((const char*)(gbase) + (voff)[_i]), (PG8_LAS unsigned*)(lds + (bufoff) + ldsw + _i * 8192), 16, 0, 0); } while (0)
; #define PG8_LDA(dst, b, h) do { _Pragma("unroll") for (int m = 0; m < 4; ++m) _Pragma("unroll") for (int k = 0; k < 2; ++k) dst[m][k] = *(const PG8_LAS bf16x8*)(lds + PG8_SA(b, h) + aoff + m * 2048 + k * 1024); } while (0)
; #define PG8_MMA(ai, bj, At, Bt) do { __builtin_amdgcn_s_setprio(1); _Pragma("unroll") for (int m = 0; m < 4; ++m) _Pragma("unroll") for (int n = 0; n < 2; ++n) _Pragma("unroll") for (int k = 0; k < 2; ++k) \
;         acc[ai][bj][m][n] = __builtin_amdgcn_mfma_f32_16x16x32_bf16(Bt[n][k], At[m][k], acc[ai][bj][m][n], 0, 0, 0); __builtin_amdgcn_s_setprio(0); } while (0)
; #define PG8_WAIT_V(n) asm volatile("s_waitcnt vmcnt(" #n ")" ::: "memory")
; #define PG8_WAIT_L(n) asm volatile("s_waitcnt lgkmcnt(" #n ")" ::: "memory")
; #define PG8_BAR __builtin_amdgcn_s_barrier()
; #define PG8_SCHED __builtin_amdgcn_sched_barrier(0)
; template <class Epi, class Sched, bool ALIGN_EPI = false, bool SP2 = false>
; __device__ __forceinline__ void gemm_phase(PG8_LAS unsigned char* lds, const Gemm g, const Sched& S, const Epi& E) {
;     ...
;             PG8_LDA(At, 1, 1); PG8_STAGE(PG8_SB(1, 0), b3, voffB); PG8_STAGE(PG8_SB(1, 1), b3 + hstepB, voffB); PG8_STAGE(PG8_SA(1, 0), a3, voffA);
;             PG8_WAIT_V(8); PG8_WAIT_L(0); PG8_BAR; PG8_MMA(1, 0, At, B0); PG8_MMA(1, 1, At, B1); PG8_BAR; PG8_SCHED;
;     ...
;         if constexpr (ALIGN_EPI) { if (wr == 0) PG8_BAR; }
;         if constexpr (!Epi::AFTER_DRAIN) { E(acc, cur, wr, wc, fr, fq); S.done(cur); }
	s_add_i32 s38, s66, s33
	v_lshl_add_u64 v[240:241], v[240:241], 0, s[6:7]
	s_mov_b32 m0, s38
	ds_read_b128 v[208:211], v166 offset:49152
	ds_read_b128 v[212:215], v166 offset:50176
	ds_read_b128 v[216:219], v166 offset:51200
	ds_read_b128 v[220:223], v166 offset:52224
	ds_read_b128 v[224:227], v166 offset:53248
	ds_read_b128 v[228:231], v166 offset:54272
	ds_read_b128 v[232:235], v166 offset:55296
	ds_read_b128 v[236:239], v166 offset:56320
	global_load_lds_dwordx4 v[240:241], off
	s_add_i32 m0, s38, 0x2000
	s_add_u32 s36, s36, 0x40080
	v_lshl_add_u64 v[240:241], v[242:243], 0, s[6:7]
	s_addc_u32 s37, s37, 0
	s_add_i32 s38, s67, s33
	global_load_lds_dwordx4 v[240:241], off
	v_lshl_add_u64 v[240:241], s[36:37], 0, v[132:133]
	s_mov_b32 m0, s38
	s_nop 0
	global_load_lds_dwordx4 v[240:241], off
	v_lshl_add_u64 v[240:241], s[36:37], 0, v[136:137]
	s_add_i32 m0, s38, 0x2000
	s_nop 0
	global_load_lds_dwordx4 v[240:241], off
	v_lshl_add_u64 v[240:241], v[244:245], 0, s[6:7]
	s_mov_b32 m0, s52
	s_nop 0
	global_load_lds_dwordx4 v[240:241], off
	v_lshl_add_u64 v[240:241], v[246:247], 0, s[6:7]
	s_mov_b32 m0, s53
	s_nop 0
	global_load_lds_dwordx4 v[240:241], off
	s_waitcnt vmcnt(8)
	s_waitcnt lgkmcnt(0)
	s_barrier
	s_waitcnt lgkmcnt(0)
	v_mfma_f32_16x16x32_bf16 v[62:65], v[160:163], v[208:211], v[62:65]
	v_mfma_f32_16x16x32_bf16 v[58:61], v[172:175], v[208:211], v[58:61]
	v_mfma_f32_16x16x32_bf16 v[46:49], v[160:163], v[216:219], v[46:49]
	v_mfma_f32_16x16x32_bf16 v[42:45], v[172:175], v[216:219], v[42:45]
	v_mfma_f32_16x16x32_bf16 v[30:33], v[160:163], v[224:227], v[30:33]
	v_mfma_f32_16x16x32_bf16 v[26:29], v[172:175], v[224:227], v[26:29]
	v_mfma_f32_16x16x32_bf16 v[14:17], v[160:163], v[232:235], v[14:17]
	v_mfma_f32_16x16x32_bf16 v[10:13], v[172:175], v[232:235], v[10:13]
	v_mfma_f32_16x16x32_bf16 v[62:65], v[168:171], v[212:215], v[62:65]
	v_mfma_f32_16x16x32_bf16 v[58:61], v[176:179], v[212:215], v[58:61]
	v_mfma_f32_16x16x32_bf16 v[46:49], v[168:171], v[220:223], v[46:49]
	v_mfma_f32_16x16x32_bf16 v[42:45], v[176:179], v[220:223], v[42:45]
	v_mfma_f32_16x16x32_bf16 v[30:33], v[168:171], v[228:231], v[30:33]
	v_mfma_f32_16x16x32_bf16 v[26:29], v[176:179], v[228:231], v[26:29]
	v_mfma_f32_16x16x32_bf16 v[14:17], v[168:171], v[236:239], v[14:17]
	v_mfma_f32_16x16x32_bf16 v[10:13], v[176:179], v[236:239], v[10:13]
	v_mfma_f32_16x16x32_bf16 v[54:57], v[180:183], v[208:211], v[54:57]
	v_mfma_f32_16x16x32_bf16 v[50:53], v[200:203], v[208:211], v[50:53]
	v_mfma_f32_16x16x32_bf16 v[38:41], v[180:183], v[216:219], v[38:41]
	v_mfma_f32_16x16x32_bf16 v[34:37], v[200:203], v[216:219], v[34:37]
	v_mfma_f32_16x16x32_bf16 v[22:25], v[180:183], v[224:227], v[22:25]
	v_mfma_f32_16x16x32_bf16 v[18:21], v[200:203], v[224:227], v[18:21]
	v_mfma_f32_16x16x32_bf16 v[6:9], v[180:183], v[232:235], v[6:9]
	v_mfma_f32_16x16x32_bf16 v[2:5], v[200:203], v[232:235], v[2:5]
	v_mfma_f32_16x16x32_bf16 v[54:57], v[196:199], v[212:215], v[54:57]
	v_mfma_f32_16x16x32_bf16 v[50:53], v[204:207], v[212:215], v[50:53]
	v_mfma_f32_16x16x32_bf16 v[38:41], v[196:199], v[220:223], v[38:41]
	v_mfma_f32_16x16x32_bf16 v[34:37], v[204:207], v[220:223], v[34:37]
	v_mfma_f32_16x16x32_bf16 v[22:25], v[196:199], v[228:231], v[22:25]
	v_mfma_f32_16x16x32_bf16 v[18:21], v[204:207], v[228:231], v[18:21]
	v_mfma_f32_16x16x32_bf16 v[6:9], v[196:199], v[236:239], v[6:9]
	v_mfma_f32_16x16x32_bf16 v[2:5], v[204:207], v[236:239], v[2:5]
	s_barrier
	s_add_i32 s43, s43, 2
	s_add_u32 s41, s41, 0x100
	s_addc_u32 s42, s42, 0
	s_add_u32 s34, s34, 0x100
	s_addc_u32 s35, s35, 0
	s_cmp_gt_u32 s43, 13
	s_cbranch_scc0 .LBB0_899
	s_setprio 0
	s_and_b64 vcc, exec, s[10:11]
	s_cbranch_vccz .LBB0_904
	s_barrier
	v_lshl_add_u32 v160, s2, 8, v1
	s_cmp_lg_u32 s30, 2
	s_mov_b64 s[34:35], -1
	s_cbranch_scc1 .LBB0_905

; #define PG8_STAGE(bufoff, gbase, voff) do { _Pragma("unroll") for (int _i = 0; _i < 2; ++_i) \
;         __builtin_amdgcn_global_load_lds((const unsigned*)((const char*)(gbase) + (voff)[_i]), (PG8_LAS unsigned*)(lds + (bufoff) + ldsw + _i * 8192), 16, 0, 0); } while (0)
; #define PG8_LDA(dst, b, h) do { _Pragma("unroll") for (int m = 0; m < 4; ++m) _Pragma("unroll") for (int k = 0; k < 2; ++k) dst[m][k] = *(const PG8_LAS bf16x8*)(lds + PG8_SA(b, h) + aoff + m * 2048 + k * 1024); } while (0)
; #define PG8_LDB(dst, b, h) do { _Pragma("unroll") for (int n = 0; n < 2; ++n) _Pragma("unroll") for (int k = 0; k < 2; ++k) dst[n][k] = *(const PG8_LAS bf16x8*)(lds + PG8_SB(b, h) + boff + n * 2048 + k * 1024); } while (0)
; #define PG8_SCHED __builtin_amdgcn_sched_barrier(0)
;     DI bool next(int i, pg8::Unit& u) const { if (i > 0 || !has) return false; u.pm = pm; u.pn = 0; return true; }
; template <class Epi, class Sched, bool ALIGN_EPI = false, bool SP2 = false>
; __device__ __forceinline__ void gemm_phase(PG8_LAS unsigned char* lds, const Gemm g, const Sched& S, const Epi& E) {
;     ...
;         const bool has_next = S.next(ui + 1, nxt);
;         const char* nA = has_next ? (const char*)g.A + (size_t)nxt.pm * tstepA : cA; const char* nB = has_next ? (const char*)g.Bt + (size_t)nxt.pn * tstepB : cB;
;         for (int t = 0; t < nt; t += 2) {
;             const bool last = (t == nt - 2);
;             const char* a1 = cA + (size_t)(t + 1) * kstep;
;             const char* a2 = last ? nA : cA + (size_t)(t + 2) * kstep; const char* b2 = last ? nB : cB + (size_t)(t + 2) * kstep;
;             const char* a3 = a2 + kstep; const char* b3 = b2 + kstep;
;             if (last && has_next) S.a_ready(nxt);
;             if constexpr (SP2) {
;             PG8_LDB(B0, 0, 0); PG8_LDB(B1, 0, 1); PG8_SCHED; PG8_LDA(At, 0, 0); PG8_STAGE(PG8_SA(1, 1), a1 + hstepA, voffA);
;     ...
; #pragma unroll
;         for (int a = 0; a < 2; ++a)
; #pragma unroll
;             for (int b = 0; b < 2; ++b)
; #pragma unroll
;                 for (int m = 0; m < 4; ++m)
; #pragma unroll
;                     for (int n = 0; n < 2; ++n) acc[a][b][m][n] = (f32x4){0.f, 0.f, 0.f, 0.f};
;         cur = nxt; cA = nA; cB = nB; ++ui;
.LBB0_1285:
	s_ashr_i32 s23, s22, 31
	s_lshl_b64 s[16:17], s[22:23], 18
	s_add_u32 s24, s35, s16
	s_addc_u32 s25, s36, s17
	s_and_b64 s[16:17], s[8:9], exec
	s_cselect_b32 s23, s25, s15
	s_cselect_b32 s46, s24, s14
	s_ashr_i32 s21, s20, 31
	s_lshl_b64 s[16:17], s[20:21], 18
	s_add_u32 s26, s37, s16
	s_addc_u32 s27, s38, s17
	s_and_b64 s[16:17], s[8:9], exec
	s_cselect_b32 s21, s27, s13
	s_cselect_b32 s47, s26, s12
	s_add_u32 s48, s12, 0x100
	s_addc_u32 s49, s13, 0
	s_add_u32 s12, s14, 0x20080
	v_mov_b32_e32 v2, 0
	s_addc_u32 s13, s15, 0
	s_mov_b32 s50, -2
	v_mov_b32_e32 v3, v2
	v_mov_b32_e32 v4, v2
	v_mov_b32_e32 v5, v2
	v_mov_b32_e32 v6, v2
	v_mov_b32_e32 v7, v2
	v_mov_b32_e32 v8, v2
	v_mov_b32_e32 v9, v2
	v_mov_b32_e32 v18, v2
	v_mov_b32_e32 v19, v2
	v_mov_b32_e32 v20, v2
	v_mov_b32_e32 v21, v2
	v_mov_b32_e32 v30, v2
	v_mov_b32_e32 v31, v2
	v_mov_b32_e32 v32, v2
	v_mov_b32_e32 v33, v2
	v_mov_b32_e32 v42, v2
	v_mov_b32_e32 v43, v2
	v_mov_b32_e32 v44, v2
	v_mov_b32_e32 v45, v2
	v_mov_b32_e32 v46, v2
	v_mov_b32_e32 v47, v2
	v_mov_b32_e32 v48, v2
	v_mov_b32_e32 v49, v2
	v_mov_b32_e32 v50, v2
	v_mov_b32_e32 v51, v2
	v_mov_b32_e32 v52, v2
	v_mov_b32_e32 v53, v2
	v_mov_b32_e32 v54, v2
	v_mov_b32_e32 v55, v2
	v_mov_b32_e32 v56, v2
	v_mov_b32_e32 v57, v2
	v_mov_b32_e32 v10, v2
	v_mov_b32_e32 v11, v2
	v_mov_b32_e32 v12, v2
	v_mov_b32_e32 v13, v2
	v_mov_b32_e32 v14, v2
	v_mov_b32_e32 v15, v2
	v_mov_b32_e32 v16, v2
	v_mov_b32_e32 v17, v2
	v_mov_b32_e32 v82, v2
	v_mov_b32_e32 v83, v2
	v_mov_b32_e32 v84, v2
	v_mov_b32_e32 v85, v2
	v_mov_b32_e32 v86, v2
	v_mov_b32_e32 v87, v2
	v_mov_b32_e32 v88, v2
	v_mov_b32_e32 v89, v2
	v_mov_b32_e32 v90, v2
	v_mov_b32_e32 v91, v2
	v_mov_b32_e32 v92, v2
	v_mov_b32_e32 v93, v2
	v_mov_b32_e32 v94, v2
	v_mov_b32_e32 v95, v2
	v_mov_b32_e32 v96, v2
	v_mov_b32_e32 v97, v2
	v_mov_b32_e32 v98, v2
	v_mov_b32_e32 v99, v2
	v_mov_b32_e32 v100, v2
	v_mov_b32_e32 v101, v2
	v_mov_b32_e32 v102, v2
	v_mov_b32_e32 v103, v2
	v_mov_b32_e32 v104, v2
	v_mov_b32_e32 v105, v2
	v_mov_b32_e32 v58, v2
	v_mov_b32_e32 v59, v2
	v_mov_b32_e32 v60, v2
	v_mov_b32_e32 v61, v2
	v_mov_b32_e32 v62, v2
	v_mov_b32_e32 v63, v2
	v_mov_b32_e32 v64, v2
	v_mov_b32_e32 v65, v2
	v_mov_b32_e32 v66, v2
	v_mov_b32_e32 v67, v2
	v_mov_b32_e32 v68, v2
	v_mov_b32_e32 v69, v2
	v_mov_b32_e32 v70, v2
	v_mov_b32_e32 v71, v2
	v_mov_b32_e32 v72, v2
	v_mov_b32_e32 v73, v2
	v_mov_b32_e32 v74, v2
	v_mov_b32_e32 v75, v2
	v_mov_b32_e32 v76, v2
	v_mov_b32_e32 v77, v2
	v_mov_b32_e32 v78, v2
	v_mov_b32_e32 v79, v2
	v_mov_b32_e32 v80, v2
	v_mov_b32_e32 v81, v2
	v_mov_b32_e32 v22, v2
	v_mov_b32_e32 v23, v2
	v_mov_b32_e32 v24, v2
	v_mov_b32_e32 v25, v2
	v_mov_b32_e32 v26, v2
	v_mov_b32_e32 v27, v2
	v_mov_b32_e32 v28, v2
	v_mov_b32_e32 v29, v2
	v_mov_b32_e32 v106, v2
	v_mov_b32_e32 v107, v2
	v_mov_b32_e32 v108, v2
	v_mov_b32_e32 v109, v2
	v_mov_b32_e32 v110, v2
	v_mov_b32_e32 v111, v2
	v_mov_b32_e32 v112, v2
	v_mov_b32_e32 v113, v2
	v_mov_b32_e32 v114, v2
	v_mov_b32_e32 v115, v2
	v_mov_b32_e32 v116, v2
	v_mov_b32_e32 v117, v2
	v_mov_b32_e32 v118, v2
	v_mov_b32_e32 v119, v2
	v_mov_b32_e32 v120, v2
	v_mov_b32_e32 v121, v2
	v_mov_b32_e32 v122, v2
	v_mov_b32_e32 v123, v2
	v_mov_b32_e32 v124, v2
	v_mov_b32_e32 v125, v2
	v_mov_b32_e32 v126, v2
	v_mov_b32_e32 v127, v2
	v_mov_b32_e32 v128, v2
	v_mov_b32_e32 v129, v2
	v_mov_b32_e32 v34, v2
	v_mov_b32_e32 v35, v2
	v_mov_b32_e32 v36, v2
	v_mov_b32_e32 v37, v2
	v_mov_b32_e32 v38, v2
	v_mov_b32_e32 v39, v2
	v_mov_b32_e32 v40, v2
	v_mov_b32_e32 v41, v2
	v_readlane_b32 s98, v250, 4
	s_cmp_lt_u32 s98, 4
	s_cbranch_scc1 .Lgp_6
	s_setprio 1
.Lgp_6:
.LBB0_1286:
	ds_read_b128 v[130:133], v179
	ds_read_b128 v[134:137], v179 offset:1024
	ds_read_b128 v[138:141], v179 offset:2048
	ds_read_b128 v[162:165], v179 offset:3072
	ds_read_b128 v[166:169], v180
	ds_read_b128 v[170:173], v180 offset:1024
	ds_read_b128 v[174:177], v180 offset:2048
	ds_read_b128 v[186:189], v180 offset:3072
	s_add_u32 s14, s12, 0xfffe0080
	s_addc_u32 s15, s13, -1
	s_cmp_eq_u32 s50, 4
	s_cselect_b32 s17, s23, s15
	s_cselect_b32 s16, s46, s14
	s_cselect_b32 s15, s21, s49
	s_cselect_b32 s14, s47, s48
	v_lshl_add_u64 v[182:183], s[12:13], 0, v[156:157]
	s_add_i32 m0, s30, 0xc000
	ds_read_b128 v[190:193], v181
	ds_read_b128 v[194:197], v181 offset:1024
	ds_read_b128 v[198:201], v181 offset:2048
	ds_read_b128 v[202:205], v181 offset:3072
	ds_read_b128 v[206:209], v181 offset:4096
	ds_read_b128 v[210:213], v181 offset:5120
	ds_read_b128 v[214:217], v181 offset:6144
	ds_read_b128 v[218:221], v181 offset:7168
	global_load_lds_dwordx4 v[182:183], off
	v_lshl_add_u64 v[182:183], s[12:13], 0, v[152:153]
	s_add_i32 m0, s30, 0xe000
	s_nop 0
	global_load_lds_dwordx4 v[182:183], off
	s_waitcnt vmcnt(8)
	s_waitcnt lgkmcnt(0)
	s_barrier
; #define PG8_STAGE(bufoff, gbase, voff) do { _Pragma("unroll") for (int _i = 0; _i < 2; ++_i) \
;         __builtin_amdgcn_global_load_lds((const unsigned*)((const char*)(gbase) + (voff)[_i]), (PG8_LAS unsigned*)(lds + (bufoff) + ldsw + _i * 8192), 16, 0, 0); } while (0)
; #define PG8_LDA(dst, b, h) do { _Pragma("unroll") for (int m = 0; m < 4; ++m) _Pragma("unroll") for (int k = 0; k < 2; ++k) dst[m][k] = *(const PG8_LAS bf16x8*)(lds + PG8_SA(b, h) + aoff + m * 2048 + k * 1024); } while (0)
; #define PG8_MMA(ai, bj, At, Bt) do { __builtin_amdgcn_s_setprio(1); _Pragma("unroll") for (int m = 0; m < 4; ++m) _Pragma("unroll") for (int n = 0; n < 2; ++n) _Pragma("unroll") for (int k = 0; k < 2; ++k) \
;         acc[ai][bj][m][n] = __builtin_amdgcn_mfma_f32_16x16x32_bf16(Bt[n][k], At[m][k], acc[ai][bj][m][n], 0, 0, 0); __builtin_amdgcn_s_setprio(0); } while (0)
; #define PG8_WAIT_V(n) asm volatile("s_waitcnt vmcnt(" #n ")" ::: "memory")
; #define PG8_WAIT_L(n) asm volatile("s_waitcnt lgkmcnt(" #n ")" ::: "memory")
; #define PG8_BAR __builtin_amdgcn_s_barrier()
; #define PG8_SCHED __builtin_amdgcn_sched_barrier(0)
; template <class Epi, class Sched, bool ALIGN_EPI = false, bool SP2 = false>
; __device__ __forceinline__ void gemm_phase(PG8_LAS unsigned char* lds, const Gemm g, const Sched& S, const Epi& E) {
;     ...
;             PG8_WAIT_V(8); PG8_WAIT_L(0); PG8_BAR; PG8_MMA(0, 0, At, B0); PG8_MMA(0, 1, At, B1); PG8_BAR; PG8_SCHED;
;             PG8_LDA(At, 0, 1); PG8_STAGE(PG8_SB(0, 0), b2, voffB); PG8_STAGE(PG8_SB(0, 1), b2 + hstepB, voffB); PG8_STAGE(PG8_SA(0, 0), a2, voffA);
;             PG8_WAIT_V(8); PG8_WAIT_L(0); PG8_BAR; PG8_MMA(1, 0, At, B0); PG8_MMA(1, 1, At, B1); PG8_BAR; PG8_SCHED;
	s_waitcnt lgkmcnt(0)
	v_mfma_f32_16x16x32_bf16 v[38:41], v[130:133], v[190:193], v[38:41]
	v_mfma_f32_16x16x32_bf16 v[34:37], v[138:141], v[190:193], v[34:37]
	v_mfma_f32_16x16x32_bf16 v[126:129], v[130:133], v[198:201], v[126:129]
	v_mfma_f32_16x16x32_bf16 v[122:125], v[138:141], v[198:201], v[122:125]
	v_mfma_f32_16x16x32_bf16 v[118:121], v[130:133], v[206:209], v[118:121]
	v_mfma_f32_16x16x32_bf16 v[114:117], v[138:141], v[206:209], v[114:117]
	v_mfma_f32_16x16x32_bf16 v[110:113], v[130:133], v[214:217], v[110:113]
	v_mfma_f32_16x16x32_bf16 v[106:109], v[138:141], v[214:217], v[106:109]
	v_mfma_f32_16x16x32_bf16 v[38:41], v[134:137], v[194:197], v[38:41]
	v_mfma_f32_16x16x32_bf16 v[34:37], v[162:165], v[194:197], v[34:37]
	v_mfma_f32_16x16x32_bf16 v[126:129], v[134:137], v[202:205], v[126:129]
	v_mfma_f32_16x16x32_bf16 v[122:125], v[162:165], v[202:205], v[122:125]
	v_mfma_f32_16x16x32_bf16 v[118:121], v[134:137], v[210:213], v[118:121]
	v_mfma_f32_16x16x32_bf16 v[114:117], v[162:165], v[210:213], v[114:117]
	v_mfma_f32_16x16x32_bf16 v[110:113], v[134:137], v[218:221], v[110:113]
	v_mfma_f32_16x16x32_bf16 v[106:109], v[162:165], v[218:221], v[106:109]
	v_mfma_f32_16x16x32_bf16 v[26:29], v[166:169], v[190:193], v[26:29]
	v_mfma_f32_16x16x32_bf16 v[22:25], v[174:177], v[190:193], v[22:25]
	v_mfma_f32_16x16x32_bf16 v[78:81], v[166:169], v[198:201], v[78:81]
	v_mfma_f32_16x16x32_bf16 v[74:77], v[174:177], v[198:201], v[74:77]
	v_mfma_f32_16x16x32_bf16 v[70:73], v[166:169], v[206:209], v[70:73]
	v_mfma_f32_16x16x32_bf16 v[66:69], v[174:177], v[206:209], v[66:69]
	v_mfma_f32_16x16x32_bf16 v[62:65], v[166:169], v[214:217], v[62:65]
	v_mfma_f32_16x16x32_bf16 v[58:61], v[174:177], v[214:217], v[58:61]
	v_mfma_f32_16x16x32_bf16 v[26:29], v[170:173], v[194:197], v[26:29]
	v_mfma_f32_16x16x32_bf16 v[22:25], v[186:189], v[194:197], v[22:25]
	v_mfma_f32_16x16x32_bf16 v[78:81], v[170:173], v[202:205], v[78:81]
	v_mfma_f32_16x16x32_bf16 v[74:77], v[186:189], v[202:205], v[74:77]
	v_mfma_f32_16x16x32_bf16 v[70:73], v[170:173], v[210:213], v[70:73]
	v_mfma_f32_16x16x32_bf16 v[66:69], v[186:189], v[210:213], v[66:69]
	v_mfma_f32_16x16x32_bf16 v[62:65], v[170:173], v[218:221], v[62:65]
	v_mfma_f32_16x16x32_bf16 v[58:61], v[186:189], v[218:221], v[58:61]
	s_barrier
	s_add_i32 s51, s44, s29
	v_lshl_add_u64 v[182:183], s[14:15], 0, v[144:145]
	s_mov_b32 m0, s51
	ds_read_b128 v[190:193], v181 offset:16384
	ds_read_b128 v[194:197], v181 offset:17408
	ds_read_b128 v[198:201], v181 offset:18432
	ds_read_b128 v[202:205], v181 offset:19456
	ds_read_b128 v[206:209], v181 offset:20480
	ds_read_b128 v[210:213], v181 offset:21504
	ds_read_b128 v[214:217], v181 offset:22528
	ds_read_b128 v[218:221], v181 offset:23552
	global_load_lds_dwordx4 v[182:183], off
	s_add_i32 m0, s51, 0x2000
	s_add_u32 s52, s14, 0x20000
	v_lshl_add_u64 v[222:223], s[14:15], 0, v[148:149]
	s_addc_u32 s53, s15, 0
	s_add_i32 s51, s45, s29
	global_load_lds_dwordx4 v[222:223], off
	v_lshl_add_u64 v[224:225], s[52:53], 0, v[144:145]
	s_mov_b32 m0, s51
	v_lshl_add_u64 v[226:227], s[16:17], 0, v[146:147]
	global_load_lds_dwordx4 v[224:225], off
	v_lshl_add_u64 v[224:225], s[52:53], 0, v[148:149]
	s_add_i32 m0, s51, 0x2000
	s_nop 0
	global_load_lds_dwordx4 v[224:225], off
	v_lshl_add_u64 v[224:225], s[16:17], 0, v[142:143]
	s_mov_b32 m0, s30
	s_nop 0
	global_load_lds_dwordx4 v[224:225], off
	s_mov_b32 m0, s31
	s_nop 0
	global_load_lds_dwordx4 v[226:227], off
	s_waitcnt vmcnt(8)
	s_waitcnt lgkmcnt(0)
	s_barrier
	s_waitcnt lgkmcnt(0)
	v_mfma_f32_16x16x32_bf16 v[102:105], v[130:133], v[190:193], v[102:105]
	v_mfma_f32_16x16x32_bf16 v[98:101], v[138:141], v[190:193], v[98:101]
	v_mfma_f32_16x16x32_bf16 v[94:97], v[130:133], v[198:201], v[94:97]
	v_mfma_f32_16x16x32_bf16 v[90:93], v[138:141], v[198:201], v[90:93]
	v_mfma_f32_16x16x32_bf16 v[86:89], v[130:133], v[206:209], v[86:89]
	v_mfma_f32_16x16x32_bf16 v[82:85], v[138:141], v[206:209], v[82:85]
	v_mfma_f32_16x16x32_bf16 v[14:17], v[130:133], v[214:217], v[14:17]
	v_mfma_f32_16x16x32_bf16 v[10:13], v[138:141], v[214:217], v[10:13]
	v_mfma_f32_16x16x32_bf16 v[102:105], v[134:137], v[194:197], v[102:105]
	v_mfma_f32_16x16x32_bf16 v[98:101], v[162:165], v[194:197], v[98:101]
	v_mfma_f32_16x16x32_bf16 v[94:97], v[134:137], v[202:205], v[94:97]
	v_mfma_f32_16x16x32_bf16 v[90:93], v[162:165], v[202:205], v[90:93]
	v_mfma_f32_16x16x32_bf16 v[86:89], v[134:137], v[210:213], v[86:89]
	v_mfma_f32_16x16x32_bf16 v[82:85], v[162:165], v[210:213], v[82:85]
	v_mfma_f32_16x16x32_bf16 v[14:17], v[134:137], v[218:221], v[14:17]
	v_mfma_f32_16x16x32_bf16 v[10:13], v[162:165], v[218:221], v[10:13]
	v_mfma_f32_16x16x32_bf16 v[54:57], v[166:169], v[190:193], v[54:57]
	v_mfma_f32_16x16x32_bf16 v[50:53], v[174:177], v[190:193], v[50:53]
	v_mfma_f32_16x16x32_bf16 v[46:49], v[166:169], v[198:201], v[46:49]
	v_mfma_f32_16x16x32_bf16 v[42:45], v[174:177], v[198:201], v[42:45]
	v_mfma_f32_16x16x32_bf16 v[30:33], v[166:169], v[206:209], v[30:33]
	v_mfma_f32_16x16x32_bf16 v[18:21], v[174:177], v[206:209], v[18:21]
	v_mfma_f32_16x16x32_bf16 v[6:9], v[166:169], v[214:217], v[6:9]
	v_mfma_f32_16x16x32_bf16 v[2:5], v[174:177], v[214:217], v[2:5]
	v_mfma_f32_16x16x32_bf16 v[54:57], v[170:173], v[194:197], v[54:57]
	v_mfma_f32_16x16x32_bf16 v[50:53], v[186:189], v[194:197], v[50:53]
	v_mfma_f32_16x16x32_bf16 v[46:49], v[170:173], v[202:205], v[46:49]
	v_mfma_f32_16x16x32_bf16 v[42:45], v[186:189], v[202:205], v[42:45]
	v_mfma_f32_16x16x32_bf16 v[30:33], v[170:173], v[210:213], v[30:33]
	v_mfma_f32_16x16x32_bf16 v[18:21], v[186:189], v[210:213], v[18:21]
	v_mfma_f32_16x16x32_bf16 v[6:9], v[170:173], v[218:221], v[6:9]
	v_mfma_f32_16x16x32_bf16 v[2:5], v[186:189], v[218:221], v[2:5]
	s_barrier
; #define PG8_STAGE(bufoff, gbase, voff) do { _Pragma("unroll") for (int _i = 0; _i < 2; ++_i) \
;         __builtin_amdgcn_global_load_lds((const unsigned*)((const char*)(gbase) + (voff)[_i]), (PG8_LAS unsigned*)(lds + (bufoff) + ldsw + _i * 8192), 16, 0, 0); } while (0)
; #define PG8_LDA(dst, b, h) do { _Pragma("unroll") for (int m = 0; m < 4; ++m) _Pragma("unroll") for (int k = 0; k < 2; ++k) dst[m][k] = *(const PG8_LAS bf16x8*)(lds + PG8_SA(b, h) + aoff + m * 2048 + k * 1024); } while (0)
; #define PG8_LDB(dst, b, h) do { _Pragma("unroll") for (int n = 0; n < 2; ++n) _Pragma("unroll") for (int k = 0; k < 2; ++k) dst[n][k] = *(const PG8_LAS bf16x8*)(lds + PG8_SB(b, h) + boff + n * 2048 + k * 1024); } while (0)
; #define PG8_MMA(ai, bj, At, Bt) do { __builtin_amdgcn_s_setprio(1); _Pragma("unroll") for (int m = 0; m < 4; ++m) _Pragma("unroll") for (int n = 0; n < 2; ++n) _Pragma("unroll") for (int k = 0; k < 2; ++k) \
;         acc[ai][bj][m][n] = __builtin_amdgcn_mfma_f32_16x16x32_bf16(Bt[n][k], At[m][k], acc[ai][bj][m][n], 0, 0, 0); __builtin_amdgcn_s_setprio(0); } while (0)
; #define PG8_WAIT_V(n) asm volatile("s_waitcnt vmcnt(" #n ")" ::: "memory")
; #define PG8_WAIT_L(n) asm volatile("s_waitcnt lgkmcnt(" #n ")" ::: "memory")
; #define PG8_BAR __builtin_amdgcn_s_barrier()
; #define PG8_SCHED __builtin_amdgcn_sched_barrier(0)
; template <class Epi, class Sched, bool ALIGN_EPI = false, bool SP2 = false>
; __device__ __forceinline__ void gemm_phase(PG8_LAS unsigned char* lds, const Gemm g, const Sched& S, const Epi& E) {
;     ...
;             PG8_LDB(B0, 1, 0); PG8_LDB(B1, 1, 1); PG8_SCHED; PG8_LDA(At, 1, 0); PG8_STAGE(PG8_SA(0, 1), a2 + hstepA, voffA);
;             PG8_WAIT_V(8); PG8_WAIT_L(0); PG8_BAR; PG8_MMA(0, 0, At, B0); PG8_MMA(0, 1, At, B1); PG8_BAR; PG8_SCHED;
	s_add_i32 s51, 0, 0x18000
	s_add_i32 s52, 0, 0x1c000
	v_add_u32_e32 v162, s51, v155
	v_add_u32_e32 v185, s52, v155
	ds_read_b128 v[130:133], v162
	ds_read_b128 v[134:137], v162 offset:1024
	ds_read_b128 v[138:141], v162 offset:2048
	ds_read_b128 v[162:165], v162 offset:3072
	ds_read_b128 v[166:169], v185
	ds_read_b128 v[170:173], v185 offset:1024
	ds_read_b128 v[174:177], v185 offset:2048
	ds_read_b128 v[186:189], v185 offset:3072
	s_add_u32 s16, s16, 0x20000
	s_addc_u32 s17, s17, 0
	s_mov_b32 m0, s33
	v_lshl_add_u64 v[228:229], s[16:17], 0, v[142:143]
	ds_read_b128 v[190:193], v181 offset:32768
	ds_read_b128 v[194:197], v181 offset:33792
	ds_read_b128 v[198:201], v181 offset:34816
	ds_read_b128 v[202:205], v181 offset:35840
	ds_read_b128 v[206:209], v181 offset:36864
	ds_read_b128 v[210:213], v181 offset:37888
	ds_read_b128 v[214:217], v181 offset:38912
	ds_read_b128 v[218:221], v181 offset:39936
	global_load_lds_dwordx4 v[228:229], off
	v_lshl_add_u64 v[228:229], s[16:17], 0, v[146:147]
	s_mov_b32 m0, s34
	s_nop 0
	global_load_lds_dwordx4 v[228:229], off
	s_waitcnt vmcnt(8)
	s_waitcnt lgkmcnt(0)
	s_barrier
	s_waitcnt lgkmcnt(0)
	v_mfma_f32_16x16x32_bf16 v[38:41], v[130:133], v[190:193], v[38:41]
	v_mfma_f32_16x16x32_bf16 v[34:37], v[138:141], v[190:193], v[34:37]
	v_mfma_f32_16x16x32_bf16 v[126:129], v[130:133], v[198:201], v[126:129]
	v_mfma_f32_16x16x32_bf16 v[122:125], v[138:141], v[198:201], v[122:125]
	v_mfma_f32_16x16x32_bf16 v[118:121], v[130:133], v[206:209], v[118:121]
	v_mfma_f32_16x16x32_bf16 v[114:117], v[138:141], v[206:209], v[114:117]
	v_mfma_f32_16x16x32_bf16 v[110:113], v[130:133], v[214:217], v[110:113]
	v_mfma_f32_16x16x32_bf16 v[106:109], v[138:141], v[214:217], v[106:109]
	v_mfma_f32_16x16x32_bf16 v[38:41], v[134:137], v[194:197], v[38:41]
	v_mfma_f32_16x16x32_bf16 v[34:37], v[162:165], v[194:197], v[34:37]
	v_mfma_f32_16x16x32_bf16 v[126:129], v[134:137], v[202:205], v[126:129]
	v_mfma_f32_16x16x32_bf16 v[122:125], v[162:165], v[202:205], v[122:125]
	v_mfma_f32_16x16x32_bf16 v[118:121], v[134:137], v[210:213], v[118:121]
	v_mfma_f32_16x16x32_bf16 v[114:117], v[162:165], v[210:213], v[114:117]
	v_mfma_f32_16x16x32_bf16 v[110:113], v[134:137], v[218:221], v[110:113]
	v_mfma_f32_16x16x32_bf16 v[106:109], v[162:165], v[218:221], v[106:109]
	v_mfma_f32_16x16x32_bf16 v[26:29], v[166:169], v[190:193], v[26:29]
	v_mfma_f32_16x16x32_bf16 v[22:25], v[174:177], v[190:193], v[22:25]
	v_mfma_f32_16x16x32_bf16 v[78:81], v[166:169], v[198:201], v[78:81]
	v_mfma_f32_16x16x32_bf16 v[74:77], v[174:177], v[198:201], v[74:77]
	v_mfma_f32_16x16x32_bf16 v[70:73], v[166:169], v[206:209], v[70:73]
	v_mfma_f32_16x16x32_bf16 v[66:69], v[174:177], v[206:209], v[66:69]
	v_mfma_f32_16x16x32_bf16 v[62:65], v[166:169], v[214:217], v[62:65]
	v_mfma_f32_16x16x32_bf16 v[58:61], v[174:177], v[214:217], v[58:61]
	v_mfma_f32_16x16x32_bf16 v[26:29], v[170:173], v[194:197], v[26:29]
	v_mfma_f32_16x16x32_bf16 v[22:25], v[186:189], v[194:197], v[22:25]
	v_mfma_f32_16x16x32_bf16 v[78:81], v[170:173], v[202:205], v[78:81]
	v_mfma_f32_16x16x32_bf16 v[74:77], v[186:189], v[202:205], v[74:77]
	v_mfma_f32_16x16x32_bf16 v[70:73], v[170:173], v[210:213], v[70:73]
	v_mfma_f32_16x16x32_bf16 v[66:69], v[186:189], v[210:213], v[66:69]
	v_mfma_f32_16x16x32_bf16 v[62:65], v[170:173], v[218:221], v[62:65]
	v_mfma_f32_16x16x32_bf16 v[58:61], v[186:189], v[218:221], v[58:61]
	s_barrier
; #define PG8_STAGE(bufoff, gbase, voff) do { _Pragma("unroll") for (int _i = 0; _i < 2; ++_i) \
;         __builtin_amdgcn_global_load_lds((const unsigned*)((const char*)(gbase) + (voff)[_i]), (PG8_LAS unsigned*)(lds + (bufoff) + ldsw + _i * 8192), 16, 0, 0); } while (0)
; #define PG8_LDA(dst, b, h) do { _Pragma("unroll") for (int m = 0; m < 4; ++m) _Pragma("unroll") for (int k = 0; k < 2; ++k) dst[m][k] = *(const PG8_LAS bf16x8*)(lds + PG8_SA(b, h) + aoff + m * 2048 + k * 1024); } while (0)
; #define PG8_MMA(ai, bj, At, Bt) do { __builtin_amdgcn_s_setprio(1); _Pragma("unroll") for (int m = 0; m < 4; ++m) _Pragma("unroll") for (int n = 0; n < 2; ++n) _Pragma("unroll") for (int k = 0; k < 2; ++k) \
;         acc[ai][bj][m][n] = __builtin_amdgcn_mfma_f32_16x16x32_bf16(Bt[n][k], At[m][k], acc[ai][bj][m][n], 0, 0, 0); __builtin_amdgcn_s_setprio(0); } while (0)
; #define PG8_WAIT_V(n) asm volatile("s_waitcnt vmcnt(" #n ")" ::: "memory")
; #define PG8_WAIT_L(n) asm volatile("s_waitcnt lgkmcnt(" #n ")" ::: "memory")
; #define PG8_BAR __builtin_amdgcn_s_barrier()
; #define PG8_SCHED __builtin_amdgcn_sched_barrier(0)
; template <class Epi, class Sched, bool ALIGN_EPI = false, bool SP2 = false>
; __device__ __forceinline__ void gemm_phase(PG8_LAS unsigned char* lds, const Gemm g, const Sched& S, const Epi& E) {
;     ...
;             PG8_LDA(At, 1, 1); PG8_STAGE(PG8_SB(1, 0), b3, voffB); PG8_STAGE(PG8_SB(1, 1), b3 + hstepB, voffB); PG8_STAGE(PG8_SA(1, 0), a3, voffA);
;             PG8_WAIT_V(8); PG8_WAIT_L(0); PG8_BAR; PG8_MMA(1, 0, At, B0); PG8_MMA(1, 1, At, B1); PG8_BAR; PG8_SCHED;
;     ...
;         if constexpr (ALIGN_EPI) { if (wr == 0) PG8_BAR; }
	s_add_i32 s16, s51, s29
	v_lshl_add_u64 v[182:183], v[182:183], 0, s[6:7]
	s_mov_b32 m0, s16
	ds_read_b128 v[190:193], v181 offset:49152
	ds_read_b128 v[194:197], v181 offset:50176
	ds_read_b128 v[198:201], v181 offset:51200
	ds_read_b128 v[202:205], v181 offset:52224
	ds_read_b128 v[206:209], v181 offset:53248
	ds_read_b128 v[210:213], v181 offset:54272
	ds_read_b128 v[214:217], v181 offset:55296
	ds_read_b128 v[218:221], v181 offset:56320
	global_load_lds_dwordx4 v[182:183], off
	s_add_i32 m0, s16, 0x2000
	s_add_u32 s14, s14, 0x20080
	v_lshl_add_u64 v[182:183], v[222:223], 0, s[6:7]
	s_addc_u32 s15, s15, 0
	s_add_i32 s16, s52, s29
	global_load_lds_dwordx4 v[182:183], off
	v_lshl_add_u64 v[182:183], s[14:15], 0, v[144:145]
	s_mov_b32 m0, s16
	s_nop 0
	global_load_lds_dwordx4 v[182:183], off
	v_lshl_add_u64 v[182:183], s[14:15], 0, v[148:149]
	s_add_i32 m0, s16, 0x2000
	s_nop 0
	global_load_lds_dwordx4 v[182:183], off
	v_lshl_add_u64 v[182:183], v[224:225], 0, s[6:7]
	s_mov_b32 m0, s40
	s_nop 0
	global_load_lds_dwordx4 v[182:183], off
	v_lshl_add_u64 v[182:183], v[226:227], 0, s[6:7]
	s_mov_b32 m0, s41
	s_nop 0
	global_load_lds_dwordx4 v[182:183], off
	s_waitcnt vmcnt(8)
	s_waitcnt lgkmcnt(0)
	s_barrier
	s_waitcnt lgkmcnt(0)
	v_mfma_f32_16x16x32_bf16 v[102:105], v[130:133], v[190:193], v[102:105]
	v_mfma_f32_16x16x32_bf16 v[98:101], v[138:141], v[190:193], v[98:101]
	v_mfma_f32_16x16x32_bf16 v[94:97], v[130:133], v[198:201], v[94:97]
	v_mfma_f32_16x16x32_bf16 v[90:93], v[138:141], v[198:201], v[90:93]
	v_mfma_f32_16x16x32_bf16 v[86:89], v[130:133], v[206:209], v[86:89]
	v_mfma_f32_16x16x32_bf16 v[82:85], v[138:141], v[206:209], v[82:85]
	v_mfma_f32_16x16x32_bf16 v[14:17], v[130:133], v[214:217], v[14:17]
	v_mfma_f32_16x16x32_bf16 v[10:13], v[138:141], v[214:217], v[10:13]
	v_mfma_f32_16x16x32_bf16 v[102:105], v[134:137], v[194:197], v[102:105]
	v_mfma_f32_16x16x32_bf16 v[98:101], v[162:165], v[194:197], v[98:101]
	v_mfma_f32_16x16x32_bf16 v[94:97], v[134:137], v[202:205], v[94:97]
	v_mfma_f32_16x16x32_bf16 v[90:93], v[162:165], v[202:205], v[90:93]
	v_mfma_f32_16x16x32_bf16 v[86:89], v[134:137], v[210:213], v[86:89]
	v_mfma_f32_16x16x32_bf16 v[82:85], v[162:165], v[210:213], v[82:85]
	v_mfma_f32_16x16x32_bf16 v[14:17], v[134:137], v[218:221], v[14:17]
	v_mfma_f32_16x16x32_bf16 v[10:13], v[162:165], v[218:221], v[10:13]
	v_mfma_f32_16x16x32_bf16 v[54:57], v[166:169], v[190:193], v[54:57]
	v_mfma_f32_16x16x32_bf16 v[50:53], v[174:177], v[190:193], v[50:53]
	v_mfma_f32_16x16x32_bf16 v[46:49], v[166:169], v[198:201], v[46:49]
	v_mfma_f32_16x16x32_bf16 v[42:45], v[174:177], v[198:201], v[42:45]
	v_mfma_f32_16x16x32_bf16 v[30:33], v[166:169], v[206:209], v[30:33]
	v_mfma_f32_16x16x32_bf16 v[18:21], v[174:177], v[206:209], v[18:21]
	v_mfma_f32_16x16x32_bf16 v[6:9], v[166:169], v[214:217], v[6:9]
	v_mfma_f32_16x16x32_bf16 v[2:5], v[174:177], v[214:217], v[2:5]
	v_mfma_f32_16x16x32_bf16 v[54:57], v[170:173], v[194:197], v[54:57]
	v_mfma_f32_16x16x32_bf16 v[50:53], v[186:189], v[194:197], v[50:53]
	v_mfma_f32_16x16x32_bf16 v[46:49], v[170:173], v[202:205], v[46:49]
	v_mfma_f32_16x16x32_bf16 v[42:45], v[186:189], v[202:205], v[42:45]
	v_mfma_f32_16x16x32_bf16 v[30:33], v[170:173], v[210:213], v[30:33]
	v_mfma_f32_16x16x32_bf16 v[18:21], v[186:189], v[210:213], v[18:21]
	v_mfma_f32_16x16x32_bf16 v[6:9], v[170:173], v[218:221], v[6:9]
	v_mfma_f32_16x16x32_bf16 v[2:5], v[186:189], v[218:221], v[2:5]
	s_barrier
	s_add_i32 s50, s50, 2
	s_add_u32 s48, s48, 0x100
	s_addc_u32 s49, s49, 0
	s_add_u32 s12, s12, 0x100
	s_addc_u32 s13, s13, 0
	s_cmp_gt_u32 s50, 5
	s_cbranch_scc0 .LBB0_1286
	s_setprio 0
	s_and_b64 vcc, exec, s[18:19]
	s_cbranch_vccz .LBB0_1289
	s_barrier

; #define PG8_STAGE(bufoff, gbase, voff) do { _Pragma("unroll") for (int _i = 0; _i < 2; ++_i) \
;         __builtin_amdgcn_global_load_lds((const unsigned*)((const char*)(gbase) + (voff)[_i]), (PG8_LAS unsigned*)(lds + (bufoff) + ldsw + _i * 8192), 16, 0, 0); } while (0)
; #define PG8_LDA(dst, b, h) do { _Pragma("unroll") for (int m = 0; m < 4; ++m) _Pragma("unroll") for (int k = 0; k < 2; ++k) dst[m][k] = *(const PG8_LAS bf16x8*)(lds + PG8_SA(b, h) + aoff + m * 2048 + k * 1024); } while (0)
; #define PG8_LDB(dst, b, h) do { _Pragma("unroll") for (int n = 0; n < 2; ++n) _Pragma("unroll") for (int k = 0; k < 2; ++k) dst[n][k] = *(const PG8_LAS bf16x8*)(lds + PG8_SB(b, h) + boff + n * 2048 + k * 1024); } while (0)
; #define PG8_SCHED __builtin_amdgcn_sched_barrier(0)
;     DI bool next(int i, pg8::Unit& u) const { if (i > 0 || !has) return false; u.pm = pm; u.pn = 0; return true; }
; template <class Epi, class Sched, bool ALIGN_EPI = false, bool SP2 = false>
; __device__ __forceinline__ void gemm_phase(PG8_LAS unsigned char* lds, const Gemm g, const Sched& S, const Epi& E) {
;     ...
;         const bool has_next = S.next(ui + 1, nxt);
;         const char* nA = has_next ? (const char*)g.A + (size_t)nxt.pm * tstepA : cA; const char* nB = has_next ? (const char*)g.Bt + (size_t)nxt.pn * tstepB : cB;
;         for (int t = 0; t < nt; t += 2) {
;             const bool last = (t == nt - 2);
;             const char* a1 = cA + (size_t)(t + 1) * kstep;
;             const char* a2 = last ? nA : cA + (size_t)(t + 2) * kstep; const char* b2 = last ? nB : cB + (size_t)(t + 2) * kstep;
;             const char* a3 = a2 + kstep; const char* b3 = b2 + kstep;
;             if (last && has_next) S.a_ready(nxt);
;             if constexpr (SP2) {
;             PG8_LDB(B0, 0, 0); PG8_LDB(B1, 0, 1); PG8_SCHED; PG8_LDA(At, 0, 0); PG8_STAGE(PG8_SA(1, 1), a1 + hstepA, voffA);
;     ...
; #pragma unroll
;         for (int a = 0; a < 2; ++a)
; #pragma unroll
;             for (int b = 0; b < 2; ++b)
; #pragma unroll
;                 for (int m = 0; m < 4; ++m)
; #pragma unroll
;                     for (int n = 0; n < 2; ++n) acc[a][b][m][n] = (f32x4){0.f, 0.f, 0.f, 0.f};
;         cur = nxt; cA = nA; cB = nB; ++ui;
.LBB0_1309:
	s_ashr_i32 s23, s22, 31
	s_lshl_b64 s[16:17], s[22:23], 18
	s_add_u32 s24, s35, s16
	s_addc_u32 s25, s36, s17
	s_and_b64 s[16:17], s[8:9], exec
	s_cselect_b32 s23, s25, s15
	s_cselect_b32 s46, s24, s14
	s_ashr_i32 s21, s20, 31
	s_lshl_b64 s[16:17], s[20:21], 18
	s_add_u32 s26, s37, s16
	s_addc_u32 s27, s38, s17
	s_and_b64 s[16:17], s[8:9], exec
	s_cselect_b32 s21, s27, s13
	s_cselect_b32 s47, s26, s12
	s_add_u32 s48, s12, 0x100
	s_addc_u32 s49, s13, 0
	s_add_u32 s12, s14, 0x20080
	v_mov_b32_e32 v2, 0
	s_addc_u32 s13, s15, 0
	s_mov_b32 s50, -2
	v_mov_b32_e32 v3, v2
	v_mov_b32_e32 v4, v2
	v_mov_b32_e32 v5, v2
	v_mov_b32_e32 v6, v2
	v_mov_b32_e32 v7, v2
	v_mov_b32_e32 v8, v2
	v_mov_b32_e32 v9, v2
	v_mov_b32_e32 v26, v2
	v_mov_b32_e32 v27, v2
	v_mov_b32_e32 v28, v2
	v_mov_b32_e32 v29, v2
	v_mov_b32_e32 v34, v2
	v_mov_b32_e32 v35, v2
	v_mov_b32_e32 v36, v2
	v_mov_b32_e32 v37, v2
	v_mov_b32_e32 v42, v2
	v_mov_b32_e32 v43, v2
	v_mov_b32_e32 v44, v2
	v_mov_b32_e32 v45, v2
	v_mov_b32_e32 v46, v2
	v_mov_b32_e32 v47, v2
	v_mov_b32_e32 v48, v2
	v_mov_b32_e32 v49, v2
	v_mov_b32_e32 v50, v2
	v_mov_b32_e32 v51, v2
	v_mov_b32_e32 v52, v2
	v_mov_b32_e32 v53, v2
	v_mov_b32_e32 v54, v2
	v_mov_b32_e32 v55, v2
	v_mov_b32_e32 v56, v2
	v_mov_b32_e32 v57, v2
	v_mov_b32_e32 v10, v2
	v_mov_b32_e32 v11, v2
	v_mov_b32_e32 v12, v2
	v_mov_b32_e32 v13, v2
	v_mov_b32_e32 v18, v2
	v_mov_b32_e32 v19, v2
	v_mov_b32_e32 v20, v2
	v_mov_b32_e32 v21, v2
	v_mov_b32_e32 v82, v2
	v_mov_b32_e32 v83, v2
	v_mov_b32_e32 v84, v2
	v_mov_b32_e32 v85, v2
	v_mov_b32_e32 v86, v2
	v_mov_b32_e32 v87, v2
	v_mov_b32_e32 v88, v2
	v_mov_b32_e32 v89, v2
	v_mov_b32_e32 v90, v2
	v_mov_b32_e32 v91, v2
	v_mov_b32_e32 v92, v2
	v_mov_b32_e32 v93, v2
	v_mov_b32_e32 v94, v2
	v_mov_b32_e32 v95, v2
	v_mov_b32_e32 v96, v2
	v_mov_b32_e32 v97, v2
	v_mov_b32_e32 v98, v2
	v_mov_b32_e32 v99, v2
	v_mov_b32_e32 v100, v2
	v_mov_b32_e32 v101, v2
	v_mov_b32_e32 v102, v2
	v_mov_b32_e32 v103, v2
	v_mov_b32_e32 v104, v2
	v_mov_b32_e32 v105, v2
	v_mov_b32_e32 v58, v2
	v_mov_b32_e32 v59, v2
	v_mov_b32_e32 v60, v2
	v_mov_b32_e32 v61, v2
	v_mov_b32_e32 v62, v2
	v_mov_b32_e32 v63, v2
	v_mov_b32_e32 v64, v2
	v_mov_b32_e32 v65, v2
	v_mov_b32_e32 v66, v2
	v_mov_b32_e32 v67, v2
	v_mov_b32_e32 v68, v2
	v_mov_b32_e32 v69, v2
	v_mov_b32_e32 v70, v2
	v_mov_b32_e32 v71, v2
	v_mov_b32_e32 v72, v2
	v_mov_b32_e32 v73, v2
	v_mov_b32_e32 v74, v2
	v_mov_b32_e32 v75, v2
	v_mov_b32_e32 v76, v2
	v_mov_b32_e32 v77, v2
	v_mov_b32_e32 v78, v2
	v_mov_b32_e32 v79, v2
	v_mov_b32_e32 v80, v2
	v_mov_b32_e32 v81, v2
	v_mov_b32_e32 v14, v2
	v_mov_b32_e32 v15, v2
	v_mov_b32_e32 v16, v2
	v_mov_b32_e32 v17, v2
	v_mov_b32_e32 v22, v2
	v_mov_b32_e32 v23, v2
	v_mov_b32_e32 v24, v2
	v_mov_b32_e32 v25, v2
	v_mov_b32_e32 v106, v2
	v_mov_b32_e32 v107, v2
	v_mov_b32_e32 v108, v2
	v_mov_b32_e32 v109, v2
	v_mov_b32_e32 v110, v2
	v_mov_b32_e32 v111, v2
	v_mov_b32_e32 v112, v2
	v_mov_b32_e32 v113, v2
	v_mov_b32_e32 v114, v2
	v_mov_b32_e32 v115, v2
	v_mov_b32_e32 v116, v2
	v_mov_b32_e32 v117, v2
	v_mov_b32_e32 v118, v2
	v_mov_b32_e32 v119, v2
	v_mov_b32_e32 v120, v2
	v_mov_b32_e32 v121, v2
	v_mov_b32_e32 v122, v2
	v_mov_b32_e32 v123, v2
	v_mov_b32_e32 v124, v2
	v_mov_b32_e32 v125, v2
	v_mov_b32_e32 v126, v2
	v_mov_b32_e32 v127, v2
	v_mov_b32_e32 v128, v2
	v_mov_b32_e32 v129, v2
	v_mov_b32_e32 v30, v2
	v_mov_b32_e32 v31, v2
	v_mov_b32_e32 v32, v2
	v_mov_b32_e32 v33, v2
	v_mov_b32_e32 v38, v2
	v_mov_b32_e32 v39, v2
	v_mov_b32_e32 v40, v2
	v_mov_b32_e32 v41, v2
	v_readlane_b32 s98, v250, 4
	s_cmp_lt_u32 s98, 4
	s_cbranch_scc1 .Lgp_7
	s_setprio 1
.Lgp_7:
.LBB0_1310:
	ds_read_b128 v[130:133], v186
	ds_read_b128 v[134:137], v186 offset:1024
	ds_read_b128 v[138:141], v186 offset:2048
	ds_read_b128 v[142:145], v186 offset:3072
	ds_read_b128 v[146:149], v187
	ds_read_b128 v[170:173], v187 offset:1024
	ds_read_b128 v[174:177], v187 offset:2048
	ds_read_b128 v[178:181], v187 offset:3072
	s_add_u32 s14, s12, 0xfffe0080
	s_addc_u32 s15, s13, -1
	s_cmp_eq_u32 s50, 4
	s_cselect_b32 s17, s23, s15
	s_cselect_b32 s16, s46, s14
	s_cselect_b32 s15, s21, s49
	s_cselect_b32 s14, s47, s48
	v_lshl_add_u64 v[182:183], s[12:13], 0, v[164:165]
	s_add_i32 m0, s30, 0xc000
	ds_read_b128 v[190:193], v188
	ds_read_b128 v[194:197], v188 offset:1024
	ds_read_b128 v[198:201], v188 offset:2048
	ds_read_b128 v[202:205], v188 offset:3072
	ds_read_b128 v[206:209], v188 offset:4096
	ds_read_b128 v[210:213], v188 offset:5120
	ds_read_b128 v[214:217], v188 offset:6144
	ds_read_b128 v[218:221], v188 offset:7168
	global_load_lds_dwordx4 v[182:183], off
	v_lshl_add_u64 v[182:183], s[12:13], 0, v[162:163]
	s_add_i32 m0, s30, 0xe000
	s_nop 0
	global_load_lds_dwordx4 v[182:183], off
	s_waitcnt vmcnt(8)
	s_waitcnt lgkmcnt(0)
	s_barrier
; #define PG8_STAGE(bufoff, gbase, voff) do { _Pragma("unroll") for (int _i = 0; _i < 2; ++_i) \
;         __builtin_amdgcn_global_load_lds((const unsigned*)((const char*)(gbase) + (voff)[_i]), (PG8_LAS unsigned*)(lds + (bufoff) + ldsw + _i * 8192), 16, 0, 0); } while (0)
; #define PG8_LDA(dst, b, h) do { _Pragma("unroll") for (int m = 0; m < 4; ++m) _Pragma("unroll") for (int k = 0; k < 2; ++k) dst[m][k] = *(const PG8_LAS bf16x8*)(lds + PG8_SA(b, h) + aoff + m * 2048 + k * 1024); } while (0)
; #define PG8_MMA(ai, bj, At, Bt) do { __builtin_amdgcn_s_setprio(1); _Pragma("unroll") for (int m = 0; m < 4; ++m) _Pragma("unroll") for (int n = 0; n < 2; ++n) _Pragma("unroll") for (int k = 0; k < 2; ++k) \
;         acc[ai][bj][m][n] = __builtin_amdgcn_mfma_f32_16x16x32_bf16(Bt[n][k], At[m][k], acc[ai][bj][m][n], 0, 0, 0); __builtin_amdgcn_s_setprio(0); } while (0)
; #define PG8_WAIT_V(n) asm volatile("s_waitcnt vmcnt(" #n ")" ::: "memory")
; #define PG8_WAIT_L(n) asm volatile("s_waitcnt lgkmcnt(" #n ")" ::: "memory")
; #define PG8_BAR __builtin_amdgcn_s_barrier()
; #define PG8_SCHED __builtin_amdgcn_sched_barrier(0)
; template <class Epi, class Sched, bool ALIGN_EPI = false, bool SP2 = false>
; __device__ __forceinline__ void gemm_phase(PG8_LAS unsigned char* lds, const Gemm g, const Sched& S, const Epi& E) {
;     ...
;             PG8_WAIT_V(8); PG8_WAIT_L(0); PG8_BAR; PG8_MMA(0, 0, At, B0); PG8_MMA(0, 1, At, B1); PG8_BAR; PG8_SCHED;
;             PG8_LDA(At, 0, 1); PG8_STAGE(PG8_SB(0, 0), b2, voffB); PG8_STAGE(PG8_SB(0, 1), b2 + hstepB, voffB); PG8_STAGE(PG8_SA(0, 0), a2, voffA);
;             PG8_WAIT_V(8); PG8_WAIT_L(0); PG8_BAR; PG8_MMA(1, 0, At, B0); PG8_MMA(1, 1, At, B1); PG8_BAR; PG8_SCHED;
	s_waitcnt lgkmcnt(0)
	v_mfma_f32_16x16x32_bf16 v[38:41], v[130:133], v[190:193], v[38:41]
	v_mfma_f32_16x16x32_bf16 v[30:33], v[138:141], v[190:193], v[30:33]
	v_mfma_f32_16x16x32_bf16 v[126:129], v[130:133], v[198:201], v[126:129]
	v_mfma_f32_16x16x32_bf16 v[122:125], v[138:141], v[198:201], v[122:125]
	v_mfma_f32_16x16x32_bf16 v[118:121], v[130:133], v[206:209], v[118:121]
	v_mfma_f32_16x16x32_bf16 v[114:117], v[138:141], v[206:209], v[114:117]
	v_mfma_f32_16x16x32_bf16 v[110:113], v[130:133], v[214:217], v[110:113]
	v_mfma_f32_16x16x32_bf16 v[106:109], v[138:141], v[214:217], v[106:109]
	v_mfma_f32_16x16x32_bf16 v[38:41], v[134:137], v[194:197], v[38:41]
	v_mfma_f32_16x16x32_bf16 v[30:33], v[142:145], v[194:197], v[30:33]
	v_mfma_f32_16x16x32_bf16 v[126:129], v[134:137], v[202:205], v[126:129]
	v_mfma_f32_16x16x32_bf16 v[122:125], v[142:145], v[202:205], v[122:125]
	v_mfma_f32_16x16x32_bf16 v[118:121], v[134:137], v[210:213], v[118:121]
	v_mfma_f32_16x16x32_bf16 v[114:117], v[142:145], v[210:213], v[114:117]
	v_mfma_f32_16x16x32_bf16 v[110:113], v[134:137], v[218:221], v[110:113]
	v_mfma_f32_16x16x32_bf16 v[106:109], v[142:145], v[218:221], v[106:109]
	v_mfma_f32_16x16x32_bf16 v[22:25], v[146:149], v[190:193], v[22:25]
	v_mfma_f32_16x16x32_bf16 v[14:17], v[174:177], v[190:193], v[14:17]
	v_mfma_f32_16x16x32_bf16 v[78:81], v[146:149], v[198:201], v[78:81]
	v_mfma_f32_16x16x32_bf16 v[74:77], v[174:177], v[198:201], v[74:77]
	v_mfma_f32_16x16x32_bf16 v[70:73], v[146:149], v[206:209], v[70:73]
	v_mfma_f32_16x16x32_bf16 v[66:69], v[174:177], v[206:209], v[66:69]
	v_mfma_f32_16x16x32_bf16 v[62:65], v[146:149], v[214:217], v[62:65]
	v_mfma_f32_16x16x32_bf16 v[58:61], v[174:177], v[214:217], v[58:61]
	v_mfma_f32_16x16x32_bf16 v[22:25], v[170:173], v[194:197], v[22:25]
	v_mfma_f32_16x16x32_bf16 v[14:17], v[178:181], v[194:197], v[14:17]
	v_mfma_f32_16x16x32_bf16 v[78:81], v[170:173], v[202:205], v[78:81]
	v_mfma_f32_16x16x32_bf16 v[74:77], v[178:181], v[202:205], v[74:77]
	v_mfma_f32_16x16x32_bf16 v[70:73], v[170:173], v[210:213], v[70:73]
	v_mfma_f32_16x16x32_bf16 v[66:69], v[178:181], v[210:213], v[66:69]
	v_mfma_f32_16x16x32_bf16 v[62:65], v[170:173], v[218:221], v[62:65]
	v_mfma_f32_16x16x32_bf16 v[58:61], v[178:181], v[218:221], v[58:61]
	s_barrier
	s_add_i32 s51, s44, s29
	v_lshl_add_u64 v[182:183], s[14:15], 0, v[156:157]
	s_mov_b32 m0, s51
	ds_read_b128 v[190:193], v188 offset:16384
	ds_read_b128 v[194:197], v188 offset:17408
	ds_read_b128 v[198:201], v188 offset:18432
	ds_read_b128 v[202:205], v188 offset:19456
	ds_read_b128 v[206:209], v188 offset:20480
	ds_read_b128 v[210:213], v188 offset:21504
	ds_read_b128 v[214:217], v188 offset:22528
	ds_read_b128 v[218:221], v188 offset:23552
	global_load_lds_dwordx4 v[182:183], off
	s_add_i32 m0, s51, 0x2000
	s_add_u32 s52, s14, 0x20000
	v_lshl_add_u64 v[222:223], s[14:15], 0, v[160:161]
	s_addc_u32 s53, s15, 0
	s_add_i32 s51, s45, s29
	global_load_lds_dwordx4 v[222:223], off
	v_lshl_add_u64 v[224:225], s[52:53], 0, v[156:157]
	s_mov_b32 m0, s51
	v_lshl_add_u64 v[226:227], s[16:17], 0, v[158:159]
	global_load_lds_dwordx4 v[224:225], off
	v_lshl_add_u64 v[224:225], s[52:53], 0, v[160:161]
	s_add_i32 m0, s51, 0x2000
	s_nop 0
	global_load_lds_dwordx4 v[224:225], off
	v_lshl_add_u64 v[224:225], s[16:17], 0, v[152:153]
	s_mov_b32 m0, s30
	s_nop 0
	global_load_lds_dwordx4 v[224:225], off
	s_mov_b32 m0, s31
	s_nop 0
	global_load_lds_dwordx4 v[226:227], off
	s_waitcnt vmcnt(8)
	s_waitcnt lgkmcnt(0)
	s_barrier
	s_waitcnt lgkmcnt(0)
	v_mfma_f32_16x16x32_bf16 v[102:105], v[130:133], v[190:193], v[102:105]
	v_mfma_f32_16x16x32_bf16 v[98:101], v[138:141], v[190:193], v[98:101]
	v_mfma_f32_16x16x32_bf16 v[94:97], v[130:133], v[198:201], v[94:97]
	v_mfma_f32_16x16x32_bf16 v[90:93], v[138:141], v[198:201], v[90:93]
	v_mfma_f32_16x16x32_bf16 v[86:89], v[130:133], v[206:209], v[86:89]
	v_mfma_f32_16x16x32_bf16 v[82:85], v[138:141], v[206:209], v[82:85]
	v_mfma_f32_16x16x32_bf16 v[18:21], v[130:133], v[214:217], v[18:21]
	v_mfma_f32_16x16x32_bf16 v[10:13], v[138:141], v[214:217], v[10:13]
	v_mfma_f32_16x16x32_bf16 v[102:105], v[134:137], v[194:197], v[102:105]
	v_mfma_f32_16x16x32_bf16 v[98:101], v[142:145], v[194:197], v[98:101]
	v_mfma_f32_16x16x32_bf16 v[94:97], v[134:137], v[202:205], v[94:97]
	v_mfma_f32_16x16x32_bf16 v[90:93], v[142:145], v[202:205], v[90:93]
	v_mfma_f32_16x16x32_bf16 v[86:89], v[134:137], v[210:213], v[86:89]
	v_mfma_f32_16x16x32_bf16 v[82:85], v[142:145], v[210:213], v[82:85]
	v_mfma_f32_16x16x32_bf16 v[18:21], v[134:137], v[218:221], v[18:21]
	v_mfma_f32_16x16x32_bf16 v[10:13], v[142:145], v[218:221], v[10:13]
	v_mfma_f32_16x16x32_bf16 v[54:57], v[146:149], v[190:193], v[54:57]
	v_mfma_f32_16x16x32_bf16 v[50:53], v[174:177], v[190:193], v[50:53]
	v_mfma_f32_16x16x32_bf16 v[46:49], v[146:149], v[198:201], v[46:49]
	v_mfma_f32_16x16x32_bf16 v[42:45], v[174:177], v[198:201], v[42:45]
	v_mfma_f32_16x16x32_bf16 v[34:37], v[146:149], v[206:209], v[34:37]
	v_mfma_f32_16x16x32_bf16 v[26:29], v[174:177], v[206:209], v[26:29]
	v_mfma_f32_16x16x32_bf16 v[6:9], v[146:149], v[214:217], v[6:9]
	v_mfma_f32_16x16x32_bf16 v[2:5], v[174:177], v[214:217], v[2:5]
	v_mfma_f32_16x16x32_bf16 v[54:57], v[170:173], v[194:197], v[54:57]
	v_mfma_f32_16x16x32_bf16 v[50:53], v[178:181], v[194:197], v[50:53]
	v_mfma_f32_16x16x32_bf16 v[46:49], v[170:173], v[202:205], v[46:49]
	v_mfma_f32_16x16x32_bf16 v[42:45], v[178:181], v[202:205], v[42:45]
	v_mfma_f32_16x16x32_bf16 v[34:37], v[170:173], v[210:213], v[34:37]
	v_mfma_f32_16x16x32_bf16 v[26:29], v[178:181], v[210:213], v[26:29]
	v_mfma_f32_16x16x32_bf16 v[6:9], v[170:173], v[218:221], v[6:9]
	v_mfma_f32_16x16x32_bf16 v[2:5], v[178:181], v[218:221], v[2:5]
	s_barrier
; #define PG8_STAGE(bufoff, gbase, voff) do { _Pragma("unroll") for (int _i = 0; _i < 2; ++_i) \
;         __builtin_amdgcn_global_load_lds((const unsigned*)((const char*)(gbase) + (voff)[_i]), (PG8_LAS unsigned*)(lds + (bufoff) + ldsw + _i * 8192), 16, 0, 0); } while (0)
; #define PG8_LDA(dst, b, h) do { _Pragma("unroll") for (int m = 0; m < 4; ++m) _Pragma("unroll") for (int k = 0; k < 2; ++k) dst[m][k] = *(const PG8_LAS bf16x8*)(lds + PG8_SA(b, h) + aoff + m * 2048 + k * 1024); } while (0)
; #define PG8_LDB(dst, b, h) do { _Pragma("unroll") for (int n = 0; n < 2; ++n) _Pragma("unroll") for (int k = 0; k < 2; ++k) dst[n][k] = *(const PG8_LAS bf16x8*)(lds + PG8_SB(b, h) + boff + n * 2048 + k * 1024); } while (0)
; #define PG8_MMA(ai, bj, At, Bt) do { __builtin_amdgcn_s_setprio(1); _Pragma("unroll") for (int m = 0; m < 4; ++m) _Pragma("unroll") for (int n = 0; n < 2; ++n) _Pragma("unroll") for (int k = 0; k < 2; ++k) \
;         acc[ai][bj][m][n] = __builtin_amdgcn_mfma_f32_16x16x32_bf16(Bt[n][k], At[m][k], acc[ai][bj][m][n], 0, 0, 0); __builtin_amdgcn_s_setprio(0); } while (0)
; #define PG8_WAIT_V(n) asm volatile("s_waitcnt vmcnt(" #n ")" ::: "memory")
; #define PG8_WAIT_L(n) asm volatile("s_waitcnt lgkmcnt(" #n ")" ::: "memory")
; #define PG8_BAR __builtin_amdgcn_s_barrier()
; #define PG8_SCHED __builtin_amdgcn_sched_barrier(0)
; template <class Epi, class Sched, bool ALIGN_EPI = false, bool SP2 = false>
; __device__ __forceinline__ void gemm_phase(PG8_LAS unsigned char* lds, const Gemm g, const Sched& S, const Epi& E) {
;     ...
;             PG8_LDB(B0, 1, 0); PG8_LDB(B1, 1, 1); PG8_SCHED; PG8_LDA(At, 1, 0); PG8_STAGE(PG8_SA(0, 1), a2 + hstepA, voffA);
;             PG8_WAIT_V(8); PG8_WAIT_L(0); PG8_BAR; PG8_MMA(0, 0, At, B0); PG8_MMA(0, 1, At, B1); PG8_BAR; PG8_SCHED;
	s_add_i32 s51, 0, 0x18000
	s_add_i32 s52, 0, 0x1c000
	v_add_u32_e32 v142, s51, v155
	v_add_u32_e32 v178, s52, v155
	ds_read_b128 v[130:133], v142
	ds_read_b128 v[134:137], v142 offset:1024
	ds_read_b128 v[138:141], v142 offset:2048
	ds_read_b128 v[142:145], v142 offset:3072
	ds_read_b128 v[146:149], v178
	ds_read_b128 v[170:173], v178 offset:1024
	ds_read_b128 v[174:177], v178 offset:2048
	ds_read_b128 v[178:181], v178 offset:3072
	s_add_u32 s16, s16, 0x20000
	s_addc_u32 s17, s17, 0
	s_mov_b32 m0, s33
	v_lshl_add_u64 v[228:229], s[16:17], 0, v[152:153]
	ds_read_b128 v[190:193], v188 offset:32768
	ds_read_b128 v[194:197], v188 offset:33792
	ds_read_b128 v[198:201], v188 offset:34816
	ds_read_b128 v[202:205], v188 offset:35840
	ds_read_b128 v[206:209], v188 offset:36864
	ds_read_b128 v[210:213], v188 offset:37888
	ds_read_b128 v[214:217], v188 offset:38912
	ds_read_b128 v[218:221], v188 offset:39936
	global_load_lds_dwordx4 v[228:229], off
	v_lshl_add_u64 v[228:229], s[16:17], 0, v[158:159]
	s_mov_b32 m0, s34
	s_nop 0
	global_load_lds_dwordx4 v[228:229], off
	s_waitcnt vmcnt(8)
	s_waitcnt lgkmcnt(0)
	s_barrier
	s_waitcnt lgkmcnt(0)
	v_mfma_f32_16x16x32_bf16 v[38:41], v[130:133], v[190:193], v[38:41]
	v_mfma_f32_16x16x32_bf16 v[30:33], v[138:141], v[190:193], v[30:33]
	v_mfma_f32_16x16x32_bf16 v[126:129], v[130:133], v[198:201], v[126:129]
	v_mfma_f32_16x16x32_bf16 v[122:125], v[138:141], v[198:201], v[122:125]
	v_mfma_f32_16x16x32_bf16 v[118:121], v[130:133], v[206:209], v[118:121]
	v_mfma_f32_16x16x32_bf16 v[114:117], v[138:141], v[206:209], v[114:117]
	v_mfma_f32_16x16x32_bf16 v[110:113], v[130:133], v[214:217], v[110:113]
	v_mfma_f32_16x16x32_bf16 v[106:109], v[138:141], v[214:217], v[106:109]
	v_mfma_f32_16x16x32_bf16 v[38:41], v[134:137], v[194:197], v[38:41]
	v_mfma_f32_16x16x32_bf16 v[30:33], v[142:145], v[194:197], v[30:33]
	v_mfma_f32_16x16x32_bf16 v[126:129], v[134:137], v[202:205], v[126:129]
	v_mfma_f32_16x16x32_bf16 v[122:125], v[142:145], v[202:205], v[122:125]
	v_mfma_f32_16x16x32_bf16 v[118:121], v[134:137], v[210:213], v[118:121]
	v_mfma_f32_16x16x32_bf16 v[114:117], v[142:145], v[210:213], v[114:117]
	v_mfma_f32_16x16x32_bf16 v[110:113], v[134:137], v[218:221], v[110:113]
	v_mfma_f32_16x16x32_bf16 v[106:109], v[142:145], v[218:221], v[106:109]
	v_mfma_f32_16x16x32_bf16 v[22:25], v[146:149], v[190:193], v[22:25]
	v_mfma_f32_16x16x32_bf16 v[14:17], v[174:177], v[190:193], v[14:17]
	v_mfma_f32_16x16x32_bf16 v[78:81], v[146:149], v[198:201], v[78:81]
	v_mfma_f32_16x16x32_bf16 v[74:77], v[174:177], v[198:201], v[74:77]
	v_mfma_f32_16x16x32_bf16 v[70:73], v[146:149], v[206:209], v[70:73]
	v_mfma_f32_16x16x32_bf16 v[66:69], v[174:177], v[206:209], v[66:69]
	v_mfma_f32_16x16x32_bf16 v[62:65], v[146:149], v[214:217], v[62:65]
	v_mfma_f32_16x16x32_bf16 v[58:61], v[174:177], v[214:217], v[58:61]
	v_mfma_f32_16x16x32_bf16 v[22:25], v[170:173], v[194:197], v[22:25]
	v_mfma_f32_16x16x32_bf16 v[14:17], v[178:181], v[194:197], v[14:17]
	v_mfma_f32_16x16x32_bf16 v[78:81], v[170:173], v[202:205], v[78:81]
	v_mfma_f32_16x16x32_bf16 v[74:77], v[178:181], v[202:205], v[74:77]
	v_mfma_f32_16x16x32_bf16 v[70:73], v[170:173], v[210:213], v[70:73]
	v_mfma_f32_16x16x32_bf16 v[66:69], v[178:181], v[210:213], v[66:69]
	v_mfma_f32_16x16x32_bf16 v[62:65], v[170:173], v[218:221], v[62:65]
	v_mfma_f32_16x16x32_bf16 v[58:61], v[178:181], v[218:221], v[58:61]
	s_barrier
; #define PG8_STAGE(bufoff, gbase, voff) do { _Pragma("unroll") for (int _i = 0; _i < 2; ++_i) \
;         __builtin_amdgcn_global_load_lds((const unsigned*)((const char*)(gbase) + (voff)[_i]), (PG8_LAS unsigned*)(lds + (bufoff) + ldsw + _i * 8192), 16, 0, 0); } while (0)
; #define PG8_LDA(dst, b, h) do { _Pragma("unroll") for (int m = 0; m < 4; ++m) _Pragma("unroll") for (int k = 0; k < 2; ++k) dst[m][k] = *(const PG8_LAS bf16x8*)(lds + PG8_SA(b, h) + aoff + m * 2048 + k * 1024); } while (0)
; #define PG8_MMA(ai, bj, At, Bt) do { __builtin_amdgcn_s_setprio(1); _Pragma("unroll") for (int m = 0; m < 4; ++m) _Pragma("unroll") for (int n = 0; n < 2; ++n) _Pragma("unroll") for (int k = 0; k < 2; ++k) \
;         acc[ai][bj][m][n] = __builtin_amdgcn_mfma_f32_16x16x32_bf16(Bt[n][k], At[m][k], acc[ai][bj][m][n], 0, 0, 0); __builtin_amdgcn_s_setprio(0); } while (0)
; #define PG8_WAIT_V(n) asm volatile("s_waitcnt vmcnt(" #n ")" ::: "memory")
; #define PG8_WAIT_L(n) asm volatile("s_waitcnt lgkmcnt(" #n ")" ::: "memory")
; #define PG8_BAR __builtin_amdgcn_s_barrier()
; #define PG8_SCHED __builtin_amdgcn_sched_barrier(0)
; template <class Epi, class Sched, bool ALIGN_EPI = false, bool SP2 = false>
; __device__ __forceinline__ void gemm_phase(PG8_LAS unsigned char* lds, const Gemm g, const Sched& S, const Epi& E) {
;     ...
;             PG8_LDA(At, 1, 1); PG8_STAGE(PG8_SB(1, 0), b3, voffB); PG8_STAGE(PG8_SB(1, 1), b3 + hstepB, voffB); PG8_STAGE(PG8_SA(1, 0), a3, voffA);
;             PG8_WAIT_V(8); PG8_WAIT_L(0); PG8_BAR; PG8_MMA(1, 0, At, B0); PG8_MMA(1, 1, At, B1); PG8_BAR; PG8_SCHED;
;     ...
;         if constexpr (ALIGN_EPI) { if (wr == 0) PG8_BAR; }
	s_add_i32 s16, s51, s29
	v_lshl_add_u64 v[182:183], v[182:183], 0, s[6:7]
	s_mov_b32 m0, s16
	ds_read_b128 v[190:193], v188 offset:49152
	ds_read_b128 v[194:197], v188 offset:50176
	ds_read_b128 v[198:201], v188 offset:51200
	ds_read_b128 v[202:205], v188 offset:52224
	ds_read_b128 v[206:209], v188 offset:53248
	ds_read_b128 v[210:213], v188 offset:54272
	ds_read_b128 v[214:217], v188 offset:55296
	ds_read_b128 v[218:221], v188 offset:56320
	global_load_lds_dwordx4 v[182:183], off
	s_add_i32 m0, s16, 0x2000
	s_add_u32 s14, s14, 0x20080
	v_lshl_add_u64 v[182:183], v[222:223], 0, s[6:7]
	s_addc_u32 s15, s15, 0
	s_add_i32 s16, s52, s29
	global_load_lds_dwordx4 v[182:183], off
	v_lshl_add_u64 v[182:183], s[14:15], 0, v[156:157]
	s_mov_b32 m0, s16
	s_nop 0
	global_load_lds_dwordx4 v[182:183], off
	v_lshl_add_u64 v[182:183], s[14:15], 0, v[160:161]
	s_add_i32 m0, s16, 0x2000
	s_nop 0
	global_load_lds_dwordx4 v[182:183], off
	v_lshl_add_u64 v[182:183], v[224:225], 0, s[6:7]
	s_mov_b32 m0, s40
	s_nop 0
	global_load_lds_dwordx4 v[182:183], off
	v_lshl_add_u64 v[182:183], v[226:227], 0, s[6:7]
	s_mov_b32 m0, s41
	s_nop 0
	global_load_lds_dwordx4 v[182:183], off
	s_waitcnt vmcnt(8)
	s_waitcnt lgkmcnt(0)
	s_barrier
	s_waitcnt lgkmcnt(0)
	v_mfma_f32_16x16x32_bf16 v[102:105], v[130:133], v[190:193], v[102:105]
	v_mfma_f32_16x16x32_bf16 v[98:101], v[138:141], v[190:193], v[98:101]
	v_mfma_f32_16x16x32_bf16 v[94:97], v[130:133], v[198:201], v[94:97]
	v_mfma_f32_16x16x32_bf16 v[90:93], v[138:141], v[198:201], v[90:93]
	v_mfma_f32_16x16x32_bf16 v[86:89], v[130:133], v[206:209], v[86:89]
	v_mfma_f32_16x16x32_bf16 v[82:85], v[138:141], v[206:209], v[82:85]
	v_mfma_f32_16x16x32_bf16 v[18:21], v[130:133], v[214:217], v[18:21]
	v_mfma_f32_16x16x32_bf16 v[10:13], v[138:141], v[214:217], v[10:13]
	v_mfma_f32_16x16x32_bf16 v[102:105], v[134:137], v[194:197], v[102:105]
	v_mfma_f32_16x16x32_bf16 v[98:101], v[142:145], v[194:197], v[98:101]
	v_mfma_f32_16x16x32_bf16 v[94:97], v[134:137], v[202:205], v[94:97]
	v_mfma_f32_16x16x32_bf16 v[90:93], v[142:145], v[202:205], v[90:93]
	v_mfma_f32_16x16x32_bf16 v[86:89], v[134:137], v[210:213], v[86:89]
	v_mfma_f32_16x16x32_bf16 v[82:85], v[142:145], v[210:213], v[82:85]
	v_mfma_f32_16x16x32_bf16 v[18:21], v[134:137], v[218:221], v[18:21]
	v_mfma_f32_16x16x32_bf16 v[10:13], v[142:145], v[218:221], v[10:13]
	v_mfma_f32_16x16x32_bf16 v[54:57], v[146:149], v[190:193], v[54:57]
	v_mfma_f32_16x16x32_bf16 v[50:53], v[174:177], v[190:193], v[50:53]
	v_mfma_f32_16x16x32_bf16 v[46:49], v[146:149], v[198:201], v[46:49]
	v_mfma_f32_16x16x32_bf16 v[42:45], v[174:177], v[198:201], v[42:45]
	v_mfma_f32_16x16x32_bf16 v[34:37], v[146:149], v[206:209], v[34:37]
	v_mfma_f32_16x16x32_bf16 v[26:29], v[174:177], v[206:209], v[26:29]
	v_mfma_f32_16x16x32_bf16 v[6:9], v[146:149], v[214:217], v[6:9]
	v_mfma_f32_16x16x32_bf16 v[2:5], v[174:177], v[214:217], v[2:5]
	v_mfma_f32_16x16x32_bf16 v[54:57], v[170:173], v[194:197], v[54:57]
	v_mfma_f32_16x16x32_bf16 v[50:53], v[178:181], v[194:197], v[50:53]
	v_mfma_f32_16x16x32_bf16 v[46:49], v[170:173], v[202:205], v[46:49]
	v_mfma_f32_16x16x32_bf16 v[42:45], v[178:181], v[202:205], v[42:45]
	v_mfma_f32_16x16x32_bf16 v[34:37], v[170:173], v[210:213], v[34:37]
	v_mfma_f32_16x16x32_bf16 v[26:29], v[178:181], v[210:213], v[26:29]
	v_mfma_f32_16x16x32_bf16 v[6:9], v[170:173], v[218:221], v[6:9]
	v_mfma_f32_16x16x32_bf16 v[2:5], v[178:181], v[218:221], v[2:5]
	s_barrier
	s_add_i32 s50, s50, 2
	s_add_u32 s48, s48, 0x100
	s_addc_u32 s49, s49, 0
	s_add_u32 s12, s12, 0x100
	s_addc_u32 s13, s13, 0
	s_cmp_gt_u32 s50, 5
	s_cbranch_scc0 .LBB0_1310
	s_setprio 0
	s_and_b64 vcc, exec, s[18:19]
	s_cbranch_vccz .LBB0_1313
	s_barrier

; #define PG8_STAGE(bufoff, gbase, voff) do { _Pragma("unroll") for (int _i = 0; _i < 2; ++_i) \
;         __builtin_amdgcn_global_load_lds((const unsigned*)((const char*)(gbase) + (voff)[_i]), (PG8_LAS unsigned*)(lds + (bufoff) + ldsw + _i * 8192), 16, 0, 0); } while (0)
; #define PG8_LDA(dst, b, h) do { _Pragma("unroll") for (int m = 0; m < 4; ++m) _Pragma("unroll") for (int k = 0; k < 2; ++k) dst[m][k] = *(const PG8_LAS bf16x8*)(lds + PG8_SA(b, h) + aoff + m * 2048 + k * 1024); } while (0)
; #define PG8_LDB(dst, b, h) do { _Pragma("unroll") for (int n = 0; n < 2; ++n) _Pragma("unroll") for (int k = 0; k < 2; ++k) dst[n][k] = *(const PG8_LAS bf16x8*)(lds + PG8_SB(b, h) + boff + n * 2048 + k * 1024); } while (0)
; #define PG8_SCHED __builtin_amdgcn_sched_barrier(0)
;     DI bool next(int i, pg8::Unit& u) const { if (i > 0 || !has) return false; u.pm = pm; u.pn = 0; return true; }
; template <class Epi, class Sched, bool ALIGN_EPI = false, bool SP2 = false>
; __device__ __forceinline__ void gemm_phase(PG8_LAS unsigned char* lds, const Gemm g, const Sched& S, const Epi& E) {
;     ...
;         const bool has_next = S.next(ui + 1, nxt);
;         const char* nA = has_next ? (const char*)g.A + (size_t)nxt.pm * tstepA : cA; const char* nB = has_next ? (const char*)g.Bt + (size_t)nxt.pn * tstepB : cB;
;         for (int t = 0; t < nt; t += 2) {
;             const bool last = (t == nt - 2);
;             const char* a1 = cA + (size_t)(t + 1) * kstep;
;             const char* a2 = last ? nA : cA + (size_t)(t + 2) * kstep; const char* b2 = last ? nB : cB + (size_t)(t + 2) * kstep;
;             const char* a3 = a2 + kstep; const char* b3 = b2 + kstep;
;             if (last && has_next) S.a_ready(nxt);
;             if constexpr (SP2) {
;             PG8_LDB(B0, 0, 0); PG8_LDB(B1, 0, 1); PG8_SCHED; PG8_LDA(At, 0, 0); PG8_STAGE(PG8_SA(1, 1), a1 + hstepA, voffA);
;     ...
; #pragma unroll
;         for (int a = 0; a < 2; ++a)
; #pragma unroll
;             for (int b = 0; b < 2; ++b)
; #pragma unroll
;                 for (int m = 0; m < 4; ++m)
; #pragma unroll
;                     for (int n = 0; n < 2; ++n) acc[a][b][m][n] = (f32x4){0.f, 0.f, 0.f, 0.f};
;         cur = nxt; cA = nA; cB = nB; ++ui;
.LBB0_1385:
	s_ashr_i32 s23, s22, 31
	s_lshl_b64 s[24:25], s[22:23], 19
	s_add_u32 s24, s40, s24
	s_addc_u32 s25, s41, s25
	s_and_b64 s[26:27], s[4:5], exec
	s_cselect_b32 s23, s25, s31
	s_cselect_b32 s56, s24, s30
	s_ashr_i32 s21, s20, 31
	s_lshl_b64 s[26:27], s[20:21], 19
	s_add_u32 s26, s42, s26
	s_addc_u32 s27, s43, s27
	s_and_b64 s[34:35], s[4:5], exec
	s_cselect_b32 s21, s27, s29
	s_cselect_b32 s57, s26, s28
	s_add_u32 s58, s28, 0x100
	s_addc_u32 s59, s29, 0
	s_add_u32 s28, s30, 0x40080
	v_mov_b32_e32 v2, 0
	s_addc_u32 s29, s31, 0
	s_mov_b32 s60, -2
	v_mov_b32_e32 v3, v2
	v_mov_b32_e32 v4, v2
	v_mov_b32_e32 v5, v2
	v_mov_b32_e32 v6, v2
	v_mov_b32_e32 v7, v2
	v_mov_b32_e32 v8, v2
	v_mov_b32_e32 v9, v2
	v_mov_b32_e32 v10, v2
	v_mov_b32_e32 v11, v2
	v_mov_b32_e32 v12, v2
	v_mov_b32_e32 v13, v2
	v_mov_b32_e32 v14, v2
	v_mov_b32_e32 v15, v2
	v_mov_b32_e32 v16, v2
	v_mov_b32_e32 v17, v2
	v_mov_b32_e32 v18, v2
	v_mov_b32_e32 v19, v2
	v_mov_b32_e32 v20, v2
	v_mov_b32_e32 v21, v2
	v_mov_b32_e32 v22, v2
	v_mov_b32_e32 v23, v2
	v_mov_b32_e32 v24, v2
	v_mov_b32_e32 v25, v2
	v_mov_b32_e32 v26, v2
	v_mov_b32_e32 v27, v2
	v_mov_b32_e32 v28, v2
	v_mov_b32_e32 v29, v2
	v_mov_b32_e32 v30, v2
	v_mov_b32_e32 v31, v2
	v_mov_b32_e32 v32, v2
	v_mov_b32_e32 v33, v2
	v_mov_b32_e32 v42, v2
	v_mov_b32_e32 v43, v2
	v_mov_b32_e32 v44, v2
	v_mov_b32_e32 v45, v2
	v_mov_b32_e32 v46, v2
	v_mov_b32_e32 v47, v2
	v_mov_b32_e32 v48, v2
	v_mov_b32_e32 v49, v2
	v_mov_b32_e32 v58, v2
	v_mov_b32_e32 v59, v2
	v_mov_b32_e32 v60, v2
	v_mov_b32_e32 v61, v2
	v_mov_b32_e32 v66, v2
	v_mov_b32_e32 v67, v2
	v_mov_b32_e32 v68, v2
	v_mov_b32_e32 v69, v2
	v_mov_b32_e32 v78, v2
	v_mov_b32_e32 v79, v2
	v_mov_b32_e32 v80, v2
	v_mov_b32_e32 v81, v2
	v_mov_b32_e32 v86, v2
	v_mov_b32_e32 v87, v2
	v_mov_b32_e32 v88, v2
	v_mov_b32_e32 v89, v2
	v_mov_b32_e32 v90, v2
	v_mov_b32_e32 v91, v2
	v_mov_b32_e32 v92, v2
	v_mov_b32_e32 v93, v2
	v_mov_b32_e32 v94, v2
	v_mov_b32_e32 v95, v2
	v_mov_b32_e32 v96, v2
	v_mov_b32_e32 v97, v2
	v_mov_b32_e32 v34, v2
	v_mov_b32_e32 v35, v2
	v_mov_b32_e32 v36, v2
	v_mov_b32_e32 v37, v2
	v_mov_b32_e32 v38, v2
	v_mov_b32_e32 v39, v2
	v_mov_b32_e32 v40, v2
	v_mov_b32_e32 v41, v2
	v_mov_b32_e32 v50, v2
	v_mov_b32_e32 v51, v2
	v_mov_b32_e32 v52, v2
	v_mov_b32_e32 v53, v2
	v_mov_b32_e32 v54, v2
	v_mov_b32_e32 v55, v2
	v_mov_b32_e32 v56, v2
	v_mov_b32_e32 v57, v2
	v_mov_b32_e32 v62, v2
	v_mov_b32_e32 v63, v2
	v_mov_b32_e32 v64, v2
	v_mov_b32_e32 v65, v2
	v_mov_b32_e32 v70, v2
	v_mov_b32_e32 v71, v2
	v_mov_b32_e32 v72, v2
	v_mov_b32_e32 v73, v2
	v_mov_b32_e32 v74, v2
	v_mov_b32_e32 v75, v2
	v_mov_b32_e32 v76, v2
	v_mov_b32_e32 v77, v2
	v_mov_b32_e32 v82, v2
	v_mov_b32_e32 v83, v2
	v_mov_b32_e32 v84, v2
	v_mov_b32_e32 v85, v2
	v_mov_b32_e32 v98, v2
	v_mov_b32_e32 v99, v2
	v_mov_b32_e32 v100, v2
	v_mov_b32_e32 v101, v2
	v_mov_b32_e32 v102, v2
	v_mov_b32_e32 v103, v2
	v_mov_b32_e32 v104, v2
	v_mov_b32_e32 v105, v2
	v_mov_b32_e32 v106, v2
	v_mov_b32_e32 v107, v2
	v_mov_b32_e32 v108, v2
	v_mov_b32_e32 v109, v2
	v_mov_b32_e32 v110, v2
	v_mov_b32_e32 v111, v2
	v_mov_b32_e32 v112, v2
	v_mov_b32_e32 v113, v2
	v_mov_b32_e32 v114, v2
	v_mov_b32_e32 v115, v2
	v_mov_b32_e32 v116, v2
	v_mov_b32_e32 v117, v2
	v_mov_b32_e32 v118, v2
	v_mov_b32_e32 v119, v2
	v_mov_b32_e32 v120, v2
	v_mov_b32_e32 v121, v2
	v_mov_b32_e32 v122, v2
	v_mov_b32_e32 v123, v2
	v_mov_b32_e32 v124, v2
	v_mov_b32_e32 v125, v2
	v_mov_b32_e32 v126, v2
	v_mov_b32_e32 v127, v2
	v_mov_b32_e32 v128, v2
	v_mov_b32_e32 v129, v2
	v_readlane_b32 s98, v250, 4
	s_cmp_lt_u32 s98, 4
	s_cbranch_scc1 .Lgp_8
	s_setprio 1
.Lgp_8:
.LBB0_1386:
	ds_read_b128 v[156:159], v148
	ds_read_b128 v[160:163], v148 offset:1024
	ds_read_b128 v[164:167], v148 offset:2048
	ds_read_b128 v[168:171], v148 offset:3072
	ds_read_b128 v[172:175], v149
	ds_read_b128 v[176:179], v149 offset:1024
	ds_read_b128 v[180:183], v149 offset:2048
	ds_read_b128 v[186:189], v149 offset:3072
	s_add_u32 s30, s28, 0xfffc0080
	s_addc_u32 s31, s29, -1
	s_cmp_eq_u32 s60, 12
	s_cselect_b32 s35, s23, s31
	s_cselect_b32 s34, s56, s30
	s_cselect_b32 s31, s21, s59
	s_cselect_b32 s30, s57, s58
	v_lshl_add_u64 v[222:223], s[28:29], 0, v[140:141]
	s_add_i32 m0, s19, 0xc000
	ds_read_b128 v[190:193], v152
	ds_read_b128 v[194:197], v152 offset:1024
	ds_read_b128 v[198:201], v152 offset:2048
	ds_read_b128 v[202:205], v152 offset:3072
	ds_read_b128 v[206:209], v152 offset:4096
	ds_read_b128 v[210:213], v152 offset:5120
	ds_read_b128 v[214:217], v152 offset:6144
	ds_read_b128 v[218:221], v152 offset:7168
	global_load_lds_dwordx4 v[222:223], off
	v_lshl_add_u64 v[222:223], s[28:29], 0, v[138:139]
	s_add_i32 m0, s19, 0xe000
	s_nop 0
	global_load_lds_dwordx4 v[222:223], off
	s_waitcnt vmcnt(8)
	s_waitcnt lgkmcnt(0)
	s_barrier
; #define PG8_STAGE(bufoff, gbase, voff) do { _Pragma("unroll") for (int _i = 0; _i < 2; ++_i) \
;         __builtin_amdgcn_global_load_lds((const unsigned*)((const char*)(gbase) + (voff)[_i]), (PG8_LAS unsigned*)(lds + (bufoff) + ldsw + _i * 8192), 16, 0, 0); } while (0)
; #define PG8_LDA(dst, b, h) do { _Pragma("unroll") for (int m = 0; m < 4; ++m) _Pragma("unroll") for (int k = 0; k < 2; ++k) dst[m][k] = *(const PG8_LAS bf16x8*)(lds + PG8_SA(b, h) + aoff + m * 2048 + k * 1024); } while (0)
; #define PG8_MMA(ai, bj, At, Bt) do { __builtin_amdgcn_s_setprio(1); _Pragma("unroll") for (int m = 0; m < 4; ++m) _Pragma("unroll") for (int n = 0; n < 2; ++n) _Pragma("unroll") for (int k = 0; k < 2; ++k) \
;         acc[ai][bj][m][n] = __builtin_amdgcn_mfma_f32_16x16x32_bf16(Bt[n][k], At[m][k], acc[ai][bj][m][n], 0, 0, 0); __builtin_amdgcn_s_setprio(0); } while (0)
; #define PG8_WAIT_V(n) asm volatile("s_waitcnt vmcnt(" #n ")" ::: "memory")
; #define PG8_WAIT_L(n) asm volatile("s_waitcnt lgkmcnt(" #n ")" ::: "memory")
; #define PG8_BAR __builtin_amdgcn_s_barrier()
; #define PG8_SCHED __builtin_amdgcn_sched_barrier(0)
; template <class Epi, class Sched, bool ALIGN_EPI = false, bool SP2 = false>
; __device__ __forceinline__ void gemm_phase(PG8_LAS unsigned char* lds, const Gemm g, const Sched& S, const Epi& E) {
;     ...
;             PG8_WAIT_V(8); PG8_WAIT_L(0); PG8_BAR; PG8_MMA(0, 0, At, B0); PG8_MMA(0, 1, At, B1); PG8_BAR; PG8_SCHED;
;             PG8_LDA(At, 0, 1); PG8_STAGE(PG8_SB(0, 0), b2, voffB); PG8_STAGE(PG8_SB(0, 1), b2 + hstepB, voffB); PG8_STAGE(PG8_SA(0, 0), a2, voffA);
;             PG8_WAIT_V(8); PG8_WAIT_L(0); PG8_BAR; PG8_MMA(1, 0, At, B0); PG8_MMA(1, 1, At, B1); PG8_BAR; PG8_SCHED;
	s_waitcnt lgkmcnt(0)
	v_mfma_f32_16x16x32_bf16 v[126:129], v[156:159], v[190:193], v[126:129]
	v_mfma_f32_16x16x32_bf16 v[122:125], v[164:167], v[190:193], v[122:125]
	v_mfma_f32_16x16x32_bf16 v[118:121], v[156:159], v[198:201], v[118:121]
	v_mfma_f32_16x16x32_bf16 v[114:117], v[164:167], v[198:201], v[114:117]
	v_mfma_f32_16x16x32_bf16 v[110:113], v[156:159], v[206:209], v[110:113]
	v_mfma_f32_16x16x32_bf16 v[106:109], v[164:167], v[206:209], v[106:109]
	v_mfma_f32_16x16x32_bf16 v[102:105], v[156:159], v[214:217], v[102:105]
	v_mfma_f32_16x16x32_bf16 v[98:101], v[164:167], v[214:217], v[98:101]
	v_mfma_f32_16x16x32_bf16 v[126:129], v[160:163], v[194:197], v[126:129]
	v_mfma_f32_16x16x32_bf16 v[122:125], v[168:171], v[194:197], v[122:125]
	v_mfma_f32_16x16x32_bf16 v[118:121], v[160:163], v[202:205], v[118:121]
	v_mfma_f32_16x16x32_bf16 v[114:117], v[168:171], v[202:205], v[114:117]
	v_mfma_f32_16x16x32_bf16 v[110:113], v[160:163], v[210:213], v[110:113]
	v_mfma_f32_16x16x32_bf16 v[106:109], v[168:171], v[210:213], v[106:109]
	v_mfma_f32_16x16x32_bf16 v[102:105], v[160:163], v[218:221], v[102:105]
	v_mfma_f32_16x16x32_bf16 v[98:101], v[168:171], v[218:221], v[98:101]
	v_mfma_f32_16x16x32_bf16 v[82:85], v[172:175], v[190:193], v[82:85]
	v_mfma_f32_16x16x32_bf16 v[74:77], v[180:183], v[190:193], v[74:77]
	v_mfma_f32_16x16x32_bf16 v[70:73], v[172:175], v[198:201], v[70:73]
	v_mfma_f32_16x16x32_bf16 v[62:65], v[180:183], v[198:201], v[62:65]
	v_mfma_f32_16x16x32_bf16 v[54:57], v[172:175], v[206:209], v[54:57]
	v_mfma_f32_16x16x32_bf16 v[50:53], v[180:183], v[206:209], v[50:53]
	v_mfma_f32_16x16x32_bf16 v[38:41], v[172:175], v[214:217], v[38:41]
	v_mfma_f32_16x16x32_bf16 v[34:37], v[180:183], v[214:217], v[34:37]
	v_mfma_f32_16x16x32_bf16 v[82:85], v[176:179], v[194:197], v[82:85]
	v_mfma_f32_16x16x32_bf16 v[74:77], v[186:189], v[194:197], v[74:77]
	v_mfma_f32_16x16x32_bf16 v[70:73], v[176:179], v[202:205], v[70:73]
	v_mfma_f32_16x16x32_bf16 v[62:65], v[186:189], v[202:205], v[62:65]
	v_mfma_f32_16x16x32_bf16 v[54:57], v[176:179], v[210:213], v[54:57]
	v_mfma_f32_16x16x32_bf16 v[50:53], v[186:189], v[210:213], v[50:53]
	v_mfma_f32_16x16x32_bf16 v[38:41], v[176:179], v[218:221], v[38:41]
	v_mfma_f32_16x16x32_bf16 v[34:37], v[186:189], v[218:221], v[34:37]
	s_barrier
	s_add_i32 s61, s49, s36
	v_lshl_add_u64 v[222:223], s[30:31], 0, v[132:133]
	s_mov_b32 m0, s61
	ds_read_b128 v[190:193], v152 offset:16384
	ds_read_b128 v[194:197], v152 offset:17408
	ds_read_b128 v[198:201], v152 offset:18432
	ds_read_b128 v[202:205], v152 offset:19456
	ds_read_b128 v[206:209], v152 offset:20480
	ds_read_b128 v[210:213], v152 offset:21504
	ds_read_b128 v[214:217], v152 offset:22528
	ds_read_b128 v[218:221], v152 offset:23552
	global_load_lds_dwordx4 v[222:223], off
	s_add_i32 m0, s61, 0x2000
	s_add_u32 s62, s30, 0x40000
	v_lshl_add_u64 v[224:225], s[30:31], 0, v[136:137]
	s_addc_u32 s63, s31, 0
	s_add_i32 s61, s50, s36
	global_load_lds_dwordx4 v[224:225], off
	v_lshl_add_u64 v[226:227], s[62:63], 0, v[132:133]
	s_mov_b32 m0, s61
	v_lshl_add_u64 v[228:229], s[34:35], 0, v[134:135]
	global_load_lds_dwordx4 v[226:227], off
	v_lshl_add_u64 v[226:227], s[62:63], 0, v[136:137]
	s_add_i32 m0, s61, 0x2000
	s_nop 0
	global_load_lds_dwordx4 v[226:227], off
	v_lshl_add_u64 v[226:227], s[34:35], 0, v[130:131]
	s_mov_b32 m0, s19
	s_nop 0
	global_load_lds_dwordx4 v[226:227], off
	s_mov_b32 m0, s37
	s_nop 0
	global_load_lds_dwordx4 v[228:229], off
	s_waitcnt vmcnt(8)
	s_waitcnt lgkmcnt(0)
	s_barrier
	s_waitcnt lgkmcnt(0)
	v_mfma_f32_16x16x32_bf16 v[94:97], v[156:159], v[190:193], v[94:97]
	v_mfma_f32_16x16x32_bf16 v[90:93], v[164:167], v[190:193], v[90:93]
	v_mfma_f32_16x16x32_bf16 v[86:89], v[156:159], v[198:201], v[86:89]
	v_mfma_f32_16x16x32_bf16 v[78:81], v[164:167], v[198:201], v[78:81]
	v_mfma_f32_16x16x32_bf16 v[66:69], v[156:159], v[206:209], v[66:69]
	v_mfma_f32_16x16x32_bf16 v[58:61], v[164:167], v[206:209], v[58:61]
	v_mfma_f32_16x16x32_bf16 v[46:49], v[156:159], v[214:217], v[46:49]
	v_mfma_f32_16x16x32_bf16 v[42:45], v[164:167], v[214:217], v[42:45]
	v_mfma_f32_16x16x32_bf16 v[94:97], v[160:163], v[194:197], v[94:97]
	v_mfma_f32_16x16x32_bf16 v[90:93], v[168:171], v[194:197], v[90:93]
	v_mfma_f32_16x16x32_bf16 v[86:89], v[160:163], v[202:205], v[86:89]
	v_mfma_f32_16x16x32_bf16 v[78:81], v[168:171], v[202:205], v[78:81]
	v_mfma_f32_16x16x32_bf16 v[66:69], v[160:163], v[210:213], v[66:69]
	v_mfma_f32_16x16x32_bf16 v[58:61], v[168:171], v[210:213], v[58:61]
	v_mfma_f32_16x16x32_bf16 v[46:49], v[160:163], v[218:221], v[46:49]
	v_mfma_f32_16x16x32_bf16 v[42:45], v[168:171], v[218:221], v[42:45]
	v_mfma_f32_16x16x32_bf16 v[30:33], v[172:175], v[190:193], v[30:33]
	v_mfma_f32_16x16x32_bf16 v[26:29], v[180:183], v[190:193], v[26:29]
	v_mfma_f32_16x16x32_bf16 v[22:25], v[172:175], v[198:201], v[22:25]
	v_mfma_f32_16x16x32_bf16 v[18:21], v[180:183], v[198:201], v[18:21]
	v_mfma_f32_16x16x32_bf16 v[14:17], v[172:175], v[206:209], v[14:17]
	v_mfma_f32_16x16x32_bf16 v[10:13], v[180:183], v[206:209], v[10:13]
	v_mfma_f32_16x16x32_bf16 v[6:9], v[172:175], v[214:217], v[6:9]
	v_mfma_f32_16x16x32_bf16 v[2:5], v[180:183], v[214:217], v[2:5]
	v_mfma_f32_16x16x32_bf16 v[30:33], v[176:179], v[194:197], v[30:33]
	v_mfma_f32_16x16x32_bf16 v[26:29], v[186:189], v[194:197], v[26:29]
	v_mfma_f32_16x16x32_bf16 v[22:25], v[176:179], v[202:205], v[22:25]
	v_mfma_f32_16x16x32_bf16 v[18:21], v[186:189], v[202:205], v[18:21]
	v_mfma_f32_16x16x32_bf16 v[14:17], v[176:179], v[210:213], v[14:17]
	v_mfma_f32_16x16x32_bf16 v[10:13], v[186:189], v[210:213], v[10:13]
	v_mfma_f32_16x16x32_bf16 v[6:9], v[176:179], v[218:221], v[6:9]
	v_mfma_f32_16x16x32_bf16 v[2:5], v[186:189], v[218:221], v[2:5]
	s_barrier
; #define PG8_STAGE(bufoff, gbase, voff) do { _Pragma("unroll") for (int _i = 0; _i < 2; ++_i) \
;         __builtin_amdgcn_global_load_lds((const unsigned*)((const char*)(gbase) + (voff)[_i]), (PG8_LAS unsigned*)(lds + (bufoff) + ldsw + _i * 8192), 16, 0, 0); } while (0)
; #define PG8_LDA(dst, b, h) do { _Pragma("unroll") for (int m = 0; m < 4; ++m) _Pragma("unroll") for (int k = 0; k < 2; ++k) dst[m][k] = *(const PG8_LAS bf16x8*)(lds + PG8_SA(b, h) + aoff + m * 2048 + k * 1024); } while (0)
; #define PG8_LDB(dst, b, h) do { _Pragma("unroll") for (int n = 0; n < 2; ++n) _Pragma("unroll") for (int k = 0; k < 2; ++k) dst[n][k] = *(const PG8_LAS bf16x8*)(lds + PG8_SB(b, h) + boff + n * 2048 + k * 1024); } while (0)
; #define PG8_MMA(ai, bj, At, Bt) do { __builtin_amdgcn_s_setprio(1); _Pragma("unroll") for (int m = 0; m < 4; ++m) _Pragma("unroll") for (int n = 0; n < 2; ++n) _Pragma("unroll") for (int k = 0; k < 2; ++k) \
;         acc[ai][bj][m][n] = __builtin_amdgcn_mfma_f32_16x16x32_bf16(Bt[n][k], At[m][k], acc[ai][bj][m][n], 0, 0, 0); __builtin_amdgcn_s_setprio(0); } while (0)
; #define PG8_WAIT_V(n) asm volatile("s_waitcnt vmcnt(" #n ")" ::: "memory")
; #define PG8_WAIT_L(n) asm volatile("s_waitcnt lgkmcnt(" #n ")" ::: "memory")
; #define PG8_BAR __builtin_amdgcn_s_barrier()
; #define PG8_SCHED __builtin_amdgcn_sched_barrier(0)
; template <class Epi, class Sched, bool ALIGN_EPI = false, bool SP2 = false>
; __device__ __forceinline__ void gemm_phase(PG8_LAS unsigned char* lds, const Gemm g, const Sched& S, const Epi& E) {
;     ...
;             PG8_LDB(B0, 1, 0); PG8_LDB(B1, 1, 1); PG8_SCHED; PG8_LDA(At, 1, 0); PG8_STAGE(PG8_SA(0, 1), a2 + hstepA, voffA);
;             PG8_WAIT_V(8); PG8_WAIT_L(0); PG8_BAR; PG8_MMA(0, 0, At, B0); PG8_MMA(0, 1, At, B1); PG8_BAR; PG8_SCHED;
	s_add_i32 s61, 0, 0x18000
	v_add_u32_e32 v153, s61, v146
	s_add_i32 s62, 0, 0x1c000
	ds_read_b128 v[156:159], v153
	ds_read_b128 v[160:163], v153 offset:1024
	ds_read_b128 v[164:167], v153 offset:2048
	ds_read_b128 v[168:171], v153 offset:3072
	v_add_u32_e32 v153, s62, v146
	ds_read_b128 v[172:175], v153
	ds_read_b128 v[176:179], v153 offset:1024
	ds_read_b128 v[180:183], v153 offset:2048
	ds_read_b128 v[186:189], v153 offset:3072
	s_add_u32 s34, s34, 0x40000
	s_addc_u32 s35, s35, 0
	s_mov_b32 m0, s38
	v_lshl_add_u64 v[230:231], s[34:35], 0, v[130:131]
	ds_read_b128 v[190:193], v152 offset:32768
	ds_read_b128 v[194:197], v152 offset:33792
	ds_read_b128 v[198:201], v152 offset:34816
	ds_read_b128 v[202:205], v152 offset:35840
	ds_read_b128 v[206:209], v152 offset:36864
	ds_read_b128 v[210:213], v152 offset:37888
	ds_read_b128 v[214:217], v152 offset:38912
	ds_read_b128 v[218:221], v152 offset:39936
	global_load_lds_dwordx4 v[230:231], off
	v_lshl_add_u64 v[230:231], s[34:35], 0, v[134:135]
	s_mov_b32 m0, s39
	s_nop 0
	global_load_lds_dwordx4 v[230:231], off
	s_waitcnt vmcnt(8)
	s_waitcnt lgkmcnt(0)
	s_barrier
	s_waitcnt lgkmcnt(0)
	v_mfma_f32_16x16x32_bf16 v[126:129], v[156:159], v[190:193], v[126:129]
	v_mfma_f32_16x16x32_bf16 v[122:125], v[164:167], v[190:193], v[122:125]
	v_mfma_f32_16x16x32_bf16 v[118:121], v[156:159], v[198:201], v[118:121]
	v_mfma_f32_16x16x32_bf16 v[114:117], v[164:167], v[198:201], v[114:117]
	v_mfma_f32_16x16x32_bf16 v[110:113], v[156:159], v[206:209], v[110:113]
	v_mfma_f32_16x16x32_bf16 v[106:109], v[164:167], v[206:209], v[106:109]
	v_mfma_f32_16x16x32_bf16 v[102:105], v[156:159], v[214:217], v[102:105]
	v_mfma_f32_16x16x32_bf16 v[98:101], v[164:167], v[214:217], v[98:101]
	v_mfma_f32_16x16x32_bf16 v[126:129], v[160:163], v[194:197], v[126:129]
	v_mfma_f32_16x16x32_bf16 v[122:125], v[168:171], v[194:197], v[122:125]
	v_mfma_f32_16x16x32_bf16 v[118:121], v[160:163], v[202:205], v[118:121]
	v_mfma_f32_16x16x32_bf16 v[114:117], v[168:171], v[202:205], v[114:117]
	v_mfma_f32_16x16x32_bf16 v[110:113], v[160:163], v[210:213], v[110:113]
	v_mfma_f32_16x16x32_bf16 v[106:109], v[168:171], v[210:213], v[106:109]
	v_mfma_f32_16x16x32_bf16 v[102:105], v[160:163], v[218:221], v[102:105]
	v_mfma_f32_16x16x32_bf16 v[98:101], v[168:171], v[218:221], v[98:101]
	v_mfma_f32_16x16x32_bf16 v[82:85], v[172:175], v[190:193], v[82:85]
	v_mfma_f32_16x16x32_bf16 v[74:77], v[180:183], v[190:193], v[74:77]
	v_mfma_f32_16x16x32_bf16 v[70:73], v[172:175], v[198:201], v[70:73]
	v_mfma_f32_16x16x32_bf16 v[62:65], v[180:183], v[198:201], v[62:65]
	v_mfma_f32_16x16x32_bf16 v[54:57], v[172:175], v[206:209], v[54:57]
	v_mfma_f32_16x16x32_bf16 v[50:53], v[180:183], v[206:209], v[50:53]
	v_mfma_f32_16x16x32_bf16 v[38:41], v[172:175], v[214:217], v[38:41]
	v_mfma_f32_16x16x32_bf16 v[34:37], v[180:183], v[214:217], v[34:37]
	v_mfma_f32_16x16x32_bf16 v[82:85], v[176:179], v[194:197], v[82:85]
	v_mfma_f32_16x16x32_bf16 v[74:77], v[186:189], v[194:197], v[74:77]
	v_mfma_f32_16x16x32_bf16 v[70:73], v[176:179], v[202:205], v[70:73]
	v_mfma_f32_16x16x32_bf16 v[62:65], v[186:189], v[202:205], v[62:65]
	v_mfma_f32_16x16x32_bf16 v[54:57], v[176:179], v[210:213], v[54:57]
	v_mfma_f32_16x16x32_bf16 v[50:53], v[186:189], v[210:213], v[50:53]
	v_mfma_f32_16x16x32_bf16 v[38:41], v[176:179], v[218:221], v[38:41]
	v_mfma_f32_16x16x32_bf16 v[34:37], v[186:189], v[218:221], v[34:37]
	s_barrier
; #define PG8_STAGE(bufoff, gbase, voff) do { _Pragma("unroll") for (int _i = 0; _i < 2; ++_i) \
;         __builtin_amdgcn_global_load_lds((const unsigned*)((const char*)(gbase) + (voff)[_i]), (PG8_LAS unsigned*)(lds + (bufoff) + ldsw + _i * 8192), 16, 0, 0); } while (0)
; #define PG8_LDA(dst, b, h) do { _Pragma("unroll") for (int m = 0; m < 4; ++m) _Pragma("unroll") for (int k = 0; k < 2; ++k) dst[m][k] = *(const PG8_LAS bf16x8*)(lds + PG8_SA(b, h) + aoff + m * 2048 + k * 1024); } while (0)
; #define PG8_MMA(ai, bj, At, Bt) do { __builtin_amdgcn_s_setprio(1); _Pragma("unroll") for (int m = 0; m < 4; ++m) _Pragma("unroll") for (int n = 0; n < 2; ++n) _Pragma("unroll") for (int k = 0; k < 2; ++k) \
;         acc[ai][bj][m][n] = __builtin_amdgcn_mfma_f32_16x16x32_bf16(Bt[n][k], At[m][k], acc[ai][bj][m][n], 0, 0, 0); __builtin_amdgcn_s_setprio(0); } while (0)
; #define PG8_WAIT_V(n) asm volatile("s_waitcnt vmcnt(" #n ")" ::: "memory")
; #define PG8_WAIT_L(n) asm volatile("s_waitcnt lgkmcnt(" #n ")" ::: "memory")
; #define PG8_BAR __builtin_amdgcn_s_barrier()
; #define PG8_SCHED __builtin_amdgcn_sched_barrier(0)
; template <class Epi, class Sched, bool ALIGN_EPI = false, bool SP2 = false>
; __device__ __forceinline__ void gemm_phase(PG8_LAS unsigned char* lds, const Gemm g, const Sched& S, const Epi& E) {
;     ...
;             PG8_LDA(At, 1, 1); PG8_STAGE(PG8_SB(1, 0), b3, voffB); PG8_STAGE(PG8_SB(1, 1), b3 + hstepB, voffB); PG8_STAGE(PG8_SA(1, 0), a3, voffA);
;             PG8_WAIT_V(8); PG8_WAIT_L(0); PG8_BAR; PG8_MMA(1, 0, At, B0); PG8_MMA(1, 1, At, B1); PG8_BAR; PG8_SCHED;
;     ...
;         if constexpr (ALIGN_EPI) { if (wr == 0) PG8_BAR; }
	s_add_i32 s34, s61, s36
	v_lshl_add_u64 v[222:223], v[222:223], 0, s[8:9]
	s_mov_b32 m0, s34
	ds_read_b128 v[190:193], v152 offset:49152
	ds_read_b128 v[194:197], v152 offset:50176
	ds_read_b128 v[198:201], v152 offset:51200
	ds_read_b128 v[202:205], v152 offset:52224
	ds_read_b128 v[206:209], v152 offset:53248
	ds_read_b128 v[210:213], v152 offset:54272
	ds_read_b128 v[214:217], v152 offset:55296
	ds_read_b128 v[218:221], v152 offset:56320
	global_load_lds_dwordx4 v[222:223], off
	s_add_i32 m0, s34, 0x2000
	s_add_u32 s30, s30, 0x40080
	v_lshl_add_u64 v[222:223], v[224:225], 0, s[8:9]
	s_addc_u32 s31, s31, 0
	s_add_i32 s34, s62, s36
	global_load_lds_dwordx4 v[222:223], off
	v_lshl_add_u64 v[222:223], s[30:31], 0, v[132:133]
	s_mov_b32 m0, s34
	s_nop 0
	global_load_lds_dwordx4 v[222:223], off
	v_lshl_add_u64 v[222:223], s[30:31], 0, v[136:137]
	s_add_i32 m0, s34, 0x2000
	s_nop 0
	global_load_lds_dwordx4 v[222:223], off
	v_lshl_add_u64 v[222:223], v[226:227], 0, s[8:9]
	s_mov_b32 m0, s45
	s_nop 0
	global_load_lds_dwordx4 v[222:223], off
	v_lshl_add_u64 v[222:223], v[228:229], 0, s[8:9]
	s_mov_b32 m0, s46
	s_nop 0
	global_load_lds_dwordx4 v[222:223], off
	s_waitcnt vmcnt(8)
	s_waitcnt lgkmcnt(0)
	s_barrier
	s_waitcnt lgkmcnt(0)
	v_mfma_f32_16x16x32_bf16 v[94:97], v[156:159], v[190:193], v[94:97]
	v_mfma_f32_16x16x32_bf16 v[90:93], v[164:167], v[190:193], v[90:93]
	v_mfma_f32_16x16x32_bf16 v[86:89], v[156:159], v[198:201], v[86:89]
	v_mfma_f32_16x16x32_bf16 v[78:81], v[164:167], v[198:201], v[78:81]
	v_mfma_f32_16x16x32_bf16 v[66:69], v[156:159], v[206:209], v[66:69]
	v_mfma_f32_16x16x32_bf16 v[58:61], v[164:167], v[206:209], v[58:61]
	v_mfma_f32_16x16x32_bf16 v[46:49], v[156:159], v[214:217], v[46:49]
	v_mfma_f32_16x16x32_bf16 v[42:45], v[164:167], v[214:217], v[42:45]
	v_mfma_f32_16x16x32_bf16 v[94:97], v[160:163], v[194:197], v[94:97]
	v_mfma_f32_16x16x32_bf16 v[90:93], v[168:171], v[194:197], v[90:93]
	v_mfma_f32_16x16x32_bf16 v[86:89], v[160:163], v[202:205], v[86:89]
	v_mfma_f32_16x16x32_bf16 v[78:81], v[168:171], v[202:205], v[78:81]
	v_mfma_f32_16x16x32_bf16 v[66:69], v[160:163], v[210:213], v[66:69]
	v_mfma_f32_16x16x32_bf16 v[58:61], v[168:171], v[210:213], v[58:61]
	v_mfma_f32_16x16x32_bf16 v[46:49], v[160:163], v[218:221], v[46:49]
	v_mfma_f32_16x16x32_bf16 v[42:45], v[168:171], v[218:221], v[42:45]
	v_mfma_f32_16x16x32_bf16 v[30:33], v[172:175], v[190:193], v[30:33]
	v_mfma_f32_16x16x32_bf16 v[26:29], v[180:183], v[190:193], v[26:29]
	v_mfma_f32_16x16x32_bf16 v[22:25], v[172:175], v[198:201], v[22:25]
	v_mfma_f32_16x16x32_bf16 v[18:21], v[180:183], v[198:201], v[18:21]
	v_mfma_f32_16x16x32_bf16 v[14:17], v[172:175], v[206:209], v[14:17]
	v_mfma_f32_16x16x32_bf16 v[10:13], v[180:183], v[206:209], v[10:13]
	v_mfma_f32_16x16x32_bf16 v[6:9], v[172:175], v[214:217], v[6:9]
	v_mfma_f32_16x16x32_bf16 v[2:5], v[180:183], v[214:217], v[2:5]
	v_mfma_f32_16x16x32_bf16 v[30:33], v[176:179], v[194:197], v[30:33]
	v_mfma_f32_16x16x32_bf16 v[26:29], v[186:189], v[194:197], v[26:29]
	v_mfma_f32_16x16x32_bf16 v[22:25], v[176:179], v[202:205], v[22:25]
	v_mfma_f32_16x16x32_bf16 v[18:21], v[186:189], v[202:205], v[18:21]
	v_mfma_f32_16x16x32_bf16 v[14:17], v[176:179], v[210:213], v[14:17]
	v_mfma_f32_16x16x32_bf16 v[10:13], v[186:189], v[210:213], v[10:13]
	v_mfma_f32_16x16x32_bf16 v[6:9], v[176:179], v[218:221], v[6:9]
	v_mfma_f32_16x16x32_bf16 v[2:5], v[186:189], v[218:221], v[2:5]
	s_barrier
	s_add_i32 s60, s60, 2
	s_add_u32 s58, s58, 0x100
	s_addc_u32 s59, s59, 0
	s_add_u32 s28, s28, 0x100
	s_addc_u32 s29, s29, 0
	s_cmp_gt_u32 s60, 13
	s_cbranch_scc0 .LBB0_1386
	s_setprio 0
	s_and_b64 vcc, exec, s[10:11]
	s_cbranch_vccz .LBB0_1389
	s_barrier
